# row phases with prefetch depth 1 (two buffers) instead of 2, on top of v114
# speedup vs baseline: 1.0084x; 1.0027x over previous
; __device__ __forceinline__ unsigned pk_bf16(float lo, float hi) { const f32x2 v = {lo, hi}; const bf16x2_t b = __builtin_convertvector(v, bf16x2_t); return __builtin_bit_cast(unsigned, b); }
; template <bool HAS_F, bool HAS_H>
; __device__ __forceinline__ void phase_rows(const Params& p, int sp, int sn, float resw, bool from_input, bool write_x = true) {
;     ...
;     for (int row = gw; row < T; row += NGW) {
;         const int b = row_batch(row);
;         const float* xin = !from_input ? p.out + (size_t)row * D : (row < TP ? p.in[0] + (size_t)row * D : p.in[1] + (size_t)(row - TP) * D);
;         f32x4 v[4];
; #pragma unroll
;         for (int j = 0; j < 4; ++j) v[j] = *(const f32x4*)(xin + 4 * lane + 256 * j);
;     ...
;         if (HAS_H) {
;             float ss = 0.f;
; #pragma unroll
;             for (int j = 0; j < 4; ++j) ss += (v[j].x * v[j].x + v[j].y * v[j].y) + (v[j].z * v[j].z + v[j].w * v[j].w);
;             const float rs = 1.0f / sqrtf(wave_sum(ss) * (1.0f / D) + EPS);
;             const float* sh = mod + b * 9216 + sn * 3072; const float* scl = sh + 1024; const float* gq = p.in[6] + sn * D;
; #pragma unroll
;             for (int j = 0; j < 4; ++j) { const f32x4 a = *(const f32x4*)(sh + 4 * lane + 256 * j), s = *(const f32x4*)(scl + 4 * lane + 256 * j), q = *(const f32x4*)(gq + 4 * lane + 256 * j);
;                 const f32x4 h = (v[j] * rs * q) * (s + 1.0f) + a;
;                 u32x2 w; w.x = pk_bf16(h.x, h.y); w.y = pk_bf16(h.z, h.w);
;                 *(u32x2*)(H + (size_t)row * D + 4 * lane + 256 * j) = w; }
.Lrp1_chunk1:
	s_mul_i32 s53, s51, 384
	s_cmp_ge_u32 s53, 0x18000
	s_cbranch_scc1 .Lrp1_done2
	s_add_u32 s53, s53, s50
	s_add_u32 s54, s53, 376
	s_mov_b32 s56, -1
	s_mov_b32 s55, s53
	s_add_u32 s57, s53, 0
	s_cmp_lt_u32 s57, 0x8000
	s_cselect_b32 s64, s8, s10
	s_cselect_b32 s65, s9, s11
	s_cselect_b32 s60, 0, 0x8000
	s_sub_u32 s60, s57, s60
	s_lshl_b32 s60, s60, 12
	s_add_u32 s64, s64, s60
	s_addc_u32 s65, s65, 0
	global_load_dwordx4 v[4:7], v0, s[64:65] nt
	global_load_dwordx4 v[8:11], v0, s[64:65] offset:1024 nt
	global_load_dwordx4 v[12:15], v0, s[64:65] offset:2048 nt
	global_load_dwordx4 v[16:19], v0, s[64:65] offset:3072 nt
	s_add_u32 s57, s55, 8
	s_min_u32 s57, s57, s54
	s_cmp_lt_u32 s57, 0x8000
	s_cselect_b32 s64, s8, s10
	s_cselect_b32 s65, s9, s11
	s_cselect_b32 s60, 0, 0x8000
	s_sub_u32 s60, s57, s60
	s_lshl_b32 s60, s60, 12
	s_add_u32 s64, s64, s60
	s_addc_u32 s65, s65, 0
	global_load_dwordx4 v[36:39], v0, s[64:65] nt
	global_load_dwordx4 v[40:43], v0, s[64:65] offset:1024 nt
	global_load_dwordx4 v[44:47], v0, s[64:65] offset:2048 nt
	global_load_dwordx4 v[48:51], v0, s[64:65] offset:3072 nt
	s_lshr_b32 s60, s55, 11
	s_sub_u32 s61, s55, 0x8000
	s_lshr_b32 s61, s61, 12
	s_add_u32 s61, s61, 16
	s_cmp_lt_u32 s55, 0x8000
	s_cselect_b32 s63, s60, s61
	s_cmp_eq_u32 s63, s56
	s_cbranch_scc1 .Lrp1_pk4
	s_mov_b32 s56, s63
	s_add_u32 s0, s20, 0x0
	s_addc_u32 s1, s21, 0
	global_load_dwordx4 v[160:163], v0, s[0:1]
	global_load_dwordx4 v[164:167], v0, s[0:1] offset:1024
	global_load_dwordx4 v[168:171], v0, s[0:1] offset:2048
	global_load_dwordx4 v[172:175], v0, s[0:1] offset:3072
	s_mul_i32 s60, s56, 0x9000
	s_add_u32 s60, s60, 0x3181000
	s_add_u32 s0, s92, s60
	s_addc_u32 s1, s93, 0
	global_load_dwordx4 v[176:179], v0, s[0:1]
	global_load_dwordx4 v[180:183], v0, s[0:1] offset:1024
	global_load_dwordx4 v[184:187], v0, s[0:1] offset:2048
	global_load_dwordx4 v[188:191], v0, s[0:1] offset:3072
	s_mul_i32 s60, s56, 0x9000
	s_add_u32 s60, s60, 0x3180000
	s_add_u32 s0, s92, s60
	s_addc_u32 s1, s93, 0
	global_load_dwordx4 v[192:195], v0, s[0:1]
	global_load_dwordx4 v[196:199], v0, s[0:1] offset:1024
	global_load_dwordx4 v[200:203], v0, s[0:1] offset:2048
	global_load_dwordx4 v[204:207], v0, s[0:1] offset:3072
	s_waitcnt vmcnt(0)
	v_pk_add_f32 v[176:177], v[176:177], 1.0 op_sel_hi:[1,0]
	v_pk_add_f32 v[178:179], v[178:179], 1.0 op_sel_hi:[1,0]
	v_pk_add_f32 v[180:181], v[180:181], 1.0 op_sel_hi:[1,0]
	v_pk_add_f32 v[182:183], v[182:183], 1.0 op_sel_hi:[1,0]
	v_pk_add_f32 v[184:185], v[184:185], 1.0 op_sel_hi:[1,0]
	v_pk_add_f32 v[186:187], v[186:187], 1.0 op_sel_hi:[1,0]
	v_pk_add_f32 v[188:189], v[188:189], 1.0 op_sel_hi:[1,0]
	v_pk_add_f32 v[190:191], v[190:191], 1.0 op_sel_hi:[1,0]
.Lrp1_pk4:
	s_waitcnt vmcnt(4)
	v_pk_mul_f32 v[102:103], v[4:5], v[4:5]
	v_pk_mul_f32 v[106:107], v[6:7], v[6:7]
	v_pk_fma_f32 v[102:103], v[8:9], v[8:9], v[102:103]
	v_pk_fma_f32 v[106:107], v[10:11], v[10:11], v[106:107]
	v_pk_fma_f32 v[102:103], v[12:13], v[12:13], v[102:103]
	v_pk_fma_f32 v[106:107], v[14:15], v[14:15], v[106:107]
	v_pk_fma_f32 v[102:103], v[16:17], v[16:17], v[102:103]
	v_pk_fma_f32 v[106:107], v[18:19], v[18:19], v[106:107]
	s_nop 0
	v_pk_add_f32 v[102:103], v[102:103], v[106:107]
	s_nop 0
	v_add_f32_e32 v102, v102, v103
	s_nop 1
	v_add_f32_dpp v102, v102, v102 quad_perm:[1,0,3,2] row_mask:0xf bank_mask:0xf
	s_nop 1
	v_add_f32_dpp v102, v102, v102 quad_perm:[2,3,0,1] row_mask:0xf bank_mask:0xf
	s_nop 1
	v_add_f32_dpp v102, v102, v102 row_half_mirror row_mask:0xf bank_mask:0xf
	s_nop 1
	v_add_f32_dpp v102, v102, v102 row_mirror row_mask:0xf bank_mask:0xf
	s_nop 1
	v_add_f32_dpp v102, v102, v102 row_bcast:15 row_mask:0xa bank_mask:0xf
	s_nop 1
	v_add_f32_dpp v102, v102, v102 row_bcast:31 row_mask:0xc bank_mask:0xf
	s_nop 1
	v_readlane_b32 s74, v102, 63
	s_nop 2
	v_mov_b32_e32 v102, s74
	v_fmamk_f32 v102, v102, 0x3a800000, v2
	v_mul_f32_e32 v103, 0x4f800000, v102
	v_cmp_gt_f32_e32 vcc, 0xf800000, v102
	s_nop 1
	v_cndmask_b32_e32 v102, v102, v103, vcc
	v_sqrt_f32_e32 v103, v102
	s_nop 0
	v_add_u32_e32 v104, -1, v103
	v_add_u32_e32 v106, 1, v103
	v_fma_f32 v107, -v104, v103, v102
	v_fma_f32 v108, -v106, v103, v102
	v_cmp_ge_f32_e64 s[76:77], 0, v107
	s_nop 1
	v_cndmask_b32_e64 v103, v103, v104, s[76:77]
	v_cmp_lt_f32_e64 s[76:77], 0, v108
	s_nop 1
	v_cndmask_b32_e64 v103, v103, v106, s[76:77]
	v_mul_f32_e32 v104, 0x37800000, v103
	v_cndmask_b32_e32 v103, v103, v104, vcc
	v_cmp_class_f32_e32 vcc, v102, v3
	s_nop 1
	v_cndmask_b32_e32 v102, v103, v102, vcc
	v_div_scale_f32 v103, s[76:77], v102, v102, 1.0
	v_rcp_f32_e32 v104, v103
	v_div_scale_f32 v106, vcc, 1.0, v102, 1.0
	v_fma_f32 v107, -v103, v104, 1.0
	v_fmac_f32_e32 v104, v107, v104
	v_mul_f32_e32 v107, v106, v104
	v_fma_f32 v108, -v103, v107, v106
	v_fmac_f32_e32 v107, v108, v104
	v_fma_f32 v103, -v103, v107, v106
	v_div_fmas_f32 v103, v103, v104, v107
	v_div_fixup_f32 v110, v103, v102, 1.0
	s_lshl_b32 s60, s55, 11
	s_add_u32 s70, s78, s60
	s_addc_u32 s71, s79, 0
	v_pk_mul_f32 v[112:113], v[4:5], v[110:111] op_sel_hi:[1,0]
	v_pk_mul_f32 v[114:115], v[6:7], v[110:111] op_sel_hi:[1,0]
	v_pk_mul_f32 v[116:117], v[8:9], v[110:111] op_sel_hi:[1,0]
	v_pk_mul_f32 v[118:119], v[10:11], v[110:111] op_sel_hi:[1,0]
	v_pk_mul_f32 v[120:121], v[12:13], v[110:111] op_sel_hi:[1,0]
	v_pk_mul_f32 v[122:123], v[14:15], v[110:111] op_sel_hi:[1,0]
	v_pk_mul_f32 v[124:125], v[16:17], v[110:111] op_sel_hi:[1,0]
	v_pk_mul_f32 v[100:101], v[18:19], v[110:111] op_sel_hi:[1,0]
	v_pk_mul_f32 v[112:113], v[160:161], v[112:113]
	v_pk_mul_f32 v[114:115], v[162:163], v[114:115]
	v_pk_mul_f32 v[116:117], v[164:165], v[116:117]
; __device__ __forceinline__ unsigned pk_bf16(float lo, float hi) { const f32x2 v = {lo, hi}; const bf16x2_t b = __builtin_convertvector(v, bf16x2_t); return __builtin_bit_cast(unsigned, b); }
; template <bool HAS_F, bool HAS_H>
; __device__ __forceinline__ void phase_rows(const Params& p, int sp, int sn, float resw, bool from_input, bool write_x = true) {
;     ...
;         if (HAS_H) {
;             float ss = 0.f;
; #pragma unroll
;             for (int j = 0; j < 4; ++j) ss += (v[j].x * v[j].x + v[j].y * v[j].y) + (v[j].z * v[j].z + v[j].w * v[j].w);
;             const float rs = 1.0f / sqrtf(wave_sum(ss) * (1.0f / D) + EPS);
;             const float* sh = mod + b * 9216 + sn * 3072; const float* scl = sh + 1024; const float* gq = p.in[6] + sn * D;
; #pragma unroll
;             for (int j = 0; j < 4; ++j) { const f32x4 a = *(const f32x4*)(sh + 4 * lane + 256 * j), s = *(const f32x4*)(scl + 4 * lane + 256 * j), q = *(const f32x4*)(gq + 4 * lane + 256 * j);
;                 const f32x4 h = (v[j] * rs * q) * (s + 1.0f) + a;
;                 u32x2 w; w.x = pk_bf16(h.x, h.y); w.y = pk_bf16(h.z, h.w);
;                 *(u32x2*)(H + (size_t)row * D + 4 * lane + 256 * j) = w; }
	v_pk_mul_f32 v[118:119], v[166:167], v[118:119]
	v_pk_mul_f32 v[120:121], v[168:169], v[120:121]
	v_pk_mul_f32 v[122:123], v[170:171], v[122:123]
	v_pk_mul_f32 v[124:125], v[172:173], v[124:125]
	v_pk_mul_f32 v[100:101], v[174:175], v[100:101]
	v_pk_fma_f32 v[112:113], v[176:177], v[112:113], v[192:193]
	v_pk_fma_f32 v[114:115], v[178:179], v[114:115], v[194:195]
	v_pk_fma_f32 v[116:117], v[180:181], v[116:117], v[196:197]
	v_pk_fma_f32 v[118:119], v[182:183], v[118:119], v[198:199]
	v_pk_fma_f32 v[120:121], v[184:185], v[120:121], v[200:201]
	v_pk_fma_f32 v[122:123], v[186:187], v[122:123], v[202:203]
	v_pk_fma_f32 v[124:125], v[188:189], v[124:125], v[204:205]
	v_pk_fma_f32 v[100:101], v[190:191], v[100:101], v[206:207]
	v_cvt_pk_bf16_f32 v240, v112, v113
	v_cvt_pk_bf16_f32 v241, v114, v115
	v_cvt_pk_bf16_f32 v242, v116, v117
	v_cvt_pk_bf16_f32 v243, v118, v119
	v_cvt_pk_bf16_f32 v244, v120, v121
	v_cvt_pk_bf16_f32 v245, v122, v123
	v_cvt_pk_bf16_f32 v246, v124, v125
	v_cvt_pk_bf16_f32 v247, v100, v101
	global_store_dwordx2 v1, v[240:241], s[70:71]
	global_store_dwordx2 v1, v[242:243], s[70:71] offset:512
	global_store_dwordx2 v1, v[244:245], s[70:71] offset:1024
	global_store_dwordx2 v1, v[246:247], s[70:71] offset:1536
	s_add_u32 s55, s55, 8
	s_add_u32 s57, s55, 8
	s_min_u32 s57, s57, s54
	s_cmp_lt_u32 s57, 0x8000
	s_cselect_b32 s64, s8, s10
	s_cselect_b32 s65, s9, s11
	s_cselect_b32 s60, 0, 0x8000
	s_sub_u32 s60, s57, s60
	s_lshl_b32 s60, s60, 12
	s_add_u32 s64, s64, s60
	s_addc_u32 s65, s65, 0
	global_load_dwordx4 v[4:7], v0, s[64:65] nt
	global_load_dwordx4 v[8:11], v0, s[64:65] offset:1024 nt
	global_load_dwordx4 v[12:15], v0, s[64:65] offset:2048 nt
	global_load_dwordx4 v[16:19], v0, s[64:65] offset:3072 nt
	s_lshr_b32 s60, s55, 11
	s_sub_u32 s61, s55, 0x8000
	s_lshr_b32 s61, s61, 12
	s_add_u32 s61, s61, 16
	s_cmp_lt_u32 s55, 0x8000
	s_cselect_b32 s63, s60, s61
	s_cmp_eq_u32 s63, s56
	s_cbranch_scc1 .Lrp1_pk5
	s_mov_b32 s56, s63
	s_add_u32 s0, s20, 0x0
	s_addc_u32 s1, s21, 0
	global_load_dwordx4 v[160:163], v0, s[0:1]
	global_load_dwordx4 v[164:167], v0, s[0:1] offset:1024
	global_load_dwordx4 v[168:171], v0, s[0:1] offset:2048
	global_load_dwordx4 v[172:175], v0, s[0:1] offset:3072
	s_mul_i32 s60, s56, 0x9000
	s_add_u32 s60, s60, 0x3181000
	s_add_u32 s0, s92, s60
	s_addc_u32 s1, s93, 0
	global_load_dwordx4 v[176:179], v0, s[0:1]
	global_load_dwordx4 v[180:183], v0, s[0:1] offset:1024
	global_load_dwordx4 v[184:187], v0, s[0:1] offset:2048
	global_load_dwordx4 v[188:191], v0, s[0:1] offset:3072
	s_mul_i32 s60, s56, 0x9000
	s_add_u32 s60, s60, 0x3180000
	s_add_u32 s0, s92, s60
	s_addc_u32 s1, s93, 0
	global_load_dwordx4 v[192:195], v0, s[0:1]
	global_load_dwordx4 v[196:199], v0, s[0:1] offset:1024
	global_load_dwordx4 v[200:203], v0, s[0:1] offset:2048
	global_load_dwordx4 v[204:207], v0, s[0:1] offset:3072
	s_waitcnt vmcnt(0)
	v_pk_add_f32 v[176:177], v[176:177], 1.0 op_sel_hi:[1,0]
	v_pk_add_f32 v[178:179], v[178:179], 1.0 op_sel_hi:[1,0]
	v_pk_add_f32 v[180:181], v[180:181], 1.0 op_sel_hi:[1,0]
	v_pk_add_f32 v[182:183], v[182:183], 1.0 op_sel_hi:[1,0]
	v_pk_add_f32 v[184:185], v[184:185], 1.0 op_sel_hi:[1,0]
	v_pk_add_f32 v[186:187], v[186:187], 1.0 op_sel_hi:[1,0]
	v_pk_add_f32 v[188:189], v[188:189], 1.0 op_sel_hi:[1,0]
	v_pk_add_f32 v[190:191], v[190:191], 1.0 op_sel_hi:[1,0]
.Lrp1_pk5:
	s_waitcnt vmcnt(8)
	v_pk_mul_f32 v[102:103], v[36:37], v[36:37]
	v_pk_mul_f32 v[106:107], v[38:39], v[38:39]
	v_pk_fma_f32 v[102:103], v[40:41], v[40:41], v[102:103]
	v_pk_fma_f32 v[106:107], v[42:43], v[42:43], v[106:107]
	v_pk_fma_f32 v[102:103], v[44:45], v[44:45], v[102:103]
	v_pk_fma_f32 v[106:107], v[46:47], v[46:47], v[106:107]
	v_pk_fma_f32 v[102:103], v[48:49], v[48:49], v[102:103]
	v_pk_fma_f32 v[106:107], v[50:51], v[50:51], v[106:107]
	s_nop 0
	v_pk_add_f32 v[102:103], v[102:103], v[106:107]
	s_nop 0
	v_add_f32_e32 v102, v102, v103
	s_nop 1
	v_add_f32_dpp v102, v102, v102 quad_perm:[1,0,3,2] row_mask:0xf bank_mask:0xf
	s_nop 1
	v_add_f32_dpp v102, v102, v102 quad_perm:[2,3,0,1] row_mask:0xf bank_mask:0xf
	s_nop 1
	v_add_f32_dpp v102, v102, v102 row_half_mirror row_mask:0xf bank_mask:0xf
	s_nop 1
	v_add_f32_dpp v102, v102, v102 row_mirror row_mask:0xf bank_mask:0xf
	s_nop 1
	v_add_f32_dpp v102, v102, v102 row_bcast:15 row_mask:0xa bank_mask:0xf
	s_nop 1
	v_add_f32_dpp v102, v102, v102 row_bcast:31 row_mask:0xc bank_mask:0xf
	s_nop 1
	v_readlane_b32 s74, v102, 63
	s_nop 2
	v_mov_b32_e32 v102, s74
	v_fmamk_f32 v102, v102, 0x3a800000, v2
	v_mul_f32_e32 v103, 0x4f800000, v102
	v_cmp_gt_f32_e32 vcc, 0xf800000, v102
	s_nop 1
	v_cndmask_b32_e32 v102, v102, v103, vcc
	v_sqrt_f32_e32 v103, v102
	s_nop 0
	v_add_u32_e32 v104, -1, v103
	v_add_u32_e32 v106, 1, v103
	v_fma_f32 v107, -v104, v103, v102
	v_fma_f32 v108, -v106, v103, v102
	v_cmp_ge_f32_e64 s[76:77], 0, v107
	s_nop 1
	v_cndmask_b32_e64 v103, v103, v104, s[76:77]
	v_cmp_lt_f32_e64 s[76:77], 0, v108
	s_nop 1
	v_cndmask_b32_e64 v103, v103, v106, s[76:77]
	v_mul_f32_e32 v104, 0x37800000, v103
	v_cndmask_b32_e32 v103, v103, v104, vcc
	v_cmp_class_f32_e32 vcc, v102, v3
	s_nop 1
	v_cndmask_b32_e32 v102, v103, v102, vcc
	v_div_scale_f32 v103, s[76:77], v102, v102, 1.0
	v_rcp_f32_e32 v104, v103
	v_div_scale_f32 v106, vcc, 1.0, v102, 1.0
	v_fma_f32 v107, -v103, v104, 1.0
	v_fmac_f32_e32 v104, v107, v104
	v_mul_f32_e32 v107, v106, v104
	v_fma_f32 v108, -v103, v107, v106
	v_fmac_f32_e32 v107, v108, v104
	v_fma_f32 v103, -v103, v107, v106
	v_div_fmas_f32 v103, v103, v104, v107
	v_div_fixup_f32 v110, v103, v102, 1.0
	s_lshl_b32 s60, s55, 11
	s_add_u32 s70, s78, s60
	s_addc_u32 s71, s79, 0
; __device__ __forceinline__ unsigned pk_bf16(float lo, float hi) { const f32x2 v = {lo, hi}; const bf16x2_t b = __builtin_convertvector(v, bf16x2_t); return __builtin_bit_cast(unsigned, b); }
; template <bool HAS_F, bool HAS_H>
; __device__ __forceinline__ void phase_rows(const Params& p, int sp, int sn, float resw, bool from_input, bool write_x = true) {
;     ...
;     for (int row = gw; row < T; row += NGW) {
;         const int b = row_batch(row);
;         const float* xin = !from_input ? p.out + (size_t)row * D : (row < TP ? p.in[0] + (size_t)row * D : p.in[1] + (size_t)(row - TP) * D);
;         f32x4 v[4];
; #pragma unroll
;         for (int j = 0; j < 4; ++j) v[j] = *(const f32x4*)(xin + 4 * lane + 256 * j);
;     ...
;         if (HAS_H) {
;             float ss = 0.f;
; #pragma unroll
;             for (int j = 0; j < 4; ++j) ss += (v[j].x * v[j].x + v[j].y * v[j].y) + (v[j].z * v[j].z + v[j].w * v[j].w);
;             const float rs = 1.0f / sqrtf(wave_sum(ss) * (1.0f / D) + EPS);
;             const float* sh = mod + b * 9216 + sn * 3072; const float* scl = sh + 1024; const float* gq = p.in[6] + sn * D;
; #pragma unroll
;             for (int j = 0; j < 4; ++j) { const f32x4 a = *(const f32x4*)(sh + 4 * lane + 256 * j), s = *(const f32x4*)(scl + 4 * lane + 256 * j), q = *(const f32x4*)(gq + 4 * lane + 256 * j);
;                 const f32x4 h = (v[j] * rs * q) * (s + 1.0f) + a;
;                 u32x2 w; w.x = pk_bf16(h.x, h.y); w.y = pk_bf16(h.z, h.w);
;                 *(u32x2*)(H + (size_t)row * D + 4 * lane + 256 * j) = w; }
	v_pk_mul_f32 v[112:113], v[36:37], v[110:111] op_sel_hi:[1,0]
	v_pk_mul_f32 v[114:115], v[38:39], v[110:111] op_sel_hi:[1,0]
	v_pk_mul_f32 v[116:117], v[40:41], v[110:111] op_sel_hi:[1,0]
	v_pk_mul_f32 v[118:119], v[42:43], v[110:111] op_sel_hi:[1,0]
	v_pk_mul_f32 v[120:121], v[44:45], v[110:111] op_sel_hi:[1,0]
	v_pk_mul_f32 v[122:123], v[46:47], v[110:111] op_sel_hi:[1,0]
	v_pk_mul_f32 v[124:125], v[48:49], v[110:111] op_sel_hi:[1,0]
	v_pk_mul_f32 v[100:101], v[50:51], v[110:111] op_sel_hi:[1,0]
	v_pk_mul_f32 v[112:113], v[160:161], v[112:113]
	v_pk_mul_f32 v[114:115], v[162:163], v[114:115]
	v_pk_mul_f32 v[116:117], v[164:165], v[116:117]
	v_pk_mul_f32 v[118:119], v[166:167], v[118:119]
	v_pk_mul_f32 v[120:121], v[168:169], v[120:121]
	v_pk_mul_f32 v[122:123], v[170:171], v[122:123]
	v_pk_mul_f32 v[124:125], v[172:173], v[124:125]
	v_pk_mul_f32 v[100:101], v[174:175], v[100:101]
	v_pk_fma_f32 v[112:113], v[176:177], v[112:113], v[192:193]
	v_pk_fma_f32 v[114:115], v[178:179], v[114:115], v[194:195]
	v_pk_fma_f32 v[116:117], v[180:181], v[116:117], v[196:197]
	v_pk_fma_f32 v[118:119], v[182:183], v[118:119], v[198:199]
	v_pk_fma_f32 v[120:121], v[184:185], v[120:121], v[200:201]
	v_pk_fma_f32 v[122:123], v[186:187], v[122:123], v[202:203]
	v_pk_fma_f32 v[124:125], v[188:189], v[124:125], v[204:205]
	v_pk_fma_f32 v[100:101], v[190:191], v[100:101], v[206:207]
	v_cvt_pk_bf16_f32 v240, v112, v113
	v_cvt_pk_bf16_f32 v241, v114, v115
	v_cvt_pk_bf16_f32 v242, v116, v117
	v_cvt_pk_bf16_f32 v243, v118, v119
	v_cvt_pk_bf16_f32 v244, v120, v121
	v_cvt_pk_bf16_f32 v245, v122, v123
	v_cvt_pk_bf16_f32 v246, v124, v125
	v_cvt_pk_bf16_f32 v247, v100, v101
	global_store_dwordx2 v1, v[240:241], s[70:71]
	global_store_dwordx2 v1, v[242:243], s[70:71] offset:512
	global_store_dwordx2 v1, v[244:245], s[70:71] offset:1024
	global_store_dwordx2 v1, v[246:247], s[70:71] offset:1536
	s_add_u32 s55, s55, 8
.Lrp1_loop3:
	s_add_u32 s57, s55, 8
	s_min_u32 s57, s57, s54
	s_cmp_lt_u32 s57, 0x8000
	s_cselect_b32 s64, s8, s10
	s_cselect_b32 s65, s9, s11
	s_cselect_b32 s60, 0, 0x8000
	s_sub_u32 s60, s57, s60
	s_lshl_b32 s60, s60, 12
	s_add_u32 s64, s64, s60
	s_addc_u32 s65, s65, 0
	global_load_dwordx4 v[36:39], v0, s[64:65] nt
	global_load_dwordx4 v[40:43], v0, s[64:65] offset:1024 nt
	global_load_dwordx4 v[44:47], v0, s[64:65] offset:2048 nt
	global_load_dwordx4 v[48:51], v0, s[64:65] offset:3072 nt
	s_lshr_b32 s60, s55, 11
	s_sub_u32 s61, s55, 0x8000
	s_lshr_b32 s61, s61, 12
	s_add_u32 s61, s61, 16
	s_cmp_lt_u32 s55, 0x8000
	s_cselect_b32 s63, s60, s61
	s_cmp_eq_u32 s63, s56
	s_cbranch_scc1 .Lrp1_pk6
	s_mov_b32 s56, s63
	s_add_u32 s0, s20, 0x0
	s_addc_u32 s1, s21, 0
	global_load_dwordx4 v[160:163], v0, s[0:1]
	global_load_dwordx4 v[164:167], v0, s[0:1] offset:1024
	global_load_dwordx4 v[168:171], v0, s[0:1] offset:2048
	global_load_dwordx4 v[172:175], v0, s[0:1] offset:3072
	s_mul_i32 s60, s56, 0x9000
	s_add_u32 s60, s60, 0x3181000
	s_add_u32 s0, s92, s60
	s_addc_u32 s1, s93, 0
	global_load_dwordx4 v[176:179], v0, s[0:1]
	global_load_dwordx4 v[180:183], v0, s[0:1] offset:1024
	global_load_dwordx4 v[184:187], v0, s[0:1] offset:2048
	global_load_dwordx4 v[188:191], v0, s[0:1] offset:3072
	s_mul_i32 s60, s56, 0x9000
	s_add_u32 s60, s60, 0x3180000
	s_add_u32 s0, s92, s60
	s_addc_u32 s1, s93, 0
	global_load_dwordx4 v[192:195], v0, s[0:1]
	global_load_dwordx4 v[196:199], v0, s[0:1] offset:1024
	global_load_dwordx4 v[200:203], v0, s[0:1] offset:2048
	global_load_dwordx4 v[204:207], v0, s[0:1] offset:3072
	s_waitcnt vmcnt(0)
	v_pk_add_f32 v[176:177], v[176:177], 1.0 op_sel_hi:[1,0]
	v_pk_add_f32 v[178:179], v[178:179], 1.0 op_sel_hi:[1,0]
	v_pk_add_f32 v[180:181], v[180:181], 1.0 op_sel_hi:[1,0]
	v_pk_add_f32 v[182:183], v[182:183], 1.0 op_sel_hi:[1,0]
	v_pk_add_f32 v[184:185], v[184:185], 1.0 op_sel_hi:[1,0]
	v_pk_add_f32 v[186:187], v[186:187], 1.0 op_sel_hi:[1,0]
	v_pk_add_f32 v[188:189], v[188:189], 1.0 op_sel_hi:[1,0]
	v_pk_add_f32 v[190:191], v[190:191], 1.0 op_sel_hi:[1,0]
.Lrp1_pk6:
	s_waitcnt vmcnt(8)
	v_pk_mul_f32 v[102:103], v[4:5], v[4:5]
	v_pk_mul_f32 v[106:107], v[6:7], v[6:7]
	v_pk_fma_f32 v[102:103], v[8:9], v[8:9], v[102:103]
	v_pk_fma_f32 v[106:107], v[10:11], v[10:11], v[106:107]
	v_pk_fma_f32 v[102:103], v[12:13], v[12:13], v[102:103]
	v_pk_fma_f32 v[106:107], v[14:15], v[14:15], v[106:107]
	v_pk_fma_f32 v[102:103], v[16:17], v[16:17], v[102:103]
	v_pk_fma_f32 v[106:107], v[18:19], v[18:19], v[106:107]
	s_nop 0
	v_pk_add_f32 v[102:103], v[102:103], v[106:107]
	s_nop 0
	v_add_f32_e32 v102, v102, v103
	s_nop 1
	v_add_f32_dpp v102, v102, v102 quad_perm:[1,0,3,2] row_mask:0xf bank_mask:0xf
	s_nop 1
	v_add_f32_dpp v102, v102, v102 quad_perm:[2,3,0,1] row_mask:0xf bank_mask:0xf
	s_nop 1
	v_add_f32_dpp v102, v102, v102 row_half_mirror row_mask:0xf bank_mask:0xf
	s_nop 1
	v_add_f32_dpp v102, v102, v102 row_mirror row_mask:0xf bank_mask:0xf
	s_nop 1
	v_add_f32_dpp v102, v102, v102 row_bcast:15 row_mask:0xa bank_mask:0xf
	s_nop 1
	v_add_f32_dpp v102, v102, v102 row_bcast:31 row_mask:0xc bank_mask:0xf
	s_nop 1
	v_readlane_b32 s74, v102, 63
	s_nop 2
	v_mov_b32_e32 v102, s74
	v_fmamk_f32 v102, v102, 0x3a800000, v2
	v_mul_f32_e32 v103, 0x4f800000, v102
	v_cmp_gt_f32_e32 vcc, 0xf800000, v102
	s_nop 1
	v_cndmask_b32_e32 v102, v102, v103, vcc
	v_sqrt_f32_e32 v103, v102
	s_nop 0
	v_add_u32_e32 v104, -1, v103
	v_add_u32_e32 v106, 1, v103
	v_fma_f32 v107, -v104, v103, v102
	v_fma_f32 v108, -v106, v103, v102
	v_cmp_ge_f32_e64 s[76:77], 0, v107
	s_nop 1
	v_cndmask_b32_e64 v103, v103, v104, s[76:77]
	v_cmp_lt_f32_e64 s[76:77], 0, v108
	s_nop 1
	v_cndmask_b32_e64 v103, v103, v106, s[76:77]
; __device__ __forceinline__ unsigned pk_bf16(float lo, float hi) { const f32x2 v = {lo, hi}; const bf16x2_t b = __builtin_convertvector(v, bf16x2_t); return __builtin_bit_cast(unsigned, b); }
; template <bool HAS_F, bool HAS_H>
; __device__ __forceinline__ void phase_rows(const Params& p, int sp, int sn, float resw, bool from_input, bool write_x = true) {
;     ...
;     for (int row = gw; row < T; row += NGW) {
;         const int b = row_batch(row);
;         const float* xin = !from_input ? p.out + (size_t)row * D : (row < TP ? p.in[0] + (size_t)row * D : p.in[1] + (size_t)(row - TP) * D);
;         f32x4 v[4];
; #pragma unroll
;         for (int j = 0; j < 4; ++j) v[j] = *(const f32x4*)(xin + 4 * lane + 256 * j);
;     ...
;         if (HAS_H) {
;             float ss = 0.f;
; #pragma unroll
;             for (int j = 0; j < 4; ++j) ss += (v[j].x * v[j].x + v[j].y * v[j].y) + (v[j].z * v[j].z + v[j].w * v[j].w);
;             const float rs = 1.0f / sqrtf(wave_sum(ss) * (1.0f / D) + EPS);
;             const float* sh = mod + b * 9216 + sn * 3072; const float* scl = sh + 1024; const float* gq = p.in[6] + sn * D;
; #pragma unroll
;             for (int j = 0; j < 4; ++j) { const f32x4 a = *(const f32x4*)(sh + 4 * lane + 256 * j), s = *(const f32x4*)(scl + 4 * lane + 256 * j), q = *(const f32x4*)(gq + 4 * lane + 256 * j);
;                 const f32x4 h = (v[j] * rs * q) * (s + 1.0f) + a;
;                 u32x2 w; w.x = pk_bf16(h.x, h.y); w.y = pk_bf16(h.z, h.w);
;                 *(u32x2*)(H + (size_t)row * D + 4 * lane + 256 * j) = w; }
	v_mul_f32_e32 v104, 0x37800000, v103
	v_cndmask_b32_e32 v103, v103, v104, vcc
	v_cmp_class_f32_e32 vcc, v102, v3
	s_nop 1
	v_cndmask_b32_e32 v102, v103, v102, vcc
	v_div_scale_f32 v103, s[76:77], v102, v102, 1.0
	v_rcp_f32_e32 v104, v103
	v_div_scale_f32 v106, vcc, 1.0, v102, 1.0
	v_fma_f32 v107, -v103, v104, 1.0
	v_fmac_f32_e32 v104, v107, v104
	v_mul_f32_e32 v107, v106, v104
	v_fma_f32 v108, -v103, v107, v106
	v_fmac_f32_e32 v107, v108, v104
	v_fma_f32 v103, -v103, v107, v106
	v_div_fmas_f32 v103, v103, v104, v107
	v_div_fixup_f32 v110, v103, v102, 1.0
	s_lshl_b32 s60, s55, 11
	s_add_u32 s70, s78, s60
	s_addc_u32 s71, s79, 0
	v_pk_mul_f32 v[112:113], v[4:5], v[110:111] op_sel_hi:[1,0]
	v_pk_mul_f32 v[114:115], v[6:7], v[110:111] op_sel_hi:[1,0]
	v_pk_mul_f32 v[116:117], v[8:9], v[110:111] op_sel_hi:[1,0]
	v_pk_mul_f32 v[118:119], v[10:11], v[110:111] op_sel_hi:[1,0]
	v_pk_mul_f32 v[120:121], v[12:13], v[110:111] op_sel_hi:[1,0]
	v_pk_mul_f32 v[122:123], v[14:15], v[110:111] op_sel_hi:[1,0]
	v_pk_mul_f32 v[124:125], v[16:17], v[110:111] op_sel_hi:[1,0]
	v_pk_mul_f32 v[100:101], v[18:19], v[110:111] op_sel_hi:[1,0]
	v_pk_mul_f32 v[112:113], v[160:161], v[112:113]
	v_pk_mul_f32 v[114:115], v[162:163], v[114:115]
	v_pk_mul_f32 v[116:117], v[164:165], v[116:117]
	v_pk_mul_f32 v[118:119], v[166:167], v[118:119]
	v_pk_mul_f32 v[120:121], v[168:169], v[120:121]
	v_pk_mul_f32 v[122:123], v[170:171], v[122:123]
	v_pk_mul_f32 v[124:125], v[172:173], v[124:125]
	v_pk_mul_f32 v[100:101], v[174:175], v[100:101]
	v_pk_fma_f32 v[112:113], v[176:177], v[112:113], v[192:193]
	v_pk_fma_f32 v[114:115], v[178:179], v[114:115], v[194:195]
	v_pk_fma_f32 v[116:117], v[180:181], v[116:117], v[196:197]
	v_pk_fma_f32 v[118:119], v[182:183], v[118:119], v[198:199]
	v_pk_fma_f32 v[120:121], v[184:185], v[120:121], v[200:201]
	v_pk_fma_f32 v[122:123], v[186:187], v[122:123], v[202:203]
	v_pk_fma_f32 v[124:125], v[188:189], v[124:125], v[204:205]
	v_pk_fma_f32 v[100:101], v[190:191], v[100:101], v[206:207]
	v_cvt_pk_bf16_f32 v240, v112, v113
	v_cvt_pk_bf16_f32 v241, v114, v115
	v_cvt_pk_bf16_f32 v242, v116, v117
	v_cvt_pk_bf16_f32 v243, v118, v119
	v_cvt_pk_bf16_f32 v244, v120, v121
	v_cvt_pk_bf16_f32 v245, v122, v123
	v_cvt_pk_bf16_f32 v246, v124, v125
	v_cvt_pk_bf16_f32 v247, v100, v101
	global_store_dwordx2 v1, v[240:241], s[70:71]
	global_store_dwordx2 v1, v[242:243], s[70:71] offset:512
	global_store_dwordx2 v1, v[244:245], s[70:71] offset:1024
	global_store_dwordx2 v1, v[246:247], s[70:71] offset:1536
	s_add_u32 s55, s55, 8
	s_add_u32 s57, s55, 8
	s_min_u32 s57, s57, s54
	s_cmp_lt_u32 s57, 0x8000
	s_cselect_b32 s64, s8, s10
	s_cselect_b32 s65, s9, s11
	s_cselect_b32 s60, 0, 0x8000
	s_sub_u32 s60, s57, s60
	s_lshl_b32 s60, s60, 12
	s_add_u32 s64, s64, s60
	s_addc_u32 s65, s65, 0
	global_load_dwordx4 v[4:7], v0, s[64:65] nt
	global_load_dwordx4 v[8:11], v0, s[64:65] offset:1024 nt
	global_load_dwordx4 v[12:15], v0, s[64:65] offset:2048 nt
	global_load_dwordx4 v[16:19], v0, s[64:65] offset:3072 nt
	s_lshr_b32 s60, s55, 11
	s_sub_u32 s61, s55, 0x8000
	s_lshr_b32 s61, s61, 12
	s_add_u32 s61, s61, 16
	s_cmp_lt_u32 s55, 0x8000
	s_cselect_b32 s63, s60, s61
	s_cmp_eq_u32 s63, s56
	s_cbranch_scc1 .Lrp1_pk7
	s_mov_b32 s56, s63
	s_add_u32 s0, s20, 0x0
	s_addc_u32 s1, s21, 0
	global_load_dwordx4 v[160:163], v0, s[0:1]
	global_load_dwordx4 v[164:167], v0, s[0:1] offset:1024
	global_load_dwordx4 v[168:171], v0, s[0:1] offset:2048
	global_load_dwordx4 v[172:175], v0, s[0:1] offset:3072
	s_mul_i32 s60, s56, 0x9000
	s_add_u32 s60, s60, 0x3181000
	s_add_u32 s0, s92, s60
	s_addc_u32 s1, s93, 0
	global_load_dwordx4 v[176:179], v0, s[0:1]
	global_load_dwordx4 v[180:183], v0, s[0:1] offset:1024
	global_load_dwordx4 v[184:187], v0, s[0:1] offset:2048
	global_load_dwordx4 v[188:191], v0, s[0:1] offset:3072
	s_mul_i32 s60, s56, 0x9000
	s_add_u32 s60, s60, 0x3180000
	s_add_u32 s0, s92, s60
	s_addc_u32 s1, s93, 0
	global_load_dwordx4 v[192:195], v0, s[0:1]
	global_load_dwordx4 v[196:199], v0, s[0:1] offset:1024
	global_load_dwordx4 v[200:203], v0, s[0:1] offset:2048
	global_load_dwordx4 v[204:207], v0, s[0:1] offset:3072
	s_waitcnt vmcnt(0)
	v_pk_add_f32 v[176:177], v[176:177], 1.0 op_sel_hi:[1,0]
	v_pk_add_f32 v[178:179], v[178:179], 1.0 op_sel_hi:[1,0]
	v_pk_add_f32 v[180:181], v[180:181], 1.0 op_sel_hi:[1,0]
	v_pk_add_f32 v[182:183], v[182:183], 1.0 op_sel_hi:[1,0]
	v_pk_add_f32 v[184:185], v[184:185], 1.0 op_sel_hi:[1,0]
	v_pk_add_f32 v[186:187], v[186:187], 1.0 op_sel_hi:[1,0]
	v_pk_add_f32 v[188:189], v[188:189], 1.0 op_sel_hi:[1,0]
	v_pk_add_f32 v[190:191], v[190:191], 1.0 op_sel_hi:[1,0]
; __device__ __forceinline__ unsigned pk_bf16(float lo, float hi) { const f32x2 v = {lo, hi}; const bf16x2_t b = __builtin_convertvector(v, bf16x2_t); return __builtin_bit_cast(unsigned, b); }
; template <bool HAS_F, bool HAS_H>
; __device__ __forceinline__ void phase_rows(const Params& p, int sp, int sn, float resw, bool from_input, bool write_x = true) {
;     ...
;         if (HAS_H) {
;             float ss = 0.f;
; #pragma unroll
;             for (int j = 0; j < 4; ++j) ss += (v[j].x * v[j].x + v[j].y * v[j].y) + (v[j].z * v[j].z + v[j].w * v[j].w);
;             const float rs = 1.0f / sqrtf(wave_sum(ss) * (1.0f / D) + EPS);
;             const float* sh = mod + b * 9216 + sn * 3072; const float* scl = sh + 1024; const float* gq = p.in[6] + sn * D;
; #pragma unroll
;             for (int j = 0; j < 4; ++j) { const f32x4 a = *(const f32x4*)(sh + 4 * lane + 256 * j), s = *(const f32x4*)(scl + 4 * lane + 256 * j), q = *(const f32x4*)(gq + 4 * lane + 256 * j);
;                 const f32x4 h = (v[j] * rs * q) * (s + 1.0f) + a;
;                 u32x2 w; w.x = pk_bf16(h.x, h.y); w.y = pk_bf16(h.z, h.w);
;                 *(u32x2*)(H + (size_t)row * D + 4 * lane + 256 * j) = w; }
;         }
;     }
.Lrp1_pk7:
	s_waitcnt vmcnt(8)
	v_pk_mul_f32 v[102:103], v[36:37], v[36:37]
	v_pk_mul_f32 v[106:107], v[38:39], v[38:39]
	v_pk_fma_f32 v[102:103], v[40:41], v[40:41], v[102:103]
	v_pk_fma_f32 v[106:107], v[42:43], v[42:43], v[106:107]
	v_pk_fma_f32 v[102:103], v[44:45], v[44:45], v[102:103]
	v_pk_fma_f32 v[106:107], v[46:47], v[46:47], v[106:107]
	v_pk_fma_f32 v[102:103], v[48:49], v[48:49], v[102:103]
	v_pk_fma_f32 v[106:107], v[50:51], v[50:51], v[106:107]
	s_nop 0
	v_pk_add_f32 v[102:103], v[102:103], v[106:107]
	s_nop 0
	v_add_f32_e32 v102, v102, v103
	s_nop 1
	v_add_f32_dpp v102, v102, v102 quad_perm:[1,0,3,2] row_mask:0xf bank_mask:0xf
	s_nop 1
	v_add_f32_dpp v102, v102, v102 quad_perm:[2,3,0,1] row_mask:0xf bank_mask:0xf
	s_nop 1
	v_add_f32_dpp v102, v102, v102 row_half_mirror row_mask:0xf bank_mask:0xf
	s_nop 1
	v_add_f32_dpp v102, v102, v102 row_mirror row_mask:0xf bank_mask:0xf
	s_nop 1
	v_add_f32_dpp v102, v102, v102 row_bcast:15 row_mask:0xa bank_mask:0xf
	s_nop 1
	v_add_f32_dpp v102, v102, v102 row_bcast:31 row_mask:0xc bank_mask:0xf
	s_nop 1
	v_readlane_b32 s74, v102, 63
	s_nop 2
	v_mov_b32_e32 v102, s74
	v_fmamk_f32 v102, v102, 0x3a800000, v2
	v_mul_f32_e32 v103, 0x4f800000, v102
	v_cmp_gt_f32_e32 vcc, 0xf800000, v102
	s_nop 1
	v_cndmask_b32_e32 v102, v102, v103, vcc
	v_sqrt_f32_e32 v103, v102
	s_nop 0
	v_add_u32_e32 v104, -1, v103
	v_add_u32_e32 v106, 1, v103
	v_fma_f32 v107, -v104, v103, v102
	v_fma_f32 v108, -v106, v103, v102
	v_cmp_ge_f32_e64 s[76:77], 0, v107
	s_nop 1
	v_cndmask_b32_e64 v103, v103, v104, s[76:77]
	v_cmp_lt_f32_e64 s[76:77], 0, v108
	s_nop 1
	v_cndmask_b32_e64 v103, v103, v106, s[76:77]
	v_mul_f32_e32 v104, 0x37800000, v103
	v_cndmask_b32_e32 v103, v103, v104, vcc
	v_cmp_class_f32_e32 vcc, v102, v3
	s_nop 1
	v_cndmask_b32_e32 v102, v103, v102, vcc
	v_div_scale_f32 v103, s[76:77], v102, v102, 1.0
	v_rcp_f32_e32 v104, v103
	v_div_scale_f32 v106, vcc, 1.0, v102, 1.0
	v_fma_f32 v107, -v103, v104, 1.0
	v_fmac_f32_e32 v104, v107, v104
	v_mul_f32_e32 v107, v106, v104
	v_fma_f32 v108, -v103, v107, v106
	v_fmac_f32_e32 v107, v108, v104
	v_fma_f32 v103, -v103, v107, v106
	v_div_fmas_f32 v103, v103, v104, v107
	v_div_fixup_f32 v110, v103, v102, 1.0
	s_lshl_b32 s60, s55, 11
	s_add_u32 s70, s78, s60
	s_addc_u32 s71, s79, 0
	v_pk_mul_f32 v[112:113], v[36:37], v[110:111] op_sel_hi:[1,0]
	v_pk_mul_f32 v[114:115], v[38:39], v[110:111] op_sel_hi:[1,0]
	v_pk_mul_f32 v[116:117], v[40:41], v[110:111] op_sel_hi:[1,0]
	v_pk_mul_f32 v[118:119], v[42:43], v[110:111] op_sel_hi:[1,0]
	v_pk_mul_f32 v[120:121], v[44:45], v[110:111] op_sel_hi:[1,0]
	v_pk_mul_f32 v[122:123], v[46:47], v[110:111] op_sel_hi:[1,0]
	v_pk_mul_f32 v[124:125], v[48:49], v[110:111] op_sel_hi:[1,0]
	v_pk_mul_f32 v[100:101], v[50:51], v[110:111] op_sel_hi:[1,0]
	v_pk_mul_f32 v[112:113], v[160:161], v[112:113]
	v_pk_mul_f32 v[114:115], v[162:163], v[114:115]
	v_pk_mul_f32 v[116:117], v[164:165], v[116:117]
	v_pk_mul_f32 v[118:119], v[166:167], v[118:119]
	v_pk_mul_f32 v[120:121], v[168:169], v[120:121]
	v_pk_mul_f32 v[122:123], v[170:171], v[122:123]
	v_pk_mul_f32 v[124:125], v[172:173], v[124:125]
	v_pk_mul_f32 v[100:101], v[174:175], v[100:101]
	v_pk_fma_f32 v[112:113], v[176:177], v[112:113], v[192:193]
	v_pk_fma_f32 v[114:115], v[178:179], v[114:115], v[194:195]
	v_pk_fma_f32 v[116:117], v[180:181], v[116:117], v[196:197]
	v_pk_fma_f32 v[118:119], v[182:183], v[118:119], v[198:199]
	v_pk_fma_f32 v[120:121], v[184:185], v[120:121], v[200:201]
	v_pk_fma_f32 v[122:123], v[186:187], v[122:123], v[202:203]
	v_pk_fma_f32 v[124:125], v[188:189], v[124:125], v[204:205]
	v_pk_fma_f32 v[100:101], v[190:191], v[100:101], v[206:207]
	v_cvt_pk_bf16_f32 v240, v112, v113
	v_cvt_pk_bf16_f32 v241, v114, v115
	v_cvt_pk_bf16_f32 v242, v116, v117
	v_cvt_pk_bf16_f32 v243, v118, v119
	v_cvt_pk_bf16_f32 v244, v120, v121
	v_cvt_pk_bf16_f32 v245, v122, v123
	v_cvt_pk_bf16_f32 v246, v124, v125
	v_cvt_pk_bf16_f32 v247, v100, v101
	global_store_dwordx2 v1, v[240:241], s[70:71]
	global_store_dwordx2 v1, v[242:243], s[70:71] offset:512
	global_store_dwordx2 v1, v[244:245], s[70:71] offset:1024
	global_store_dwordx2 v1, v[246:247], s[70:71] offset:1536
	s_add_u32 s55, s55, 8
	s_cmp_le_u32 s55, s54
	s_cbranch_scc1 .Lrp1_loop3
	s_add_u32 s51, s51, s52
	s_branch .Lrp1_chunk1

; __device__ __forceinline__ float lo_bf(unsigned w) { return __uint_as_float(w << 16); }
; __device__ __forceinline__ float hi_bf(unsigned w) { return __uint_as_float(w & 0xffff0000u); }
; template <bool HAS_F, bool HAS_H>
; __device__ __forceinline__ void phase_rows(const Params& p, int sp, int sn, float resw, bool from_input, bool write_x = true) {
;     ...
;     for (int row = gw; row < T; row += NGW) {
;         const int b = row_batch(row);
;         const float* xin = !from_input ? p.out + (size_t)row * D : (row < TP ? p.in[0] + (size_t)row * D : p.in[1] + (size_t)(row - TP) * D);
;         f32x4 v[4];
; #pragma unroll
;         for (int j = 0; j < 4; ++j) v[j] = *(const f32x4*)(xin + 4 * lane + 256 * j);
;         if (HAS_F) {
;             f32x4 f[4]; float ss = 0.f;
; #pragma unroll
;             for (int j = 0; j < 4; ++j) { const u32x2 w = *(const u32x2*)(F + (size_t)row * D + 4 * lane + 256 * j);
;                 f[j] = (f32x4){lo_bf(w.x), hi_bf(w.x), lo_bf(w.y), hi_bf(w.y)}; ss += (f[j].x * f[j].x + f[j].y * f[j].y) + (f[j].z * f[j].z + f[j].w * f[j].w); }
;             const float rs = 1.0f / sqrtf(wave_sum(ss) * (1.0f / D) + EPS) * resw;
;             const float* gate = mod + b * 9216 + sp * 3072 + 2048; const float* gp = p.in[7] + sp * D;
; #pragma unroll
;             for (int j = 0; j < 4; ++j) { const f32x4 g = *(const f32x4*)(gate + 4 * lane + 256 * j), q = *(const f32x4*)(gp + 4 * lane + 256 * j);
.Lrp4_chunk1:
	s_mul_i32 s53, s51, 384
	s_cmp_ge_u32 s53, 0x18000
	s_cbranch_scc1 .Lrp4_done2
	s_add_u32 s53, s53, s50
	s_add_u32 s54, s53, 376
	s_mov_b32 s56, -1
	s_mov_b32 s55, s53
	s_add_u32 s57, s53, 0
	s_cmp_lt_u32 s57, 0x8000
	s_cselect_b32 s64, s8, s10
	s_cselect_b32 s65, s9, s11
	s_cselect_b32 s60, 0, 0x8000
	s_sub_u32 s60, s57, s60
	s_lshl_b32 s60, s60, 12
	s_add_u32 s64, s64, s60
	s_addc_u32 s65, s65, 0
	s_lshl_b32 s60, s57, 11
	s_add_u32 s66, s82, s60
	s_addc_u32 s67, s83, 0
	global_load_dwordx4 v[4:7], v0, s[64:65] nt
	global_load_dwordx4 v[8:11], v0, s[64:65] offset:1024 nt
	global_load_dwordx4 v[12:15], v0, s[64:65] offset:2048 nt
	global_load_dwordx4 v[16:19], v0, s[64:65] offset:3072 nt
	global_load_dwordx2 v[20:21], v1, s[66:67] nt
	global_load_dwordx2 v[22:23], v1, s[66:67] offset:512 nt
	global_load_dwordx2 v[24:25], v1, s[66:67] offset:1024 nt
	global_load_dwordx2 v[26:27], v1, s[66:67] offset:1536 nt
	s_add_u32 s57, s55, 8
	s_min_u32 s57, s57, s54
	s_cmp_lt_u32 s57, 0x8000
	s_cselect_b32 s64, s8, s10
	s_cselect_b32 s65, s9, s11
	s_cselect_b32 s60, 0, 0x8000
	s_sub_u32 s60, s57, s60
	s_lshl_b32 s60, s60, 12
	s_add_u32 s64, s64, s60
	s_addc_u32 s65, s65, 0
	s_lshl_b32 s60, s57, 11
	s_add_u32 s66, s82, s60
	s_addc_u32 s67, s83, 0
	global_load_dwordx4 v[36:39], v0, s[64:65] nt
	global_load_dwordx4 v[40:43], v0, s[64:65] offset:1024 nt
	global_load_dwordx4 v[44:47], v0, s[64:65] offset:2048 nt
	global_load_dwordx4 v[48:51], v0, s[64:65] offset:3072 nt
	global_load_dwordx2 v[52:53], v1, s[66:67] nt
	global_load_dwordx2 v[54:55], v1, s[66:67] offset:512 nt
	global_load_dwordx2 v[56:57], v1, s[66:67] offset:1024 nt
	global_load_dwordx2 v[58:59], v1, s[66:67] offset:1536 nt
	s_lshr_b32 s60, s55, 11
	s_sub_u32 s61, s55, 0x8000
	s_lshr_b32 s61, s61, 12
	s_add_u32 s61, s61, 16
	s_cmp_lt_u32 s55, 0x8000
	s_cselect_b32 s63, s60, s61
	s_cmp_eq_u32 s63, s56
	s_cbranch_scc1 .Lrp4_pk4
	s_mov_b32 s56, s63
	s_mul_i32 s60, s56, 0x9000
	s_add_u32 s60, s60, 0x3182000
	s_add_u32 s0, s92, s60
	s_addc_u32 s1, s93, 0
	global_load_dwordx4 v[160:163], v0, s[0:1]
	global_load_dwordx4 v[164:167], v0, s[0:1] offset:1024
	global_load_dwordx4 v[168:171], v0, s[0:1] offset:2048
	global_load_dwordx4 v[172:175], v0, s[0:1] offset:3072
	s_add_u32 s0, s22, 0x0
	s_addc_u32 s1, s23, 0
	global_load_dwordx4 v[176:179], v0, s[0:1]
	global_load_dwordx4 v[180:183], v0, s[0:1] offset:1024
	global_load_dwordx4 v[184:187], v0, s[0:1] offset:2048
	global_load_dwordx4 v[188:191], v0, s[0:1] offset:3072
	s_add_u32 s0, s20, 0x1000
	s_addc_u32 s1, s21, 0
	global_load_dwordx4 v[192:195], v0, s[0:1]
	global_load_dwordx4 v[196:199], v0, s[0:1] offset:1024
	global_load_dwordx4 v[200:203], v0, s[0:1] offset:2048
	global_load_dwordx4 v[204:207], v0, s[0:1] offset:3072
	s_mul_i32 s60, s56, 0x9000
	s_add_u32 s60, s60, 0x3184000
	s_add_u32 s0, s92, s60
	s_addc_u32 s1, s93, 0
	global_load_dwordx4 v[208:211], v0, s[0:1]
	global_load_dwordx4 v[212:215], v0, s[0:1] offset:1024
	global_load_dwordx4 v[216:219], v0, s[0:1] offset:2048
	global_load_dwordx4 v[220:223], v0, s[0:1] offset:3072
	s_mul_i32 s60, s56, 0x9000
	s_add_u32 s60, s60, 0x3183000
	s_add_u32 s0, s92, s60
	s_addc_u32 s1, s93, 0
	global_load_dwordx4 v[224:227], v0, s[0:1]
	global_load_dwordx4 v[228:231], v0, s[0:1] offset:1024
	global_load_dwordx4 v[232:235], v0, s[0:1] offset:2048
	global_load_dwordx4 v[236:239], v0, s[0:1] offset:3072
	s_waitcnt vmcnt(0)
	v_pk_add_f32 v[208:209], v[208:209], 1.0 op_sel_hi:[1,0]
	v_pk_add_f32 v[210:211], v[210:211], 1.0 op_sel_hi:[1,0]
	v_pk_add_f32 v[212:213], v[212:213], 1.0 op_sel_hi:[1,0]
	v_pk_add_f32 v[214:215], v[214:215], 1.0 op_sel_hi:[1,0]
	v_pk_add_f32 v[216:217], v[216:217], 1.0 op_sel_hi:[1,0]
	v_pk_add_f32 v[218:219], v[218:219], 1.0 op_sel_hi:[1,0]
	v_pk_add_f32 v[220:221], v[220:221], 1.0 op_sel_hi:[1,0]
	v_pk_add_f32 v[222:223], v[222:223], 1.0 op_sel_hi:[1,0]
.Lrp4_pk4:
	s_waitcnt vmcnt(8)
	v_lshlrev_b32_e32 v112, 16, v20
	v_and_b32_e32 v113, 0xffff0000, v20
	v_lshlrev_b32_e32 v114, 16, v21
	v_and_b32_e32 v115, 0xffff0000, v21
	v_lshlrev_b32_e32 v116, 16, v22
	v_and_b32_e32 v117, 0xffff0000, v22
	v_lshlrev_b32_e32 v118, 16, v23
	v_and_b32_e32 v119, 0xffff0000, v23
	v_lshlrev_b32_e32 v120, 16, v24
	v_and_b32_e32 v121, 0xffff0000, v24
	v_lshlrev_b32_e32 v122, 16, v25
	v_and_b32_e32 v123, 0xffff0000, v25
	v_lshlrev_b32_e32 v124, 16, v26
	v_and_b32_e32 v125, 0xffff0000, v26
	v_lshlrev_b32_e32 v100, 16, v27
	v_and_b32_e32 v101, 0xffff0000, v27
	v_pk_mul_f32 v[102:103], v[112:113], v[112:113]
	v_pk_mul_f32 v[106:107], v[114:115], v[114:115]
	v_pk_fma_f32 v[102:103], v[116:117], v[116:117], v[102:103]
	v_pk_fma_f32 v[106:107], v[118:119], v[118:119], v[106:107]
	v_pk_fma_f32 v[102:103], v[120:121], v[120:121], v[102:103]
	v_pk_fma_f32 v[106:107], v[122:123], v[122:123], v[106:107]
	v_pk_fma_f32 v[102:103], v[124:125], v[124:125], v[102:103]
	v_pk_fma_f32 v[106:107], v[100:101], v[100:101], v[106:107]
	s_nop 0
	v_pk_add_f32 v[102:103], v[102:103], v[106:107]
	s_nop 0
	v_add_f32_e32 v102, v102, v103
	s_nop 1
	v_add_f32_dpp v102, v102, v102 quad_perm:[1,0,3,2] row_mask:0xf bank_mask:0xf
	s_nop 1
	v_add_f32_dpp v102, v102, v102 quad_perm:[2,3,0,1] row_mask:0xf bank_mask:0xf
	s_nop 1
	v_add_f32_dpp v102, v102, v102 row_half_mirror row_mask:0xf bank_mask:0xf
	s_nop 1
	v_add_f32_dpp v102, v102, v102 row_mirror row_mask:0xf bank_mask:0xf
	s_nop 1
	v_add_f32_dpp v102, v102, v102 row_bcast:15 row_mask:0xa bank_mask:0xf
	s_nop 1
	v_add_f32_dpp v102, v102, v102 row_bcast:31 row_mask:0xc bank_mask:0xf
	s_nop 1
	v_readlane_b32 s74, v102, 63
	s_nop 2
	v_mov_b32_e32 v102, s74
; __device__ __forceinline__ unsigned pk_bf16(float lo, float hi) { const f32x2 v = {lo, hi}; const bf16x2_t b = __builtin_convertvector(v, bf16x2_t); return __builtin_bit_cast(unsigned, b); }
; template <bool HAS_F, bool HAS_H>
; __device__ __forceinline__ void phase_rows(const Params& p, int sp, int sn, float resw, bool from_input, bool write_x = true) {
;     ...
;             const float rs = 1.0f / sqrtf(wave_sum(ss) * (1.0f / D) + EPS) * resw;
;             const float* gate = mod + b * 9216 + sp * 3072 + 2048; const float* gp = p.in[7] + sp * D;
; #pragma unroll
;             for (int j = 0; j < 4; ++j) { const f32x4 g = *(const f32x4*)(gate + 4 * lane + 256 * j), q = *(const f32x4*)(gp + 4 * lane + 256 * j);
;                 v[j] = v[j] + g * (f[j] * rs * q);
;                 if (write_x) *(f32x4*)(p.out + (size_t)row * D + 4 * lane + 256 * j) = v[j]; }
;         }
;         if (HAS_H) {
;             float ss = 0.f;
; #pragma unroll
;             for (int j = 0; j < 4; ++j) ss += (v[j].x * v[j].x + v[j].y * v[j].y) + (v[j].z * v[j].z + v[j].w * v[j].w);
;             const float rs = 1.0f / sqrtf(wave_sum(ss) * (1.0f / D) + EPS);
;             const float* sh = mod + b * 9216 + sn * 3072; const float* scl = sh + 1024; const float* gq = p.in[6] + sn * D;
; #pragma unroll
;             for (int j = 0; j < 4; ++j) { const f32x4 a = *(const f32x4*)(sh + 4 * lane + 256 * j), s = *(const f32x4*)(scl + 4 * lane + 256 * j), q = *(const f32x4*)(gq + 4 * lane + 256 * j);
;                 const f32x4 h = (v[j] * rs * q) * (s + 1.0f) + a;
;                 u32x2 w; w.x = pk_bf16(h.x, h.y); w.y = pk_bf16(h.z, h.w);
;                 *(u32x2*)(H + (size_t)row * D + 4 * lane + 256 * j) = w; }
	v_fmamk_f32 v102, v102, 0x3a800000, v2
	v_mul_f32_e32 v103, 0x4f800000, v102
	v_cmp_gt_f32_e32 vcc, 0xf800000, v102
	s_nop 1
	v_cndmask_b32_e32 v102, v102, v103, vcc
	v_sqrt_f32_e32 v103, v102
	s_nop 0
	v_add_u32_e32 v104, -1, v103
	v_add_u32_e32 v106, 1, v103
	v_fma_f32 v107, -v104, v103, v102
	v_fma_f32 v108, -v106, v103, v102
	v_cmp_ge_f32_e64 s[76:77], 0, v107
	s_nop 1
	v_cndmask_b32_e64 v103, v103, v104, s[76:77]
	v_cmp_lt_f32_e64 s[76:77], 0, v108
	s_nop 1
	v_cndmask_b32_e64 v103, v103, v106, s[76:77]
	v_mul_f32_e32 v104, 0x37800000, v103
	v_cndmask_b32_e32 v103, v103, v104, vcc
	v_cmp_class_f32_e32 vcc, v102, v3
	s_nop 1
	v_cndmask_b32_e32 v102, v103, v102, vcc
	v_div_scale_f32 v103, s[76:77], v102, v102, 1.0
	v_rcp_f32_e32 v104, v103
	v_div_scale_f32 v106, vcc, 1.0, v102, 1.0
	v_fma_f32 v107, -v103, v104, 1.0
	v_fmac_f32_e32 v104, v107, v104
	v_mul_f32_e32 v107, v106, v104
	v_fma_f32 v108, -v103, v107, v106
	v_fmac_f32_e32 v107, v108, v104
	v_fma_f32 v103, -v103, v107, v106
	v_div_fmas_f32 v103, v103, v104, v107
	v_div_fixup_f32 v110, v103, v102, 1.0
	v_mul_f32_e32 v110, 0.5, v110
	v_pk_mul_f32 v[112:113], v[112:113], v[110:111] op_sel_hi:[1,0]
	v_pk_mul_f32 v[114:115], v[114:115], v[110:111] op_sel_hi:[1,0]
	v_pk_mul_f32 v[116:117], v[116:117], v[110:111] op_sel_hi:[1,0]
	v_pk_mul_f32 v[118:119], v[118:119], v[110:111] op_sel_hi:[1,0]
	v_pk_mul_f32 v[120:121], v[120:121], v[110:111] op_sel_hi:[1,0]
	v_pk_mul_f32 v[122:123], v[122:123], v[110:111] op_sel_hi:[1,0]
	v_pk_mul_f32 v[124:125], v[124:125], v[110:111] op_sel_hi:[1,0]
	v_pk_mul_f32 v[100:101], v[100:101], v[110:111] op_sel_hi:[1,0]
	v_pk_mul_f32 v[112:113], v[176:177], v[112:113]
	v_pk_mul_f32 v[114:115], v[178:179], v[114:115]
	v_pk_mul_f32 v[116:117], v[180:181], v[116:117]
	v_pk_mul_f32 v[118:119], v[182:183], v[118:119]
	v_pk_mul_f32 v[120:121], v[184:185], v[120:121]
	v_pk_mul_f32 v[122:123], v[186:187], v[122:123]
	v_pk_mul_f32 v[124:125], v[188:189], v[124:125]
	v_pk_mul_f32 v[100:101], v[190:191], v[100:101]
	v_pk_fma_f32 v[4:5], v[160:161], v[112:113], v[4:5]
	v_pk_fma_f32 v[6:7], v[162:163], v[114:115], v[6:7]
	v_pk_fma_f32 v[8:9], v[164:165], v[116:117], v[8:9]
	v_pk_fma_f32 v[10:11], v[166:167], v[118:119], v[10:11]
	v_pk_fma_f32 v[12:13], v[168:169], v[120:121], v[12:13]
	v_pk_fma_f32 v[14:15], v[170:171], v[122:123], v[14:15]
	v_pk_fma_f32 v[16:17], v[172:173], v[124:125], v[16:17]
	v_pk_fma_f32 v[18:19], v[174:175], v[100:101], v[18:19]
	s_lshl_b32 s60, s55, 12
	s_add_u32 s72, s84, s60
	s_addc_u32 s73, s85, 0
	global_store_dwordx4 v0, v[4:7], s[72:73] sc1
	global_store_dwordx4 v0, v[8:11], s[72:73] offset:1024 sc1
	global_store_dwordx4 v0, v[12:15], s[72:73] offset:2048 sc1
	global_store_dwordx4 v0, v[16:19], s[72:73] offset:3072 sc1
	v_pk_mul_f32 v[102:103], v[4:5], v[4:5]
	v_pk_mul_f32 v[106:107], v[6:7], v[6:7]
	v_pk_fma_f32 v[102:103], v[8:9], v[8:9], v[102:103]
	v_pk_fma_f32 v[106:107], v[10:11], v[10:11], v[106:107]
	v_pk_fma_f32 v[102:103], v[12:13], v[12:13], v[102:103]
	v_pk_fma_f32 v[106:107], v[14:15], v[14:15], v[106:107]
	v_pk_fma_f32 v[102:103], v[16:17], v[16:17], v[102:103]
	v_pk_fma_f32 v[106:107], v[18:19], v[18:19], v[106:107]
	s_nop 0
	v_pk_add_f32 v[102:103], v[102:103], v[106:107]
	s_nop 0
	v_add_f32_e32 v102, v102, v103
	s_nop 1
	v_add_f32_dpp v102, v102, v102 quad_perm:[1,0,3,2] row_mask:0xf bank_mask:0xf
	s_nop 1
	v_add_f32_dpp v102, v102, v102 quad_perm:[2,3,0,1] row_mask:0xf bank_mask:0xf
	s_nop 1
	v_add_f32_dpp v102, v102, v102 row_half_mirror row_mask:0xf bank_mask:0xf
	s_nop 1
	v_add_f32_dpp v102, v102, v102 row_mirror row_mask:0xf bank_mask:0xf
	s_nop 1
	v_add_f32_dpp v102, v102, v102 row_bcast:15 row_mask:0xa bank_mask:0xf
	s_nop 1
	v_add_f32_dpp v102, v102, v102 row_bcast:31 row_mask:0xc bank_mask:0xf
	s_nop 1
	v_readlane_b32 s74, v102, 63
	s_nop 2
	v_mov_b32_e32 v102, s74
	v_fmamk_f32 v102, v102, 0x3a800000, v2
	v_mul_f32_e32 v103, 0x4f800000, v102
	v_cmp_gt_f32_e32 vcc, 0xf800000, v102
	s_nop 1
	v_cndmask_b32_e32 v102, v102, v103, vcc
	v_sqrt_f32_e32 v103, v102
	s_nop 0
	v_add_u32_e32 v104, -1, v103
	v_add_u32_e32 v106, 1, v103
	v_fma_f32 v107, -v104, v103, v102
	v_fma_f32 v108, -v106, v103, v102
	v_cmp_ge_f32_e64 s[76:77], 0, v107
	s_nop 1
	v_cndmask_b32_e64 v103, v103, v104, s[76:77]
	v_cmp_lt_f32_e64 s[76:77], 0, v108
	s_nop 1
	v_cndmask_b32_e64 v103, v103, v106, s[76:77]
	v_mul_f32_e32 v104, 0x37800000, v103
	v_cndmask_b32_e32 v103, v103, v104, vcc
	v_cmp_class_f32_e32 vcc, v102, v3
	s_nop 1
	v_cndmask_b32_e32 v102, v103, v102, vcc
	v_div_scale_f32 v103, s[76:77], v102, v102, 1.0
	v_rcp_f32_e32 v104, v103
	v_div_scale_f32 v106, vcc, 1.0, v102, 1.0
	v_fma_f32 v107, -v103, v104, 1.0
	v_fmac_f32_e32 v104, v107, v104
	v_mul_f32_e32 v107, v106, v104
	v_fma_f32 v108, -v103, v107, v106
	v_fmac_f32_e32 v107, v108, v104
	v_fma_f32 v103, -v103, v107, v106
	v_div_fmas_f32 v103, v103, v104, v107
	v_div_fixup_f32 v110, v103, v102, 1.0
	s_lshl_b32 s60, s55, 11
	s_add_u32 s70, s78, s60
	s_addc_u32 s71, s79, 0
	v_pk_mul_f32 v[112:113], v[4:5], v[110:111] op_sel_hi:[1,0]
	v_pk_mul_f32 v[114:115], v[6:7], v[110:111] op_sel_hi:[1,0]
	v_pk_mul_f32 v[116:117], v[8:9], v[110:111] op_sel_hi:[1,0]
	v_pk_mul_f32 v[118:119], v[10:11], v[110:111] op_sel_hi:[1,0]
	v_pk_mul_f32 v[120:121], v[12:13], v[110:111] op_sel_hi:[1,0]
	v_pk_mul_f32 v[122:123], v[14:15], v[110:111] op_sel_hi:[1,0]
	v_pk_mul_f32 v[124:125], v[16:17], v[110:111] op_sel_hi:[1,0]
	v_pk_mul_f32 v[100:101], v[18:19], v[110:111] op_sel_hi:[1,0]
	v_pk_mul_f32 v[112:113], v[192:193], v[112:113]
	v_pk_mul_f32 v[114:115], v[194:195], v[114:115]
	v_pk_mul_f32 v[116:117], v[196:197], v[116:117]
; __device__ __forceinline__ unsigned pk_bf16(float lo, float hi) { const f32x2 v = {lo, hi}; const bf16x2_t b = __builtin_convertvector(v, bf16x2_t); return __builtin_bit_cast(unsigned, b); }
; __device__ __forceinline__ float lo_bf(unsigned w) { return __uint_as_float(w << 16); }
; __device__ __forceinline__ float hi_bf(unsigned w) { return __uint_as_float(w & 0xffff0000u); }
; template <bool HAS_F, bool HAS_H>
; __device__ __forceinline__ void phase_rows(const Params& p, int sp, int sn, float resw, bool from_input, bool write_x = true) {
;     ...
;     for (int row = gw; row < T; row += NGW) {
;         const int b = row_batch(row);
;         const float* xin = !from_input ? p.out + (size_t)row * D : (row < TP ? p.in[0] + (size_t)row * D : p.in[1] + (size_t)(row - TP) * D);
;         f32x4 v[4];
; #pragma unroll
;         for (int j = 0; j < 4; ++j) v[j] = *(const f32x4*)(xin + 4 * lane + 256 * j);
;         if (HAS_F) {
;             f32x4 f[4]; float ss = 0.f;
; #pragma unroll
;             for (int j = 0; j < 4; ++j) { const u32x2 w = *(const u32x2*)(F + (size_t)row * D + 4 * lane + 256 * j);
;                 f[j] = (f32x4){lo_bf(w.x), hi_bf(w.x), lo_bf(w.y), hi_bf(w.y)}; ss += (f[j].x * f[j].x + f[j].y * f[j].y) + (f[j].z * f[j].z + f[j].w * f[j].w); }
;     ...
;             const float* sh = mod + b * 9216 + sn * 3072; const float* scl = sh + 1024; const float* gq = p.in[6] + sn * D;
; #pragma unroll
;             for (int j = 0; j < 4; ++j) { const f32x4 a = *(const f32x4*)(sh + 4 * lane + 256 * j), s = *(const f32x4*)(scl + 4 * lane + 256 * j), q = *(const f32x4*)(gq + 4 * lane + 256 * j);
;                 const f32x4 h = (v[j] * rs * q) * (s + 1.0f) + a;
;                 u32x2 w; w.x = pk_bf16(h.x, h.y); w.y = pk_bf16(h.z, h.w);
;                 *(u32x2*)(H + (size_t)row * D + 4 * lane + 256 * j) = w; }
	v_pk_mul_f32 v[118:119], v[198:199], v[118:119]
	v_pk_mul_f32 v[120:121], v[200:201], v[120:121]
	v_pk_mul_f32 v[122:123], v[202:203], v[122:123]
	v_pk_mul_f32 v[124:125], v[204:205], v[124:125]
	v_pk_mul_f32 v[100:101], v[206:207], v[100:101]
	v_pk_fma_f32 v[112:113], v[208:209], v[112:113], v[224:225]
	v_pk_fma_f32 v[114:115], v[210:211], v[114:115], v[226:227]
	v_pk_fma_f32 v[116:117], v[212:213], v[116:117], v[228:229]
	v_pk_fma_f32 v[118:119], v[214:215], v[118:119], v[230:231]
	v_pk_fma_f32 v[120:121], v[216:217], v[120:121], v[232:233]
	v_pk_fma_f32 v[122:123], v[218:219], v[122:123], v[234:235]
	v_pk_fma_f32 v[124:125], v[220:221], v[124:125], v[236:237]
	v_pk_fma_f32 v[100:101], v[222:223], v[100:101], v[238:239]
	v_cvt_pk_bf16_f32 v240, v112, v113
	v_cvt_pk_bf16_f32 v241, v114, v115
	v_cvt_pk_bf16_f32 v242, v116, v117
	v_cvt_pk_bf16_f32 v243, v118, v119
	v_cvt_pk_bf16_f32 v244, v120, v121
	v_cvt_pk_bf16_f32 v245, v122, v123
	v_cvt_pk_bf16_f32 v246, v124, v125
	v_cvt_pk_bf16_f32 v247, v100, v101
	global_store_dwordx2 v1, v[240:241], s[70:71]
	global_store_dwordx2 v1, v[242:243], s[70:71] offset:512
	global_store_dwordx2 v1, v[244:245], s[70:71] offset:1024
	global_store_dwordx2 v1, v[246:247], s[70:71] offset:1536
	s_add_u32 s55, s55, 8
	s_add_u32 s57, s55, 8
	s_min_u32 s57, s57, s54
	s_cmp_lt_u32 s57, 0x8000
	s_cselect_b32 s64, s8, s10
	s_cselect_b32 s65, s9, s11
	s_cselect_b32 s60, 0, 0x8000
	s_sub_u32 s60, s57, s60
	s_lshl_b32 s60, s60, 12
	s_add_u32 s64, s64, s60
	s_addc_u32 s65, s65, 0
	s_lshl_b32 s60, s57, 11
	s_add_u32 s66, s82, s60
	s_addc_u32 s67, s83, 0
	global_load_dwordx4 v[4:7], v0, s[64:65] nt
	global_load_dwordx4 v[8:11], v0, s[64:65] offset:1024 nt
	global_load_dwordx4 v[12:15], v0, s[64:65] offset:2048 nt
	global_load_dwordx4 v[16:19], v0, s[64:65] offset:3072 nt
	global_load_dwordx2 v[20:21], v1, s[66:67] nt
	global_load_dwordx2 v[22:23], v1, s[66:67] offset:512 nt
	global_load_dwordx2 v[24:25], v1, s[66:67] offset:1024 nt
	global_load_dwordx2 v[26:27], v1, s[66:67] offset:1536 nt
	s_lshr_b32 s60, s55, 11
	s_sub_u32 s61, s55, 0x8000
	s_lshr_b32 s61, s61, 12
	s_add_u32 s61, s61, 16
	s_cmp_lt_u32 s55, 0x8000
	s_cselect_b32 s63, s60, s61
	s_cmp_eq_u32 s63, s56
	s_cbranch_scc1 .Lrp4_pk5
	s_mov_b32 s56, s63
	s_mul_i32 s60, s56, 0x9000
	s_add_u32 s60, s60, 0x3182000
	s_add_u32 s0, s92, s60
	s_addc_u32 s1, s93, 0
	global_load_dwordx4 v[160:163], v0, s[0:1]
	global_load_dwordx4 v[164:167], v0, s[0:1] offset:1024
	global_load_dwordx4 v[168:171], v0, s[0:1] offset:2048
	global_load_dwordx4 v[172:175], v0, s[0:1] offset:3072
	s_add_u32 s0, s22, 0x0
	s_addc_u32 s1, s23, 0
	global_load_dwordx4 v[176:179], v0, s[0:1]
	global_load_dwordx4 v[180:183], v0, s[0:1] offset:1024
	global_load_dwordx4 v[184:187], v0, s[0:1] offset:2048
	global_load_dwordx4 v[188:191], v0, s[0:1] offset:3072
	s_add_u32 s0, s20, 0x1000
	s_addc_u32 s1, s21, 0
	global_load_dwordx4 v[192:195], v0, s[0:1]
	global_load_dwordx4 v[196:199], v0, s[0:1] offset:1024
	global_load_dwordx4 v[200:203], v0, s[0:1] offset:2048
	global_load_dwordx4 v[204:207], v0, s[0:1] offset:3072
	s_mul_i32 s60, s56, 0x9000
	s_add_u32 s60, s60, 0x3184000
	s_add_u32 s0, s92, s60
	s_addc_u32 s1, s93, 0
	global_load_dwordx4 v[208:211], v0, s[0:1]
	global_load_dwordx4 v[212:215], v0, s[0:1] offset:1024
	global_load_dwordx4 v[216:219], v0, s[0:1] offset:2048
	global_load_dwordx4 v[220:223], v0, s[0:1] offset:3072
	s_mul_i32 s60, s56, 0x9000
	s_add_u32 s60, s60, 0x3183000
	s_add_u32 s0, s92, s60
	s_addc_u32 s1, s93, 0
	global_load_dwordx4 v[224:227], v0, s[0:1]
	global_load_dwordx4 v[228:231], v0, s[0:1] offset:1024
	global_load_dwordx4 v[232:235], v0, s[0:1] offset:2048
	global_load_dwordx4 v[236:239], v0, s[0:1] offset:3072
	s_waitcnt vmcnt(0)
	v_pk_add_f32 v[208:209], v[208:209], 1.0 op_sel_hi:[1,0]
	v_pk_add_f32 v[210:211], v[210:211], 1.0 op_sel_hi:[1,0]
	v_pk_add_f32 v[212:213], v[212:213], 1.0 op_sel_hi:[1,0]
	v_pk_add_f32 v[214:215], v[214:215], 1.0 op_sel_hi:[1,0]
	v_pk_add_f32 v[216:217], v[216:217], 1.0 op_sel_hi:[1,0]
	v_pk_add_f32 v[218:219], v[218:219], 1.0 op_sel_hi:[1,0]
	v_pk_add_f32 v[220:221], v[220:221], 1.0 op_sel_hi:[1,0]
	v_pk_add_f32 v[222:223], v[222:223], 1.0 op_sel_hi:[1,0]
.Lrp4_pk5:
	s_waitcnt vmcnt(16)
; __device__ __forceinline__ float lo_bf(unsigned w) { return __uint_as_float(w << 16); }
; __device__ __forceinline__ float hi_bf(unsigned w) { return __uint_as_float(w & 0xffff0000u); }
; template <bool HAS_F, bool HAS_H>
; __device__ __forceinline__ void phase_rows(const Params& p, int sp, int sn, float resw, bool from_input, bool write_x = true) {
;     ...
;         if (HAS_F) {
;             f32x4 f[4]; float ss = 0.f;
; #pragma unroll
;             for (int j = 0; j < 4; ++j) { const u32x2 w = *(const u32x2*)(F + (size_t)row * D + 4 * lane + 256 * j);
;                 f[j] = (f32x4){lo_bf(w.x), hi_bf(w.x), lo_bf(w.y), hi_bf(w.y)}; ss += (f[j].x * f[j].x + f[j].y * f[j].y) + (f[j].z * f[j].z + f[j].w * f[j].w); }
;             const float rs = 1.0f / sqrtf(wave_sum(ss) * (1.0f / D) + EPS) * resw;
;             const float* gate = mod + b * 9216 + sp * 3072 + 2048; const float* gp = p.in[7] + sp * D;
; #pragma unroll
;             for (int j = 0; j < 4; ++j) { const f32x4 g = *(const f32x4*)(gate + 4 * lane + 256 * j), q = *(const f32x4*)(gp + 4 * lane + 256 * j);
;                 v[j] = v[j] + g * (f[j] * rs * q);
;                 if (write_x) *(f32x4*)(p.out + (size_t)row * D + 4 * lane + 256 * j) = v[j]; }
;         }
;         if (HAS_H) {
;             float ss = 0.f;
; #pragma unroll
;             for (int j = 0; j < 4; ++j) ss += (v[j].x * v[j].x + v[j].y * v[j].y) + (v[j].z * v[j].z + v[j].w * v[j].w);
;             const float rs = 1.0f / sqrtf(wave_sum(ss) * (1.0f / D) + EPS);
	v_lshlrev_b32_e32 v112, 16, v52
	v_and_b32_e32 v113, 0xffff0000, v52
	v_lshlrev_b32_e32 v114, 16, v53
	v_and_b32_e32 v115, 0xffff0000, v53
	v_lshlrev_b32_e32 v116, 16, v54
	v_and_b32_e32 v117, 0xffff0000, v54
	v_lshlrev_b32_e32 v118, 16, v55
	v_and_b32_e32 v119, 0xffff0000, v55
	v_lshlrev_b32_e32 v120, 16, v56
	v_and_b32_e32 v121, 0xffff0000, v56
	v_lshlrev_b32_e32 v122, 16, v57
	v_and_b32_e32 v123, 0xffff0000, v57
	v_lshlrev_b32_e32 v124, 16, v58
	v_and_b32_e32 v125, 0xffff0000, v58
	v_lshlrev_b32_e32 v100, 16, v59
	v_and_b32_e32 v101, 0xffff0000, v59
	v_pk_mul_f32 v[102:103], v[112:113], v[112:113]
	v_pk_mul_f32 v[106:107], v[114:115], v[114:115]
	v_pk_fma_f32 v[102:103], v[116:117], v[116:117], v[102:103]
	v_pk_fma_f32 v[106:107], v[118:119], v[118:119], v[106:107]
	v_pk_fma_f32 v[102:103], v[120:121], v[120:121], v[102:103]
	v_pk_fma_f32 v[106:107], v[122:123], v[122:123], v[106:107]
	v_pk_fma_f32 v[102:103], v[124:125], v[124:125], v[102:103]
	v_pk_fma_f32 v[106:107], v[100:101], v[100:101], v[106:107]
	s_nop 0
	v_pk_add_f32 v[102:103], v[102:103], v[106:107]
	s_nop 0
	v_add_f32_e32 v102, v102, v103
	s_nop 1
	v_add_f32_dpp v102, v102, v102 quad_perm:[1,0,3,2] row_mask:0xf bank_mask:0xf
	s_nop 1
	v_add_f32_dpp v102, v102, v102 quad_perm:[2,3,0,1] row_mask:0xf bank_mask:0xf
	s_nop 1
	v_add_f32_dpp v102, v102, v102 row_half_mirror row_mask:0xf bank_mask:0xf
	s_nop 1
	v_add_f32_dpp v102, v102, v102 row_mirror row_mask:0xf bank_mask:0xf
	s_nop 1
	v_add_f32_dpp v102, v102, v102 row_bcast:15 row_mask:0xa bank_mask:0xf
	s_nop 1
	v_add_f32_dpp v102, v102, v102 row_bcast:31 row_mask:0xc bank_mask:0xf
	s_nop 1
	v_readlane_b32 s74, v102, 63
	s_nop 2
	v_mov_b32_e32 v102, s74
	v_fmamk_f32 v102, v102, 0x3a800000, v2
	v_mul_f32_e32 v103, 0x4f800000, v102
	v_cmp_gt_f32_e32 vcc, 0xf800000, v102
	s_nop 1
	v_cndmask_b32_e32 v102, v102, v103, vcc
	v_sqrt_f32_e32 v103, v102
	s_nop 0
	v_add_u32_e32 v104, -1, v103
	v_add_u32_e32 v106, 1, v103
	v_fma_f32 v107, -v104, v103, v102
	v_fma_f32 v108, -v106, v103, v102
	v_cmp_ge_f32_e64 s[76:77], 0, v107
	s_nop 1
	v_cndmask_b32_e64 v103, v103, v104, s[76:77]
	v_cmp_lt_f32_e64 s[76:77], 0, v108
	s_nop 1
	v_cndmask_b32_e64 v103, v103, v106, s[76:77]
	v_mul_f32_e32 v104, 0x37800000, v103
	v_cndmask_b32_e32 v103, v103, v104, vcc
	v_cmp_class_f32_e32 vcc, v102, v3
	s_nop 1
	v_cndmask_b32_e32 v102, v103, v102, vcc
	v_div_scale_f32 v103, s[76:77], v102, v102, 1.0
	v_rcp_f32_e32 v104, v103
	v_div_scale_f32 v106, vcc, 1.0, v102, 1.0
	v_fma_f32 v107, -v103, v104, 1.0
	v_fmac_f32_e32 v104, v107, v104
	v_mul_f32_e32 v107, v106, v104
	v_fma_f32 v108, -v103, v107, v106
	v_fmac_f32_e32 v107, v108, v104
	v_fma_f32 v103, -v103, v107, v106
	v_div_fmas_f32 v103, v103, v104, v107
	v_div_fixup_f32 v110, v103, v102, 1.0
	v_mul_f32_e32 v110, 0.5, v110
	v_pk_mul_f32 v[112:113], v[112:113], v[110:111] op_sel_hi:[1,0]
	v_pk_mul_f32 v[114:115], v[114:115], v[110:111] op_sel_hi:[1,0]
	v_pk_mul_f32 v[116:117], v[116:117], v[110:111] op_sel_hi:[1,0]
	v_pk_mul_f32 v[118:119], v[118:119], v[110:111] op_sel_hi:[1,0]
	v_pk_mul_f32 v[120:121], v[120:121], v[110:111] op_sel_hi:[1,0]
	v_pk_mul_f32 v[122:123], v[122:123], v[110:111] op_sel_hi:[1,0]
	v_pk_mul_f32 v[124:125], v[124:125], v[110:111] op_sel_hi:[1,0]
	v_pk_mul_f32 v[100:101], v[100:101], v[110:111] op_sel_hi:[1,0]
	v_pk_mul_f32 v[112:113], v[176:177], v[112:113]
	v_pk_mul_f32 v[114:115], v[178:179], v[114:115]
	v_pk_mul_f32 v[116:117], v[180:181], v[116:117]
	v_pk_mul_f32 v[118:119], v[182:183], v[118:119]
	v_pk_mul_f32 v[120:121], v[184:185], v[120:121]
	v_pk_mul_f32 v[122:123], v[186:187], v[122:123]
	v_pk_mul_f32 v[124:125], v[188:189], v[124:125]
	v_pk_mul_f32 v[100:101], v[190:191], v[100:101]
	v_pk_fma_f32 v[36:37], v[160:161], v[112:113], v[36:37]
	v_pk_fma_f32 v[38:39], v[162:163], v[114:115], v[38:39]
	v_pk_fma_f32 v[40:41], v[164:165], v[116:117], v[40:41]
	v_pk_fma_f32 v[42:43], v[166:167], v[118:119], v[42:43]
	v_pk_fma_f32 v[44:45], v[168:169], v[120:121], v[44:45]
	v_pk_fma_f32 v[46:47], v[170:171], v[122:123], v[46:47]
	v_pk_fma_f32 v[48:49], v[172:173], v[124:125], v[48:49]
	v_pk_fma_f32 v[50:51], v[174:175], v[100:101], v[50:51]
	s_lshl_b32 s60, s55, 12
	s_add_u32 s72, s84, s60
	s_addc_u32 s73, s85, 0
	global_store_dwordx4 v0, v[36:39], s[72:73] sc1
	global_store_dwordx4 v0, v[40:43], s[72:73] offset:1024 sc1
	global_store_dwordx4 v0, v[44:47], s[72:73] offset:2048 sc1
	global_store_dwordx4 v0, v[48:51], s[72:73] offset:3072 sc1
	v_pk_mul_f32 v[102:103], v[36:37], v[36:37]
	v_pk_mul_f32 v[106:107], v[38:39], v[38:39]
	v_pk_fma_f32 v[102:103], v[40:41], v[40:41], v[102:103]
	v_pk_fma_f32 v[106:107], v[42:43], v[42:43], v[106:107]
	v_pk_fma_f32 v[102:103], v[44:45], v[44:45], v[102:103]
	v_pk_fma_f32 v[106:107], v[46:47], v[46:47], v[106:107]
	v_pk_fma_f32 v[102:103], v[48:49], v[48:49], v[102:103]
	v_pk_fma_f32 v[106:107], v[50:51], v[50:51], v[106:107]
	s_nop 0
	v_pk_add_f32 v[102:103], v[102:103], v[106:107]
	s_nop 0
	v_add_f32_e32 v102, v102, v103
	s_nop 1
	v_add_f32_dpp v102, v102, v102 quad_perm:[1,0,3,2] row_mask:0xf bank_mask:0xf
	s_nop 1
	v_add_f32_dpp v102, v102, v102 quad_perm:[2,3,0,1] row_mask:0xf bank_mask:0xf
	s_nop 1
	v_add_f32_dpp v102, v102, v102 row_half_mirror row_mask:0xf bank_mask:0xf
	s_nop 1
	v_add_f32_dpp v102, v102, v102 row_mirror row_mask:0xf bank_mask:0xf
	s_nop 1
	v_add_f32_dpp v102, v102, v102 row_bcast:15 row_mask:0xa bank_mask:0xf
	s_nop 1
	v_add_f32_dpp v102, v102, v102 row_bcast:31 row_mask:0xc bank_mask:0xf
	s_nop 1
	v_readlane_b32 s74, v102, 63
	s_nop 2
	v_mov_b32_e32 v102, s74
	v_fmamk_f32 v102, v102, 0x3a800000, v2
; __device__ __forceinline__ unsigned pk_bf16(float lo, float hi) { const f32x2 v = {lo, hi}; const bf16x2_t b = __builtin_convertvector(v, bf16x2_t); return __builtin_bit_cast(unsigned, b); }
; template <bool HAS_F, bool HAS_H>
; __device__ __forceinline__ void phase_rows(const Params& p, int sp, int sn, float resw, bool from_input, bool write_x = true) {
;     ...
;     for (int row = gw; row < T; row += NGW) {
;         const int b = row_batch(row);
;         const float* xin = !from_input ? p.out + (size_t)row * D : (row < TP ? p.in[0] + (size_t)row * D : p.in[1] + (size_t)(row - TP) * D);
;         f32x4 v[4];
; #pragma unroll
;         for (int j = 0; j < 4; ++j) v[j] = *(const f32x4*)(xin + 4 * lane + 256 * j);
;     ...
;             const float* sh = mod + b * 9216 + sn * 3072; const float* scl = sh + 1024; const float* gq = p.in[6] + sn * D;
; #pragma unroll
;             for (int j = 0; j < 4; ++j) { const f32x4 a = *(const f32x4*)(sh + 4 * lane + 256 * j), s = *(const f32x4*)(scl + 4 * lane + 256 * j), q = *(const f32x4*)(gq + 4 * lane + 256 * j);
;                 const f32x4 h = (v[j] * rs * q) * (s + 1.0f) + a;
;                 u32x2 w; w.x = pk_bf16(h.x, h.y); w.y = pk_bf16(h.z, h.w);
;                 *(u32x2*)(H + (size_t)row * D + 4 * lane + 256 * j) = w; }
	v_mul_f32_e32 v103, 0x4f800000, v102
	v_cmp_gt_f32_e32 vcc, 0xf800000, v102
	s_nop 1
	v_cndmask_b32_e32 v102, v102, v103, vcc
	v_sqrt_f32_e32 v103, v102
	s_nop 0
	v_add_u32_e32 v104, -1, v103
	v_add_u32_e32 v106, 1, v103
	v_fma_f32 v107, -v104, v103, v102
	v_fma_f32 v108, -v106, v103, v102
	v_cmp_ge_f32_e64 s[76:77], 0, v107
	s_nop 1
	v_cndmask_b32_e64 v103, v103, v104, s[76:77]
	v_cmp_lt_f32_e64 s[76:77], 0, v108
	s_nop 1
	v_cndmask_b32_e64 v103, v103, v106, s[76:77]
	v_mul_f32_e32 v104, 0x37800000, v103
	v_cndmask_b32_e32 v103, v103, v104, vcc
	v_cmp_class_f32_e32 vcc, v102, v3
	s_nop 1
	v_cndmask_b32_e32 v102, v103, v102, vcc
	v_div_scale_f32 v103, s[76:77], v102, v102, 1.0
	v_rcp_f32_e32 v104, v103
	v_div_scale_f32 v106, vcc, 1.0, v102, 1.0
	v_fma_f32 v107, -v103, v104, 1.0
	v_fmac_f32_e32 v104, v107, v104
	v_mul_f32_e32 v107, v106, v104
	v_fma_f32 v108, -v103, v107, v106
	v_fmac_f32_e32 v107, v108, v104
	v_fma_f32 v103, -v103, v107, v106
	v_div_fmas_f32 v103, v103, v104, v107
	v_div_fixup_f32 v110, v103, v102, 1.0
	s_lshl_b32 s60, s55, 11
	s_add_u32 s70, s78, s60
	s_addc_u32 s71, s79, 0
	v_pk_mul_f32 v[112:113], v[36:37], v[110:111] op_sel_hi:[1,0]
	v_pk_mul_f32 v[114:115], v[38:39], v[110:111] op_sel_hi:[1,0]
	v_pk_mul_f32 v[116:117], v[40:41], v[110:111] op_sel_hi:[1,0]
	v_pk_mul_f32 v[118:119], v[42:43], v[110:111] op_sel_hi:[1,0]
	v_pk_mul_f32 v[120:121], v[44:45], v[110:111] op_sel_hi:[1,0]
	v_pk_mul_f32 v[122:123], v[46:47], v[110:111] op_sel_hi:[1,0]
	v_pk_mul_f32 v[124:125], v[48:49], v[110:111] op_sel_hi:[1,0]
	v_pk_mul_f32 v[100:101], v[50:51], v[110:111] op_sel_hi:[1,0]
	v_pk_mul_f32 v[112:113], v[192:193], v[112:113]
	v_pk_mul_f32 v[114:115], v[194:195], v[114:115]
	v_pk_mul_f32 v[116:117], v[196:197], v[116:117]
	v_pk_mul_f32 v[118:119], v[198:199], v[118:119]
	v_pk_mul_f32 v[120:121], v[200:201], v[120:121]
	v_pk_mul_f32 v[122:123], v[202:203], v[122:123]
	v_pk_mul_f32 v[124:125], v[204:205], v[124:125]
	v_pk_mul_f32 v[100:101], v[206:207], v[100:101]
	v_pk_fma_f32 v[112:113], v[208:209], v[112:113], v[224:225]
	v_pk_fma_f32 v[114:115], v[210:211], v[114:115], v[226:227]
	v_pk_fma_f32 v[116:117], v[212:213], v[116:117], v[228:229]
	v_pk_fma_f32 v[118:119], v[214:215], v[118:119], v[230:231]
	v_pk_fma_f32 v[120:121], v[216:217], v[120:121], v[232:233]
	v_pk_fma_f32 v[122:123], v[218:219], v[122:123], v[234:235]
	v_pk_fma_f32 v[124:125], v[220:221], v[124:125], v[236:237]
	v_pk_fma_f32 v[100:101], v[222:223], v[100:101], v[238:239]
	v_cvt_pk_bf16_f32 v240, v112, v113
	v_cvt_pk_bf16_f32 v241, v114, v115
	v_cvt_pk_bf16_f32 v242, v116, v117
	v_cvt_pk_bf16_f32 v243, v118, v119
	v_cvt_pk_bf16_f32 v244, v120, v121
	v_cvt_pk_bf16_f32 v245, v122, v123
	v_cvt_pk_bf16_f32 v246, v124, v125
	v_cvt_pk_bf16_f32 v247, v100, v101
	global_store_dwordx2 v1, v[240:241], s[70:71]
	global_store_dwordx2 v1, v[242:243], s[70:71] offset:512
	global_store_dwordx2 v1, v[244:245], s[70:71] offset:1024
	global_store_dwordx2 v1, v[246:247], s[70:71] offset:1536
	s_add_u32 s55, s55, 8
.Lrp4_loop3:
	s_add_u32 s57, s55, 8
	s_min_u32 s57, s57, s54
	s_cmp_lt_u32 s57, 0x8000
	s_cselect_b32 s64, s8, s10
	s_cselect_b32 s65, s9, s11
	s_cselect_b32 s60, 0, 0x8000
	s_sub_u32 s60, s57, s60
	s_lshl_b32 s60, s60, 12
	s_add_u32 s64, s64, s60
	s_addc_u32 s65, s65, 0
	s_lshl_b32 s60, s57, 11
	s_add_u32 s66, s82, s60
	s_addc_u32 s67, s83, 0
	global_load_dwordx4 v[36:39], v0, s[64:65] nt
	global_load_dwordx4 v[40:43], v0, s[64:65] offset:1024 nt
	global_load_dwordx4 v[44:47], v0, s[64:65] offset:2048 nt
	global_load_dwordx4 v[48:51], v0, s[64:65] offset:3072 nt
	global_load_dwordx2 v[52:53], v1, s[66:67] nt
	global_load_dwordx2 v[54:55], v1, s[66:67] offset:512 nt
	global_load_dwordx2 v[56:57], v1, s[66:67] offset:1024 nt
	global_load_dwordx2 v[58:59], v1, s[66:67] offset:1536 nt
	s_lshr_b32 s60, s55, 11
	s_sub_u32 s61, s55, 0x8000
	s_lshr_b32 s61, s61, 12
	s_add_u32 s61, s61, 16
	s_cmp_lt_u32 s55, 0x8000
	s_cselect_b32 s63, s60, s61
	s_cmp_eq_u32 s63, s56
	s_cbranch_scc1 .Lrp4_pk6
	s_mov_b32 s56, s63
	s_mul_i32 s60, s56, 0x9000
	s_add_u32 s60, s60, 0x3182000
	s_add_u32 s0, s92, s60
	s_addc_u32 s1, s93, 0
	global_load_dwordx4 v[160:163], v0, s[0:1]
	global_load_dwordx4 v[164:167], v0, s[0:1] offset:1024
	global_load_dwordx4 v[168:171], v0, s[0:1] offset:2048
	global_load_dwordx4 v[172:175], v0, s[0:1] offset:3072
	s_add_u32 s0, s22, 0x0
	s_addc_u32 s1, s23, 0
	global_load_dwordx4 v[176:179], v0, s[0:1]
	global_load_dwordx4 v[180:183], v0, s[0:1] offset:1024
	global_load_dwordx4 v[184:187], v0, s[0:1] offset:2048
	global_load_dwordx4 v[188:191], v0, s[0:1] offset:3072
	s_add_u32 s0, s20, 0x1000
	s_addc_u32 s1, s21, 0
	global_load_dwordx4 v[192:195], v0, s[0:1]
	global_load_dwordx4 v[196:199], v0, s[0:1] offset:1024
	global_load_dwordx4 v[200:203], v0, s[0:1] offset:2048
	global_load_dwordx4 v[204:207], v0, s[0:1] offset:3072
	s_mul_i32 s60, s56, 0x9000
	s_add_u32 s60, s60, 0x3184000
	s_add_u32 s0, s92, s60
	s_addc_u32 s1, s93, 0
	global_load_dwordx4 v[208:211], v0, s[0:1]
	global_load_dwordx4 v[212:215], v0, s[0:1] offset:1024
	global_load_dwordx4 v[216:219], v0, s[0:1] offset:2048
	global_load_dwordx4 v[220:223], v0, s[0:1] offset:3072
	s_mul_i32 s60, s56, 0x9000
	s_add_u32 s60, s60, 0x3183000
	s_add_u32 s0, s92, s60
	s_addc_u32 s1, s93, 0
	global_load_dwordx4 v[224:227], v0, s[0:1]
	global_load_dwordx4 v[228:231], v0, s[0:1] offset:1024
	global_load_dwordx4 v[232:235], v0, s[0:1] offset:2048
	global_load_dwordx4 v[236:239], v0, s[0:1] offset:3072
	s_waitcnt vmcnt(0)
	v_pk_add_f32 v[208:209], v[208:209], 1.0 op_sel_hi:[1,0]
	v_pk_add_f32 v[210:211], v[210:211], 1.0 op_sel_hi:[1,0]
	v_pk_add_f32 v[212:213], v[212:213], 1.0 op_sel_hi:[1,0]
	v_pk_add_f32 v[214:215], v[214:215], 1.0 op_sel_hi:[1,0]
	v_pk_add_f32 v[216:217], v[216:217], 1.0 op_sel_hi:[1,0]
	v_pk_add_f32 v[218:219], v[218:219], 1.0 op_sel_hi:[1,0]
	v_pk_add_f32 v[220:221], v[220:221], 1.0 op_sel_hi:[1,0]
	v_pk_add_f32 v[222:223], v[222:223], 1.0 op_sel_hi:[1,0]
; __device__ __forceinline__ float lo_bf(unsigned w) { return __uint_as_float(w << 16); }
; __device__ __forceinline__ float hi_bf(unsigned w) { return __uint_as_float(w & 0xffff0000u); }
; template <bool HAS_F, bool HAS_H>
; __device__ __forceinline__ void phase_rows(const Params& p, int sp, int sn, float resw, bool from_input, bool write_x = true) {
;     ...
;         if (HAS_F) {
;             f32x4 f[4]; float ss = 0.f;
; #pragma unroll
;             for (int j = 0; j < 4; ++j) { const u32x2 w = *(const u32x2*)(F + (size_t)row * D + 4 * lane + 256 * j);
;                 f[j] = (f32x4){lo_bf(w.x), hi_bf(w.x), lo_bf(w.y), hi_bf(w.y)}; ss += (f[j].x * f[j].x + f[j].y * f[j].y) + (f[j].z * f[j].z + f[j].w * f[j].w); }
;             const float rs = 1.0f / sqrtf(wave_sum(ss) * (1.0f / D) + EPS) * resw;
;             const float* gate = mod + b * 9216 + sp * 3072 + 2048; const float* gp = p.in[7] + sp * D;
; #pragma unroll
;             for (int j = 0; j < 4; ++j) { const f32x4 g = *(const f32x4*)(gate + 4 * lane + 256 * j), q = *(const f32x4*)(gp + 4 * lane + 256 * j);
;                 v[j] = v[j] + g * (f[j] * rs * q);
;                 if (write_x) *(f32x4*)(p.out + (size_t)row * D + 4 * lane + 256 * j) = v[j]; }
;         }
;         if (HAS_H) {
;             float ss = 0.f;
; #pragma unroll
;             for (int j = 0; j < 4; ++j) ss += (v[j].x * v[j].x + v[j].y * v[j].y) + (v[j].z * v[j].z + v[j].w * v[j].w);
;             const float rs = 1.0f / sqrtf(wave_sum(ss) * (1.0f / D) + EPS);
.Lrp4_pk6:
	s_waitcnt vmcnt(16)
	v_lshlrev_b32_e32 v112, 16, v20
	v_and_b32_e32 v113, 0xffff0000, v20
	v_lshlrev_b32_e32 v114, 16, v21
	v_and_b32_e32 v115, 0xffff0000, v21
	v_lshlrev_b32_e32 v116, 16, v22
	v_and_b32_e32 v117, 0xffff0000, v22
	v_lshlrev_b32_e32 v118, 16, v23
	v_and_b32_e32 v119, 0xffff0000, v23
	v_lshlrev_b32_e32 v120, 16, v24
	v_and_b32_e32 v121, 0xffff0000, v24
	v_lshlrev_b32_e32 v122, 16, v25
	v_and_b32_e32 v123, 0xffff0000, v25
	v_lshlrev_b32_e32 v124, 16, v26
	v_and_b32_e32 v125, 0xffff0000, v26
	v_lshlrev_b32_e32 v100, 16, v27
	v_and_b32_e32 v101, 0xffff0000, v27
	v_pk_mul_f32 v[102:103], v[112:113], v[112:113]
	v_pk_mul_f32 v[106:107], v[114:115], v[114:115]
	v_pk_fma_f32 v[102:103], v[116:117], v[116:117], v[102:103]
	v_pk_fma_f32 v[106:107], v[118:119], v[118:119], v[106:107]
	v_pk_fma_f32 v[102:103], v[120:121], v[120:121], v[102:103]
	v_pk_fma_f32 v[106:107], v[122:123], v[122:123], v[106:107]
	v_pk_fma_f32 v[102:103], v[124:125], v[124:125], v[102:103]
	v_pk_fma_f32 v[106:107], v[100:101], v[100:101], v[106:107]
	s_nop 0
	v_pk_add_f32 v[102:103], v[102:103], v[106:107]
	s_nop 0
	v_add_f32_e32 v102, v102, v103
	s_nop 1
	v_add_f32_dpp v102, v102, v102 quad_perm:[1,0,3,2] row_mask:0xf bank_mask:0xf
	s_nop 1
	v_add_f32_dpp v102, v102, v102 quad_perm:[2,3,0,1] row_mask:0xf bank_mask:0xf
	s_nop 1
	v_add_f32_dpp v102, v102, v102 row_half_mirror row_mask:0xf bank_mask:0xf
	s_nop 1
	v_add_f32_dpp v102, v102, v102 row_mirror row_mask:0xf bank_mask:0xf
	s_nop 1
	v_add_f32_dpp v102, v102, v102 row_bcast:15 row_mask:0xa bank_mask:0xf
	s_nop 1
	v_add_f32_dpp v102, v102, v102 row_bcast:31 row_mask:0xc bank_mask:0xf
	s_nop 1
	v_readlane_b32 s74, v102, 63
	s_nop 2
	v_mov_b32_e32 v102, s74
	v_fmamk_f32 v102, v102, 0x3a800000, v2
	v_mul_f32_e32 v103, 0x4f800000, v102
	v_cmp_gt_f32_e32 vcc, 0xf800000, v102
	s_nop 1
	v_cndmask_b32_e32 v102, v102, v103, vcc
	v_sqrt_f32_e32 v103, v102
	s_nop 0
	v_add_u32_e32 v104, -1, v103
	v_add_u32_e32 v106, 1, v103
	v_fma_f32 v107, -v104, v103, v102
	v_fma_f32 v108, -v106, v103, v102
	v_cmp_ge_f32_e64 s[76:77], 0, v107
	s_nop 1
	v_cndmask_b32_e64 v103, v103, v104, s[76:77]
	v_cmp_lt_f32_e64 s[76:77], 0, v108
	s_nop 1
	v_cndmask_b32_e64 v103, v103, v106, s[76:77]
	v_mul_f32_e32 v104, 0x37800000, v103
	v_cndmask_b32_e32 v103, v103, v104, vcc
	v_cmp_class_f32_e32 vcc, v102, v3
	s_nop 1
	v_cndmask_b32_e32 v102, v103, v102, vcc
	v_div_scale_f32 v103, s[76:77], v102, v102, 1.0
	v_rcp_f32_e32 v104, v103
	v_div_scale_f32 v106, vcc, 1.0, v102, 1.0
	v_fma_f32 v107, -v103, v104, 1.0
	v_fmac_f32_e32 v104, v107, v104
	v_mul_f32_e32 v107, v106, v104
	v_fma_f32 v108, -v103, v107, v106
	v_fmac_f32_e32 v107, v108, v104
	v_fma_f32 v103, -v103, v107, v106
	v_div_fmas_f32 v103, v103, v104, v107
	v_div_fixup_f32 v110, v103, v102, 1.0
	v_mul_f32_e32 v110, 0.5, v110
	v_pk_mul_f32 v[112:113], v[112:113], v[110:111] op_sel_hi:[1,0]
	v_pk_mul_f32 v[114:115], v[114:115], v[110:111] op_sel_hi:[1,0]
	v_pk_mul_f32 v[116:117], v[116:117], v[110:111] op_sel_hi:[1,0]
	v_pk_mul_f32 v[118:119], v[118:119], v[110:111] op_sel_hi:[1,0]
	v_pk_mul_f32 v[120:121], v[120:121], v[110:111] op_sel_hi:[1,0]
	v_pk_mul_f32 v[122:123], v[122:123], v[110:111] op_sel_hi:[1,0]
	v_pk_mul_f32 v[124:125], v[124:125], v[110:111] op_sel_hi:[1,0]
	v_pk_mul_f32 v[100:101], v[100:101], v[110:111] op_sel_hi:[1,0]
	v_pk_mul_f32 v[112:113], v[176:177], v[112:113]
	v_pk_mul_f32 v[114:115], v[178:179], v[114:115]
	v_pk_mul_f32 v[116:117], v[180:181], v[116:117]
	v_pk_mul_f32 v[118:119], v[182:183], v[118:119]
	v_pk_mul_f32 v[120:121], v[184:185], v[120:121]
	v_pk_mul_f32 v[122:123], v[186:187], v[122:123]
	v_pk_mul_f32 v[124:125], v[188:189], v[124:125]
	v_pk_mul_f32 v[100:101], v[190:191], v[100:101]
	v_pk_fma_f32 v[4:5], v[160:161], v[112:113], v[4:5]
	v_pk_fma_f32 v[6:7], v[162:163], v[114:115], v[6:7]
	v_pk_fma_f32 v[8:9], v[164:165], v[116:117], v[8:9]
	v_pk_fma_f32 v[10:11], v[166:167], v[118:119], v[10:11]
	v_pk_fma_f32 v[12:13], v[168:169], v[120:121], v[12:13]
	v_pk_fma_f32 v[14:15], v[170:171], v[122:123], v[14:15]
	v_pk_fma_f32 v[16:17], v[172:173], v[124:125], v[16:17]
	v_pk_fma_f32 v[18:19], v[174:175], v[100:101], v[18:19]
	s_lshl_b32 s60, s55, 12
	s_add_u32 s72, s84, s60
	s_addc_u32 s73, s85, 0
	global_store_dwordx4 v0, v[4:7], s[72:73] sc1
	global_store_dwordx4 v0, v[8:11], s[72:73] offset:1024 sc1
	global_store_dwordx4 v0, v[12:15], s[72:73] offset:2048 sc1
	global_store_dwordx4 v0, v[16:19], s[72:73] offset:3072 sc1
	v_pk_mul_f32 v[102:103], v[4:5], v[4:5]
	v_pk_mul_f32 v[106:107], v[6:7], v[6:7]
	v_pk_fma_f32 v[102:103], v[8:9], v[8:9], v[102:103]
	v_pk_fma_f32 v[106:107], v[10:11], v[10:11], v[106:107]
	v_pk_fma_f32 v[102:103], v[12:13], v[12:13], v[102:103]
	v_pk_fma_f32 v[106:107], v[14:15], v[14:15], v[106:107]
	v_pk_fma_f32 v[102:103], v[16:17], v[16:17], v[102:103]
	v_pk_fma_f32 v[106:107], v[18:19], v[18:19], v[106:107]
	s_nop 0
	v_pk_add_f32 v[102:103], v[102:103], v[106:107]
	s_nop 0
	v_add_f32_e32 v102, v102, v103
	s_nop 1
	v_add_f32_dpp v102, v102, v102 quad_perm:[1,0,3,2] row_mask:0xf bank_mask:0xf
	s_nop 1
	v_add_f32_dpp v102, v102, v102 quad_perm:[2,3,0,1] row_mask:0xf bank_mask:0xf
	s_nop 1
	v_add_f32_dpp v102, v102, v102 row_half_mirror row_mask:0xf bank_mask:0xf
	s_nop 1
	v_add_f32_dpp v102, v102, v102 row_mirror row_mask:0xf bank_mask:0xf
	s_nop 1
	v_add_f32_dpp v102, v102, v102 row_bcast:15 row_mask:0xa bank_mask:0xf
	s_nop 1
	v_add_f32_dpp v102, v102, v102 row_bcast:31 row_mask:0xc bank_mask:0xf
	s_nop 1
	v_readlane_b32 s74, v102, 63
	s_nop 2
	v_mov_b32_e32 v102, s74
	v_fmamk_f32 v102, v102, 0x3a800000, v2
; __device__ __forceinline__ unsigned pk_bf16(float lo, float hi) { const f32x2 v = {lo, hi}; const bf16x2_t b = __builtin_convertvector(v, bf16x2_t); return __builtin_bit_cast(unsigned, b); }
; template <bool HAS_F, bool HAS_H>
; __device__ __forceinline__ void phase_rows(const Params& p, int sp, int sn, float resw, bool from_input, bool write_x = true) {
;     ...
;     for (int row = gw; row < T; row += NGW) {
;         const int b = row_batch(row);
;         const float* xin = !from_input ? p.out + (size_t)row * D : (row < TP ? p.in[0] + (size_t)row * D : p.in[1] + (size_t)(row - TP) * D);
;         f32x4 v[4];
; #pragma unroll
;         for (int j = 0; j < 4; ++j) v[j] = *(const f32x4*)(xin + 4 * lane + 256 * j);
;     ...
;             const float* sh = mod + b * 9216 + sn * 3072; const float* scl = sh + 1024; const float* gq = p.in[6] + sn * D;
; #pragma unroll
;             for (int j = 0; j < 4; ++j) { const f32x4 a = *(const f32x4*)(sh + 4 * lane + 256 * j), s = *(const f32x4*)(scl + 4 * lane + 256 * j), q = *(const f32x4*)(gq + 4 * lane + 256 * j);
;                 const f32x4 h = (v[j] * rs * q) * (s + 1.0f) + a;
;                 u32x2 w; w.x = pk_bf16(h.x, h.y); w.y = pk_bf16(h.z, h.w);
;                 *(u32x2*)(H + (size_t)row * D + 4 * lane + 256 * j) = w; }
	v_mul_f32_e32 v103, 0x4f800000, v102
	v_cmp_gt_f32_e32 vcc, 0xf800000, v102
	s_nop 1
	v_cndmask_b32_e32 v102, v102, v103, vcc
	v_sqrt_f32_e32 v103, v102
	s_nop 0
	v_add_u32_e32 v104, -1, v103
	v_add_u32_e32 v106, 1, v103
	v_fma_f32 v107, -v104, v103, v102
	v_fma_f32 v108, -v106, v103, v102
	v_cmp_ge_f32_e64 s[76:77], 0, v107
	s_nop 1
	v_cndmask_b32_e64 v103, v103, v104, s[76:77]
	v_cmp_lt_f32_e64 s[76:77], 0, v108
	s_nop 1
	v_cndmask_b32_e64 v103, v103, v106, s[76:77]
	v_mul_f32_e32 v104, 0x37800000, v103
	v_cndmask_b32_e32 v103, v103, v104, vcc
	v_cmp_class_f32_e32 vcc, v102, v3
	s_nop 1
	v_cndmask_b32_e32 v102, v103, v102, vcc
	v_div_scale_f32 v103, s[76:77], v102, v102, 1.0
	v_rcp_f32_e32 v104, v103
	v_div_scale_f32 v106, vcc, 1.0, v102, 1.0
	v_fma_f32 v107, -v103, v104, 1.0
	v_fmac_f32_e32 v104, v107, v104
	v_mul_f32_e32 v107, v106, v104
	v_fma_f32 v108, -v103, v107, v106
	v_fmac_f32_e32 v107, v108, v104
	v_fma_f32 v103, -v103, v107, v106
	v_div_fmas_f32 v103, v103, v104, v107
	v_div_fixup_f32 v110, v103, v102, 1.0
	s_lshl_b32 s60, s55, 11
	s_add_u32 s70, s78, s60
	s_addc_u32 s71, s79, 0
	v_pk_mul_f32 v[112:113], v[4:5], v[110:111] op_sel_hi:[1,0]
	v_pk_mul_f32 v[114:115], v[6:7], v[110:111] op_sel_hi:[1,0]
	v_pk_mul_f32 v[116:117], v[8:9], v[110:111] op_sel_hi:[1,0]
	v_pk_mul_f32 v[118:119], v[10:11], v[110:111] op_sel_hi:[1,0]
	v_pk_mul_f32 v[120:121], v[12:13], v[110:111] op_sel_hi:[1,0]
	v_pk_mul_f32 v[122:123], v[14:15], v[110:111] op_sel_hi:[1,0]
	v_pk_mul_f32 v[124:125], v[16:17], v[110:111] op_sel_hi:[1,0]
	v_pk_mul_f32 v[100:101], v[18:19], v[110:111] op_sel_hi:[1,0]
	v_pk_mul_f32 v[112:113], v[192:193], v[112:113]
	v_pk_mul_f32 v[114:115], v[194:195], v[114:115]
	v_pk_mul_f32 v[116:117], v[196:197], v[116:117]
	v_pk_mul_f32 v[118:119], v[198:199], v[118:119]
	v_pk_mul_f32 v[120:121], v[200:201], v[120:121]
	v_pk_mul_f32 v[122:123], v[202:203], v[122:123]
	v_pk_mul_f32 v[124:125], v[204:205], v[124:125]
	v_pk_mul_f32 v[100:101], v[206:207], v[100:101]
	v_pk_fma_f32 v[112:113], v[208:209], v[112:113], v[224:225]
	v_pk_fma_f32 v[114:115], v[210:211], v[114:115], v[226:227]
	v_pk_fma_f32 v[116:117], v[212:213], v[116:117], v[228:229]
	v_pk_fma_f32 v[118:119], v[214:215], v[118:119], v[230:231]
	v_pk_fma_f32 v[120:121], v[216:217], v[120:121], v[232:233]
	v_pk_fma_f32 v[122:123], v[218:219], v[122:123], v[234:235]
	v_pk_fma_f32 v[124:125], v[220:221], v[124:125], v[236:237]
	v_pk_fma_f32 v[100:101], v[222:223], v[100:101], v[238:239]
	v_cvt_pk_bf16_f32 v240, v112, v113
	v_cvt_pk_bf16_f32 v241, v114, v115
	v_cvt_pk_bf16_f32 v242, v116, v117
	v_cvt_pk_bf16_f32 v243, v118, v119
	v_cvt_pk_bf16_f32 v244, v120, v121
	v_cvt_pk_bf16_f32 v245, v122, v123
	v_cvt_pk_bf16_f32 v246, v124, v125
	v_cvt_pk_bf16_f32 v247, v100, v101
	global_store_dwordx2 v1, v[240:241], s[70:71]
	global_store_dwordx2 v1, v[242:243], s[70:71] offset:512
	global_store_dwordx2 v1, v[244:245], s[70:71] offset:1024
	global_store_dwordx2 v1, v[246:247], s[70:71] offset:1536
	s_add_u32 s55, s55, 8
	s_add_u32 s57, s55, 8
	s_min_u32 s57, s57, s54
	s_cmp_lt_u32 s57, 0x8000
	s_cselect_b32 s64, s8, s10
	s_cselect_b32 s65, s9, s11
	s_cselect_b32 s60, 0, 0x8000
	s_sub_u32 s60, s57, s60
	s_lshl_b32 s60, s60, 12
	s_add_u32 s64, s64, s60
	s_addc_u32 s65, s65, 0
	s_lshl_b32 s60, s57, 11
	s_add_u32 s66, s82, s60
	s_addc_u32 s67, s83, 0
	global_load_dwordx4 v[4:7], v0, s[64:65] nt
	global_load_dwordx4 v[8:11], v0, s[64:65] offset:1024 nt
	global_load_dwordx4 v[12:15], v0, s[64:65] offset:2048 nt
	global_load_dwordx4 v[16:19], v0, s[64:65] offset:3072 nt
	global_load_dwordx2 v[20:21], v1, s[66:67] nt
	global_load_dwordx2 v[22:23], v1, s[66:67] offset:512 nt
	global_load_dwordx2 v[24:25], v1, s[66:67] offset:1024 nt
	global_load_dwordx2 v[26:27], v1, s[66:67] offset:1536 nt
	s_lshr_b32 s60, s55, 11
	s_sub_u32 s61, s55, 0x8000
	s_lshr_b32 s61, s61, 12
	s_add_u32 s61, s61, 16
	s_cmp_lt_u32 s55, 0x8000
	s_cselect_b32 s63, s60, s61
	s_cmp_eq_u32 s63, s56
	s_cbranch_scc1 .Lrp4_pk7
	s_mov_b32 s56, s63
	s_mul_i32 s60, s56, 0x9000
	s_add_u32 s60, s60, 0x3182000
	s_add_u32 s0, s92, s60
	s_addc_u32 s1, s93, 0
	global_load_dwordx4 v[160:163], v0, s[0:1]
	global_load_dwordx4 v[164:167], v0, s[0:1] offset:1024
	global_load_dwordx4 v[168:171], v0, s[0:1] offset:2048
	global_load_dwordx4 v[172:175], v0, s[0:1] offset:3072
	s_add_u32 s0, s22, 0x0
	s_addc_u32 s1, s23, 0
	global_load_dwordx4 v[176:179], v0, s[0:1]
	global_load_dwordx4 v[180:183], v0, s[0:1] offset:1024
	global_load_dwordx4 v[184:187], v0, s[0:1] offset:2048
	global_load_dwordx4 v[188:191], v0, s[0:1] offset:3072
	s_add_u32 s0, s20, 0x1000
	s_addc_u32 s1, s21, 0
	global_load_dwordx4 v[192:195], v0, s[0:1]
	global_load_dwordx4 v[196:199], v0, s[0:1] offset:1024
	global_load_dwordx4 v[200:203], v0, s[0:1] offset:2048
	global_load_dwordx4 v[204:207], v0, s[0:1] offset:3072
	s_mul_i32 s60, s56, 0x9000
	s_add_u32 s60, s60, 0x3184000
	s_add_u32 s0, s92, s60
	s_addc_u32 s1, s93, 0
	global_load_dwordx4 v[208:211], v0, s[0:1]
	global_load_dwordx4 v[212:215], v0, s[0:1] offset:1024
	global_load_dwordx4 v[216:219], v0, s[0:1] offset:2048
	global_load_dwordx4 v[220:223], v0, s[0:1] offset:3072
	s_mul_i32 s60, s56, 0x9000
	s_add_u32 s60, s60, 0x3183000
	s_add_u32 s0, s92, s60
	s_addc_u32 s1, s93, 0
	global_load_dwordx4 v[224:227], v0, s[0:1]
	global_load_dwordx4 v[228:231], v0, s[0:1] offset:1024
	global_load_dwordx4 v[232:235], v0, s[0:1] offset:2048
	global_load_dwordx4 v[236:239], v0, s[0:1] offset:3072
	s_waitcnt vmcnt(0)
	v_pk_add_f32 v[208:209], v[208:209], 1.0 op_sel_hi:[1,0]
	v_pk_add_f32 v[210:211], v[210:211], 1.0 op_sel_hi:[1,0]
	v_pk_add_f32 v[212:213], v[212:213], 1.0 op_sel_hi:[1,0]
	v_pk_add_f32 v[214:215], v[214:215], 1.0 op_sel_hi:[1,0]
	v_pk_add_f32 v[216:217], v[216:217], 1.0 op_sel_hi:[1,0]
	v_pk_add_f32 v[218:219], v[218:219], 1.0 op_sel_hi:[1,0]
	v_pk_add_f32 v[220:221], v[220:221], 1.0 op_sel_hi:[1,0]
	v_pk_add_f32 v[222:223], v[222:223], 1.0 op_sel_hi:[1,0]
; __device__ __forceinline__ float lo_bf(unsigned w) { return __uint_as_float(w << 16); }
; __device__ __forceinline__ float hi_bf(unsigned w) { return __uint_as_float(w & 0xffff0000u); }
; template <bool HAS_F, bool HAS_H>
; __device__ __forceinline__ void phase_rows(const Params& p, int sp, int sn, float resw, bool from_input, bool write_x = true) {
;     ...
;         if (HAS_F) {
;             f32x4 f[4]; float ss = 0.f;
; #pragma unroll
;             for (int j = 0; j < 4; ++j) { const u32x2 w = *(const u32x2*)(F + (size_t)row * D + 4 * lane + 256 * j);
;                 f[j] = (f32x4){lo_bf(w.x), hi_bf(w.x), lo_bf(w.y), hi_bf(w.y)}; ss += (f[j].x * f[j].x + f[j].y * f[j].y) + (f[j].z * f[j].z + f[j].w * f[j].w); }
;             const float rs = 1.0f / sqrtf(wave_sum(ss) * (1.0f / D) + EPS) * resw;
;             const float* gate = mod + b * 9216 + sp * 3072 + 2048; const float* gp = p.in[7] + sp * D;
; #pragma unroll
;             for (int j = 0; j < 4; ++j) { const f32x4 g = *(const f32x4*)(gate + 4 * lane + 256 * j), q = *(const f32x4*)(gp + 4 * lane + 256 * j);
;                 v[j] = v[j] + g * (f[j] * rs * q);
;                 if (write_x) *(f32x4*)(p.out + (size_t)row * D + 4 * lane + 256 * j) = v[j]; }
.Lrp4_pk7:
	s_waitcnt vmcnt(16)
	v_lshlrev_b32_e32 v112, 16, v52
	v_and_b32_e32 v113, 0xffff0000, v52
	v_lshlrev_b32_e32 v114, 16, v53
	v_and_b32_e32 v115, 0xffff0000, v53
	v_lshlrev_b32_e32 v116, 16, v54
	v_and_b32_e32 v117, 0xffff0000, v54
	v_lshlrev_b32_e32 v118, 16, v55
	v_and_b32_e32 v119, 0xffff0000, v55
	v_lshlrev_b32_e32 v120, 16, v56
	v_and_b32_e32 v121, 0xffff0000, v56
	v_lshlrev_b32_e32 v122, 16, v57
	v_and_b32_e32 v123, 0xffff0000, v57
	v_lshlrev_b32_e32 v124, 16, v58
	v_and_b32_e32 v125, 0xffff0000, v58
	v_lshlrev_b32_e32 v100, 16, v59
	v_and_b32_e32 v101, 0xffff0000, v59
	v_pk_mul_f32 v[102:103], v[112:113], v[112:113]
	v_pk_mul_f32 v[106:107], v[114:115], v[114:115]
	v_pk_fma_f32 v[102:103], v[116:117], v[116:117], v[102:103]
	v_pk_fma_f32 v[106:107], v[118:119], v[118:119], v[106:107]
	v_pk_fma_f32 v[102:103], v[120:121], v[120:121], v[102:103]
	v_pk_fma_f32 v[106:107], v[122:123], v[122:123], v[106:107]
	v_pk_fma_f32 v[102:103], v[124:125], v[124:125], v[102:103]
	v_pk_fma_f32 v[106:107], v[100:101], v[100:101], v[106:107]
	s_nop 0
	v_pk_add_f32 v[102:103], v[102:103], v[106:107]
	s_nop 0
	v_add_f32_e32 v102, v102, v103
	s_nop 1
	v_add_f32_dpp v102, v102, v102 quad_perm:[1,0,3,2] row_mask:0xf bank_mask:0xf
	s_nop 1
	v_add_f32_dpp v102, v102, v102 quad_perm:[2,3,0,1] row_mask:0xf bank_mask:0xf
	s_nop 1
	v_add_f32_dpp v102, v102, v102 row_half_mirror row_mask:0xf bank_mask:0xf
	s_nop 1
	v_add_f32_dpp v102, v102, v102 row_mirror row_mask:0xf bank_mask:0xf
	s_nop 1
	v_add_f32_dpp v102, v102, v102 row_bcast:15 row_mask:0xa bank_mask:0xf
	s_nop 1
	v_add_f32_dpp v102, v102, v102 row_bcast:31 row_mask:0xc bank_mask:0xf
	s_nop 1
	v_readlane_b32 s74, v102, 63
	s_nop 2
	v_mov_b32_e32 v102, s74
	v_fmamk_f32 v102, v102, 0x3a800000, v2
	v_mul_f32_e32 v103, 0x4f800000, v102
	v_cmp_gt_f32_e32 vcc, 0xf800000, v102
	s_nop 1
	v_cndmask_b32_e32 v102, v102, v103, vcc
	v_sqrt_f32_e32 v103, v102
	s_nop 0
	v_add_u32_e32 v104, -1, v103
	v_add_u32_e32 v106, 1, v103
	v_fma_f32 v107, -v104, v103, v102
	v_fma_f32 v108, -v106, v103, v102
	v_cmp_ge_f32_e64 s[76:77], 0, v107
	s_nop 1
	v_cndmask_b32_e64 v103, v103, v104, s[76:77]
	v_cmp_lt_f32_e64 s[76:77], 0, v108
	s_nop 1
	v_cndmask_b32_e64 v103, v103, v106, s[76:77]
	v_mul_f32_e32 v104, 0x37800000, v103
	v_cndmask_b32_e32 v103, v103, v104, vcc
	v_cmp_class_f32_e32 vcc, v102, v3
	s_nop 1
	v_cndmask_b32_e32 v102, v103, v102, vcc
	v_div_scale_f32 v103, s[76:77], v102, v102, 1.0
	v_rcp_f32_e32 v104, v103
	v_div_scale_f32 v106, vcc, 1.0, v102, 1.0
	v_fma_f32 v107, -v103, v104, 1.0
	v_fmac_f32_e32 v104, v107, v104
	v_mul_f32_e32 v107, v106, v104
	v_fma_f32 v108, -v103, v107, v106
	v_fmac_f32_e32 v107, v108, v104
	v_fma_f32 v103, -v103, v107, v106
	v_div_fmas_f32 v103, v103, v104, v107
	v_div_fixup_f32 v110, v103, v102, 1.0
	v_mul_f32_e32 v110, 0.5, v110
	v_pk_mul_f32 v[112:113], v[112:113], v[110:111] op_sel_hi:[1,0]
	v_pk_mul_f32 v[114:115], v[114:115], v[110:111] op_sel_hi:[1,0]
	v_pk_mul_f32 v[116:117], v[116:117], v[110:111] op_sel_hi:[1,0]
	v_pk_mul_f32 v[118:119], v[118:119], v[110:111] op_sel_hi:[1,0]
	v_pk_mul_f32 v[120:121], v[120:121], v[110:111] op_sel_hi:[1,0]
	v_pk_mul_f32 v[122:123], v[122:123], v[110:111] op_sel_hi:[1,0]
	v_pk_mul_f32 v[124:125], v[124:125], v[110:111] op_sel_hi:[1,0]
	v_pk_mul_f32 v[100:101], v[100:101], v[110:111] op_sel_hi:[1,0]
	v_pk_mul_f32 v[112:113], v[176:177], v[112:113]
	v_pk_mul_f32 v[114:115], v[178:179], v[114:115]
	v_pk_mul_f32 v[116:117], v[180:181], v[116:117]
	v_pk_mul_f32 v[118:119], v[182:183], v[118:119]
	v_pk_mul_f32 v[120:121], v[184:185], v[120:121]
	v_pk_mul_f32 v[122:123], v[186:187], v[122:123]
	v_pk_mul_f32 v[124:125], v[188:189], v[124:125]
	v_pk_mul_f32 v[100:101], v[190:191], v[100:101]
	v_pk_fma_f32 v[36:37], v[160:161], v[112:113], v[36:37]
	v_pk_fma_f32 v[38:39], v[162:163], v[114:115], v[38:39]
	v_pk_fma_f32 v[40:41], v[164:165], v[116:117], v[40:41]
	v_pk_fma_f32 v[42:43], v[166:167], v[118:119], v[42:43]
	v_pk_fma_f32 v[44:45], v[168:169], v[120:121], v[44:45]
	v_pk_fma_f32 v[46:47], v[170:171], v[122:123], v[46:47]
	v_pk_fma_f32 v[48:49], v[172:173], v[124:125], v[48:49]
	v_pk_fma_f32 v[50:51], v[174:175], v[100:101], v[50:51]
	s_lshl_b32 s60, s55, 12
	s_add_u32 s72, s84, s60
	s_addc_u32 s73, s85, 0
	global_store_dwordx4 v0, v[36:39], s[72:73] sc1
	global_store_dwordx4 v0, v[40:43], s[72:73] offset:1024 sc1
; __device__ __forceinline__ unsigned pk_bf16(float lo, float hi) { const f32x2 v = {lo, hi}; const bf16x2_t b = __builtin_convertvector(v, bf16x2_t); return __builtin_bit_cast(unsigned, b); }
; template <bool HAS_F, bool HAS_H>
; __device__ __forceinline__ void phase_rows(const Params& p, int sp, int sn, float resw, bool from_input, bool write_x = true) {
;     ...
;         if (HAS_H) {
;             float ss = 0.f;
; #pragma unroll
;             for (int j = 0; j < 4; ++j) ss += (v[j].x * v[j].x + v[j].y * v[j].y) + (v[j].z * v[j].z + v[j].w * v[j].w);
;             const float rs = 1.0f / sqrtf(wave_sum(ss) * (1.0f / D) + EPS);
;             const float* sh = mod + b * 9216 + sn * 3072; const float* scl = sh + 1024; const float* gq = p.in[6] + sn * D;
; #pragma unroll
;             for (int j = 0; j < 4; ++j) { const f32x4 a = *(const f32x4*)(sh + 4 * lane + 256 * j), s = *(const f32x4*)(scl + 4 * lane + 256 * j), q = *(const f32x4*)(gq + 4 * lane + 256 * j);
;                 const f32x4 h = (v[j] * rs * q) * (s + 1.0f) + a;
;                 u32x2 w; w.x = pk_bf16(h.x, h.y); w.y = pk_bf16(h.z, h.w);
;                 *(u32x2*)(H + (size_t)row * D + 4 * lane + 256 * j) = w; }
;         }
;     }
	global_store_dwordx4 v0, v[44:47], s[72:73] offset:2048 sc1
	global_store_dwordx4 v0, v[48:51], s[72:73] offset:3072 sc1
	v_pk_mul_f32 v[102:103], v[36:37], v[36:37]
	v_pk_mul_f32 v[106:107], v[38:39], v[38:39]
	v_pk_fma_f32 v[102:103], v[40:41], v[40:41], v[102:103]
	v_pk_fma_f32 v[106:107], v[42:43], v[42:43], v[106:107]
	v_pk_fma_f32 v[102:103], v[44:45], v[44:45], v[102:103]
	v_pk_fma_f32 v[106:107], v[46:47], v[46:47], v[106:107]
	v_pk_fma_f32 v[102:103], v[48:49], v[48:49], v[102:103]
	v_pk_fma_f32 v[106:107], v[50:51], v[50:51], v[106:107]
	s_nop 0
	v_pk_add_f32 v[102:103], v[102:103], v[106:107]
	s_nop 0
	v_add_f32_e32 v102, v102, v103
	s_nop 1
	v_add_f32_dpp v102, v102, v102 quad_perm:[1,0,3,2] row_mask:0xf bank_mask:0xf
	s_nop 1
	v_add_f32_dpp v102, v102, v102 quad_perm:[2,3,0,1] row_mask:0xf bank_mask:0xf
	s_nop 1
	v_add_f32_dpp v102, v102, v102 row_half_mirror row_mask:0xf bank_mask:0xf
	s_nop 1
	v_add_f32_dpp v102, v102, v102 row_mirror row_mask:0xf bank_mask:0xf
	s_nop 1
	v_add_f32_dpp v102, v102, v102 row_bcast:15 row_mask:0xa bank_mask:0xf
	s_nop 1
	v_add_f32_dpp v102, v102, v102 row_bcast:31 row_mask:0xc bank_mask:0xf
	s_nop 1
	v_readlane_b32 s74, v102, 63
	s_nop 2
	v_mov_b32_e32 v102, s74
	v_fmamk_f32 v102, v102, 0x3a800000, v2
	v_mul_f32_e32 v103, 0x4f800000, v102
	v_cmp_gt_f32_e32 vcc, 0xf800000, v102
	s_nop 1
	v_cndmask_b32_e32 v102, v102, v103, vcc
	v_sqrt_f32_e32 v103, v102
	s_nop 0
	v_add_u32_e32 v104, -1, v103
	v_add_u32_e32 v106, 1, v103
	v_fma_f32 v107, -v104, v103, v102
	v_fma_f32 v108, -v106, v103, v102
	v_cmp_ge_f32_e64 s[76:77], 0, v107
	s_nop 1
	v_cndmask_b32_e64 v103, v103, v104, s[76:77]
	v_cmp_lt_f32_e64 s[76:77], 0, v108
	s_nop 1
	v_cndmask_b32_e64 v103, v103, v106, s[76:77]
	v_mul_f32_e32 v104, 0x37800000, v103
	v_cndmask_b32_e32 v103, v103, v104, vcc
	v_cmp_class_f32_e32 vcc, v102, v3
	s_nop 1
	v_cndmask_b32_e32 v102, v103, v102, vcc
	v_div_scale_f32 v103, s[76:77], v102, v102, 1.0
	v_rcp_f32_e32 v104, v103
	v_div_scale_f32 v106, vcc, 1.0, v102, 1.0
	v_fma_f32 v107, -v103, v104, 1.0
	v_fmac_f32_e32 v104, v107, v104
	v_mul_f32_e32 v107, v106, v104
	v_fma_f32 v108, -v103, v107, v106
	v_fmac_f32_e32 v107, v108, v104
	v_fma_f32 v103, -v103, v107, v106
	v_div_fmas_f32 v103, v103, v104, v107
	v_div_fixup_f32 v110, v103, v102, 1.0
	s_lshl_b32 s60, s55, 11
	s_add_u32 s70, s78, s60
	s_addc_u32 s71, s79, 0
	v_pk_mul_f32 v[112:113], v[36:37], v[110:111] op_sel_hi:[1,0]
	v_pk_mul_f32 v[114:115], v[38:39], v[110:111] op_sel_hi:[1,0]
	v_pk_mul_f32 v[116:117], v[40:41], v[110:111] op_sel_hi:[1,0]
	v_pk_mul_f32 v[118:119], v[42:43], v[110:111] op_sel_hi:[1,0]
	v_pk_mul_f32 v[120:121], v[44:45], v[110:111] op_sel_hi:[1,0]
	v_pk_mul_f32 v[122:123], v[46:47], v[110:111] op_sel_hi:[1,0]
	v_pk_mul_f32 v[124:125], v[48:49], v[110:111] op_sel_hi:[1,0]
	v_pk_mul_f32 v[100:101], v[50:51], v[110:111] op_sel_hi:[1,0]
	v_pk_mul_f32 v[112:113], v[192:193], v[112:113]
	v_pk_mul_f32 v[114:115], v[194:195], v[114:115]
	v_pk_mul_f32 v[116:117], v[196:197], v[116:117]
	v_pk_mul_f32 v[118:119], v[198:199], v[118:119]
	v_pk_mul_f32 v[120:121], v[200:201], v[120:121]
	v_pk_mul_f32 v[122:123], v[202:203], v[122:123]
	v_pk_mul_f32 v[124:125], v[204:205], v[124:125]
	v_pk_mul_f32 v[100:101], v[206:207], v[100:101]
	v_pk_fma_f32 v[112:113], v[208:209], v[112:113], v[224:225]
	v_pk_fma_f32 v[114:115], v[210:211], v[114:115], v[226:227]
	v_pk_fma_f32 v[116:117], v[212:213], v[116:117], v[228:229]
	v_pk_fma_f32 v[118:119], v[214:215], v[118:119], v[230:231]
	v_pk_fma_f32 v[120:121], v[216:217], v[120:121], v[232:233]
	v_pk_fma_f32 v[122:123], v[218:219], v[122:123], v[234:235]
	v_pk_fma_f32 v[124:125], v[220:221], v[124:125], v[236:237]
	v_pk_fma_f32 v[100:101], v[222:223], v[100:101], v[238:239]
	v_cvt_pk_bf16_f32 v240, v112, v113
	v_cvt_pk_bf16_f32 v241, v114, v115
	v_cvt_pk_bf16_f32 v242, v116, v117
	v_cvt_pk_bf16_f32 v243, v118, v119
	v_cvt_pk_bf16_f32 v244, v120, v121
	v_cvt_pk_bf16_f32 v245, v122, v123
	v_cvt_pk_bf16_f32 v246, v124, v125
	v_cvt_pk_bf16_f32 v247, v100, v101
	global_store_dwordx2 v1, v[240:241], s[70:71]
	global_store_dwordx2 v1, v[242:243], s[70:71] offset:512
	global_store_dwordx2 v1, v[244:245], s[70:71] offset:1024
	global_store_dwordx2 v1, v[246:247], s[70:71] offset:1536
	s_add_u32 s55, s55, 8
	s_cmp_le_u32 s55, s54
	s_cbranch_scc1 .Lrp4_loop3
	s_add_u32 s51, s51, s52
	s_branch .Lrp4_chunk1

; __device__ __forceinline__ float lo_bf(unsigned w) { return __uint_as_float(w << 16); }
; __device__ __forceinline__ float hi_bf(unsigned w) { return __uint_as_float(w & 0xffff0000u); }
; template <bool HAS_F, bool HAS_H>
; __device__ __forceinline__ void phase_rows(const Params& p, int sp, int sn, float resw, bool from_input, bool write_x = true) {
;     ...
;     for (int row = gw; row < T; row += NGW) {
;         const int b = row_batch(row);
;         const float* xin = !from_input ? p.out + (size_t)row * D : (row < TP ? p.in[0] + (size_t)row * D : p.in[1] + (size_t)(row - TP) * D);
;         f32x4 v[4];
; #pragma unroll
;         for (int j = 0; j < 4; ++j) v[j] = *(const f32x4*)(xin + 4 * lane + 256 * j);
;         if (HAS_F) {
;             f32x4 f[4]; float ss = 0.f;
; #pragma unroll
;             for (int j = 0; j < 4; ++j) { const u32x2 w = *(const u32x2*)(F + (size_t)row * D + 4 * lane + 256 * j);
;                 f[j] = (f32x4){lo_bf(w.x), hi_bf(w.x), lo_bf(w.y), hi_bf(w.y)}; ss += (f[j].x * f[j].x + f[j].y * f[j].y) + (f[j].z * f[j].z + f[j].w * f[j].w); }
;             const float rs = 1.0f / sqrtf(wave_sum(ss) * (1.0f / D) + EPS) * resw;
;             const float* gate = mod + b * 9216 + sp * 3072 + 2048; const float* gp = p.in[7] + sp * D;
; #pragma unroll
;             for (int j = 0; j < 4; ++j) { const f32x4 g = *(const f32x4*)(gate + 4 * lane + 256 * j), q = *(const f32x4*)(gp + 4 * lane + 256 * j);
.Lrp12_chunk1:
	s_mul_i32 s53, s51, 384
	s_cmp_ge_u32 s53, 0x18000
	s_cbranch_scc1 .Lrp12_done2
	s_add_u32 s53, s53, s50
	s_add_u32 s54, s53, 376
	s_mov_b32 s56, -1
	s_mov_b32 s55, s53
	s_add_u32 s57, s53, 0
	s_lshl_b32 s60, s57, 12
	s_add_u32 s64, s84, s60
	s_addc_u32 s65, s85, 0
	s_lshl_b32 s60, s57, 11
	s_add_u32 s66, s82, s60
	s_addc_u32 s67, s83, 0
	global_load_dwordx4 v[4:7], v0, s[64:65] nt
	global_load_dwordx4 v[8:11], v0, s[64:65] offset:1024 nt
	global_load_dwordx4 v[12:15], v0, s[64:65] offset:2048 nt
	global_load_dwordx4 v[16:19], v0, s[64:65] offset:3072 nt
	global_load_dwordx2 v[20:21], v1, s[66:67] nt
	global_load_dwordx2 v[22:23], v1, s[66:67] offset:512 nt
	global_load_dwordx2 v[24:25], v1, s[66:67] offset:1024 nt
	global_load_dwordx2 v[26:27], v1, s[66:67] offset:1536 nt
	s_add_u32 s57, s55, 8
	s_min_u32 s57, s57, s54
	s_lshl_b32 s60, s57, 12
	s_add_u32 s64, s84, s60
	s_addc_u32 s65, s85, 0
	s_lshl_b32 s60, s57, 11
	s_add_u32 s66, s82, s60
	s_addc_u32 s67, s83, 0
	global_load_dwordx4 v[36:39], v0, s[64:65] nt
	global_load_dwordx4 v[40:43], v0, s[64:65] offset:1024 nt
	global_load_dwordx4 v[44:47], v0, s[64:65] offset:2048 nt
	global_load_dwordx4 v[48:51], v0, s[64:65] offset:3072 nt
	global_load_dwordx2 v[52:53], v1, s[66:67] nt
	global_load_dwordx2 v[54:55], v1, s[66:67] offset:512 nt
	global_load_dwordx2 v[56:57], v1, s[66:67] offset:1024 nt
	global_load_dwordx2 v[58:59], v1, s[66:67] offset:1536 nt
	s_lshr_b32 s60, s55, 11
	s_sub_u32 s61, s55, 0x8000
	s_lshr_b32 s61, s61, 12
	s_add_u32 s61, s61, 16
	s_cmp_lt_u32 s55, 0x8000
	s_cselect_b32 s63, s60, s61
	s_cmp_eq_u32 s63, s56
	s_cbranch_scc1 .Lrp12_pk4
	s_mov_b32 s56, s63
	s_mul_i32 s60, s56, 0x9000
	s_add_u32 s60, s60, 0x3185000
	s_add_u32 s0, s92, s60
	s_addc_u32 s1, s93, 0
	global_load_dwordx4 v[160:163], v0, s[0:1]
	global_load_dwordx4 v[164:167], v0, s[0:1] offset:1024
	global_load_dwordx4 v[168:171], v0, s[0:1] offset:2048
	global_load_dwordx4 v[172:175], v0, s[0:1] offset:3072
	s_add_u32 s0, s22, 0x1000
	s_addc_u32 s1, s23, 0
	global_load_dwordx4 v[176:179], v0, s[0:1]
	global_load_dwordx4 v[180:183], v0, s[0:1] offset:1024
	global_load_dwordx4 v[184:187], v0, s[0:1] offset:2048
	global_load_dwordx4 v[188:191], v0, s[0:1] offset:3072
	s_add_u32 s0, s20, 0x2000
	s_addc_u32 s1, s21, 0
	global_load_dwordx4 v[192:195], v0, s[0:1]
	global_load_dwordx4 v[196:199], v0, s[0:1] offset:1024
	global_load_dwordx4 v[200:203], v0, s[0:1] offset:2048
	global_load_dwordx4 v[204:207], v0, s[0:1] offset:3072
	s_mul_i32 s60, s56, 0x9000
	s_add_u32 s60, s60, 0x3187000
	s_add_u32 s0, s92, s60
	s_addc_u32 s1, s93, 0
	global_load_dwordx4 v[208:211], v0, s[0:1]
	global_load_dwordx4 v[212:215], v0, s[0:1] offset:1024
	global_load_dwordx4 v[216:219], v0, s[0:1] offset:2048
	global_load_dwordx4 v[220:223], v0, s[0:1] offset:3072
	s_mul_i32 s60, s56, 0x9000
	s_add_u32 s60, s60, 0x3186000
	s_add_u32 s0, s92, s60
	s_addc_u32 s1, s93, 0
	global_load_dwordx4 v[224:227], v0, s[0:1]
	global_load_dwordx4 v[228:231], v0, s[0:1] offset:1024
	global_load_dwordx4 v[232:235], v0, s[0:1] offset:2048
	global_load_dwordx4 v[236:239], v0, s[0:1] offset:3072
	s_waitcnt vmcnt(0)
	v_pk_add_f32 v[208:209], v[208:209], 1.0 op_sel_hi:[1,0]
	v_pk_add_f32 v[210:211], v[210:211], 1.0 op_sel_hi:[1,0]
	v_pk_add_f32 v[212:213], v[212:213], 1.0 op_sel_hi:[1,0]
	v_pk_add_f32 v[214:215], v[214:215], 1.0 op_sel_hi:[1,0]
	v_pk_add_f32 v[216:217], v[216:217], 1.0 op_sel_hi:[1,0]
	v_pk_add_f32 v[218:219], v[218:219], 1.0 op_sel_hi:[1,0]
	v_pk_add_f32 v[220:221], v[220:221], 1.0 op_sel_hi:[1,0]
	v_pk_add_f32 v[222:223], v[222:223], 1.0 op_sel_hi:[1,0]
.Lrp12_pk4:
	s_waitcnt vmcnt(8)
	v_lshlrev_b32_e32 v112, 16, v20
	v_and_b32_e32 v113, 0xffff0000, v20
	v_lshlrev_b32_e32 v114, 16, v21
	v_and_b32_e32 v115, 0xffff0000, v21
	v_lshlrev_b32_e32 v116, 16, v22
	v_and_b32_e32 v117, 0xffff0000, v22
	v_lshlrev_b32_e32 v118, 16, v23
	v_and_b32_e32 v119, 0xffff0000, v23
	v_lshlrev_b32_e32 v120, 16, v24
	v_and_b32_e32 v121, 0xffff0000, v24
	v_lshlrev_b32_e32 v122, 16, v25
	v_and_b32_e32 v123, 0xffff0000, v25
	v_lshlrev_b32_e32 v124, 16, v26
	v_and_b32_e32 v125, 0xffff0000, v26
	v_lshlrev_b32_e32 v100, 16, v27
	v_and_b32_e32 v101, 0xffff0000, v27
	v_pk_mul_f32 v[102:103], v[112:113], v[112:113]
	v_pk_mul_f32 v[106:107], v[114:115], v[114:115]
	v_pk_fma_f32 v[102:103], v[116:117], v[116:117], v[102:103]
	v_pk_fma_f32 v[106:107], v[118:119], v[118:119], v[106:107]
	v_pk_fma_f32 v[102:103], v[120:121], v[120:121], v[102:103]
	v_pk_fma_f32 v[106:107], v[122:123], v[122:123], v[106:107]
	v_pk_fma_f32 v[102:103], v[124:125], v[124:125], v[102:103]
	v_pk_fma_f32 v[106:107], v[100:101], v[100:101], v[106:107]
	s_nop 0
	v_pk_add_f32 v[102:103], v[102:103], v[106:107]
	s_nop 0
	v_add_f32_e32 v102, v102, v103
	s_nop 1
	v_add_f32_dpp v102, v102, v102 quad_perm:[1,0,3,2] row_mask:0xf bank_mask:0xf
	s_nop 1
	v_add_f32_dpp v102, v102, v102 quad_perm:[2,3,0,1] row_mask:0xf bank_mask:0xf
	s_nop 1
	v_add_f32_dpp v102, v102, v102 row_half_mirror row_mask:0xf bank_mask:0xf
	s_nop 1
	v_add_f32_dpp v102, v102, v102 row_mirror row_mask:0xf bank_mask:0xf
	s_nop 1
	v_add_f32_dpp v102, v102, v102 row_bcast:15 row_mask:0xa bank_mask:0xf
	s_nop 1
	v_add_f32_dpp v102, v102, v102 row_bcast:31 row_mask:0xc bank_mask:0xf
	s_nop 1
	v_readlane_b32 s74, v102, 63
	s_nop 2
	v_mov_b32_e32 v102, s74
	v_fmamk_f32 v102, v102, 0x3a800000, v2
	v_mul_f32_e32 v103, 0x4f800000, v102
	v_cmp_gt_f32_e32 vcc, 0xf800000, v102
	s_nop 1
	v_cndmask_b32_e32 v102, v102, v103, vcc
	v_sqrt_f32_e32 v103, v102
	s_nop 0
	v_add_u32_e32 v104, -1, v103
	v_add_u32_e32 v106, 1, v103
; __device__ __forceinline__ unsigned pk_bf16(float lo, float hi) { const f32x2 v = {lo, hi}; const bf16x2_t b = __builtin_convertvector(v, bf16x2_t); return __builtin_bit_cast(unsigned, b); }
; template <bool HAS_F, bool HAS_H>
; __device__ __forceinline__ void phase_rows(const Params& p, int sp, int sn, float resw, bool from_input, bool write_x = true) {
;     ...
;             const float rs = 1.0f / sqrtf(wave_sum(ss) * (1.0f / D) + EPS) * resw;
;             const float* gate = mod + b * 9216 + sp * 3072 + 2048; const float* gp = p.in[7] + sp * D;
; #pragma unroll
;             for (int j = 0; j < 4; ++j) { const f32x4 g = *(const f32x4*)(gate + 4 * lane + 256 * j), q = *(const f32x4*)(gp + 4 * lane + 256 * j);
;                 v[j] = v[j] + g * (f[j] * rs * q);
;                 if (write_x) *(f32x4*)(p.out + (size_t)row * D + 4 * lane + 256 * j) = v[j]; }
;         }
;         if (HAS_H) {
;             float ss = 0.f;
; #pragma unroll
;             for (int j = 0; j < 4; ++j) ss += (v[j].x * v[j].x + v[j].y * v[j].y) + (v[j].z * v[j].z + v[j].w * v[j].w);
;             const float rs = 1.0f / sqrtf(wave_sum(ss) * (1.0f / D) + EPS);
;             const float* sh = mod + b * 9216 + sn * 3072; const float* scl = sh + 1024; const float* gq = p.in[6] + sn * D;
; #pragma unroll
;             for (int j = 0; j < 4; ++j) { const f32x4 a = *(const f32x4*)(sh + 4 * lane + 256 * j), s = *(const f32x4*)(scl + 4 * lane + 256 * j), q = *(const f32x4*)(gq + 4 * lane + 256 * j);
;                 const f32x4 h = (v[j] * rs * q) * (s + 1.0f) + a;
;                 u32x2 w; w.x = pk_bf16(h.x, h.y); w.y = pk_bf16(h.z, h.w);
;                 *(u32x2*)(H + (size_t)row * D + 4 * lane + 256 * j) = w; }
	v_fma_f32 v107, -v104, v103, v102
	v_fma_f32 v108, -v106, v103, v102
	v_cmp_ge_f32_e64 s[76:77], 0, v107
	s_nop 1
	v_cndmask_b32_e64 v103, v103, v104, s[76:77]
	v_cmp_lt_f32_e64 s[76:77], 0, v108
	s_nop 1
	v_cndmask_b32_e64 v103, v103, v106, s[76:77]
	v_mul_f32_e32 v104, 0x37800000, v103
	v_cndmask_b32_e32 v103, v103, v104, vcc
	v_cmp_class_f32_e32 vcc, v102, v3
	s_nop 1
	v_cndmask_b32_e32 v102, v103, v102, vcc
	v_div_scale_f32 v103, s[76:77], v102, v102, 1.0
	v_rcp_f32_e32 v104, v103
	v_div_scale_f32 v106, vcc, 1.0, v102, 1.0
	v_fma_f32 v107, -v103, v104, 1.0
	v_fmac_f32_e32 v104, v107, v104
	v_mul_f32_e32 v107, v106, v104
	v_fma_f32 v108, -v103, v107, v106
	v_fmac_f32_e32 v107, v108, v104
	v_fma_f32 v103, -v103, v107, v106
	v_div_fmas_f32 v103, v103, v104, v107
	v_div_fixup_f32 v110, v103, v102, 1.0
	v_pk_mul_f32 v[112:113], v[112:113], v[110:111] op_sel_hi:[1,0]
	v_pk_mul_f32 v[114:115], v[114:115], v[110:111] op_sel_hi:[1,0]
	v_pk_mul_f32 v[116:117], v[116:117], v[110:111] op_sel_hi:[1,0]
	v_pk_mul_f32 v[118:119], v[118:119], v[110:111] op_sel_hi:[1,0]
	v_pk_mul_f32 v[120:121], v[120:121], v[110:111] op_sel_hi:[1,0]
	v_pk_mul_f32 v[122:123], v[122:123], v[110:111] op_sel_hi:[1,0]
	v_pk_mul_f32 v[124:125], v[124:125], v[110:111] op_sel_hi:[1,0]
	v_pk_mul_f32 v[100:101], v[100:101], v[110:111] op_sel_hi:[1,0]
	v_pk_mul_f32 v[112:113], v[176:177], v[112:113]
	v_pk_mul_f32 v[114:115], v[178:179], v[114:115]
	v_pk_mul_f32 v[116:117], v[180:181], v[116:117]
	v_pk_mul_f32 v[118:119], v[182:183], v[118:119]
	v_pk_mul_f32 v[120:121], v[184:185], v[120:121]
	v_pk_mul_f32 v[122:123], v[186:187], v[122:123]
	v_pk_mul_f32 v[124:125], v[188:189], v[124:125]
	v_pk_mul_f32 v[100:101], v[190:191], v[100:101]
	v_pk_fma_f32 v[4:5], v[160:161], v[112:113], v[4:5]
	v_pk_fma_f32 v[6:7], v[162:163], v[114:115], v[6:7]
	v_pk_fma_f32 v[8:9], v[164:165], v[116:117], v[8:9]
	v_pk_fma_f32 v[10:11], v[166:167], v[118:119], v[10:11]
	v_pk_fma_f32 v[12:13], v[168:169], v[120:121], v[12:13]
	v_pk_fma_f32 v[14:15], v[170:171], v[122:123], v[14:15]
	v_pk_fma_f32 v[16:17], v[172:173], v[124:125], v[16:17]
	v_pk_fma_f32 v[18:19], v[174:175], v[100:101], v[18:19]
	v_pk_mul_f32 v[102:103], v[4:5], v[4:5]
	v_pk_mul_f32 v[106:107], v[6:7], v[6:7]
	v_pk_fma_f32 v[102:103], v[8:9], v[8:9], v[102:103]
	v_pk_fma_f32 v[106:107], v[10:11], v[10:11], v[106:107]
	v_pk_fma_f32 v[102:103], v[12:13], v[12:13], v[102:103]
	v_pk_fma_f32 v[106:107], v[14:15], v[14:15], v[106:107]
	v_pk_fma_f32 v[102:103], v[16:17], v[16:17], v[102:103]
	v_pk_fma_f32 v[106:107], v[18:19], v[18:19], v[106:107]
	s_nop 0
	v_pk_add_f32 v[102:103], v[102:103], v[106:107]
	s_nop 0
	v_add_f32_e32 v102, v102, v103
	s_nop 1
	v_add_f32_dpp v102, v102, v102 quad_perm:[1,0,3,2] row_mask:0xf bank_mask:0xf
	s_nop 1
	v_add_f32_dpp v102, v102, v102 quad_perm:[2,3,0,1] row_mask:0xf bank_mask:0xf
	s_nop 1
	v_add_f32_dpp v102, v102, v102 row_half_mirror row_mask:0xf bank_mask:0xf
	s_nop 1
	v_add_f32_dpp v102, v102, v102 row_mirror row_mask:0xf bank_mask:0xf
	s_nop 1
	v_add_f32_dpp v102, v102, v102 row_bcast:15 row_mask:0xa bank_mask:0xf
	s_nop 1
	v_add_f32_dpp v102, v102, v102 row_bcast:31 row_mask:0xc bank_mask:0xf
	s_nop 1
	v_readlane_b32 s74, v102, 63
	s_nop 2
	v_mov_b32_e32 v102, s74
	v_fmamk_f32 v102, v102, 0x3a800000, v2
	v_mul_f32_e32 v103, 0x4f800000, v102
	v_cmp_gt_f32_e32 vcc, 0xf800000, v102
	s_nop 1
	v_cndmask_b32_e32 v102, v102, v103, vcc
	v_sqrt_f32_e32 v103, v102
	s_nop 0
	v_add_u32_e32 v104, -1, v103
	v_add_u32_e32 v106, 1, v103
	v_fma_f32 v107, -v104, v103, v102
	v_fma_f32 v108, -v106, v103, v102
	v_cmp_ge_f32_e64 s[76:77], 0, v107
	s_nop 1
	v_cndmask_b32_e64 v103, v103, v104, s[76:77]
	v_cmp_lt_f32_e64 s[76:77], 0, v108
	s_nop 1
	v_cndmask_b32_e64 v103, v103, v106, s[76:77]
	v_mul_f32_e32 v104, 0x37800000, v103
	v_cndmask_b32_e32 v103, v103, v104, vcc
	v_cmp_class_f32_e32 vcc, v102, v3
	s_nop 1
	v_cndmask_b32_e32 v102, v103, v102, vcc
	v_div_scale_f32 v103, s[76:77], v102, v102, 1.0
	v_rcp_f32_e32 v104, v103
	v_div_scale_f32 v106, vcc, 1.0, v102, 1.0
	v_fma_f32 v107, -v103, v104, 1.0
	v_fmac_f32_e32 v104, v107, v104
	v_mul_f32_e32 v107, v106, v104
	v_fma_f32 v108, -v103, v107, v106
	v_fmac_f32_e32 v107, v108, v104
	v_fma_f32 v103, -v103, v107, v106
	v_div_fmas_f32 v103, v103, v104, v107
	v_div_fixup_f32 v110, v103, v102, 1.0
	s_lshl_b32 s60, s55, 11
	s_add_u32 s70, s78, s60
	s_addc_u32 s71, s79, 0
	v_pk_mul_f32 v[112:113], v[4:5], v[110:111] op_sel_hi:[1,0]
	v_pk_mul_f32 v[114:115], v[6:7], v[110:111] op_sel_hi:[1,0]
	v_pk_mul_f32 v[116:117], v[8:9], v[110:111] op_sel_hi:[1,0]
	v_pk_mul_f32 v[118:119], v[10:11], v[110:111] op_sel_hi:[1,0]
	v_pk_mul_f32 v[120:121], v[12:13], v[110:111] op_sel_hi:[1,0]
	v_pk_mul_f32 v[122:123], v[14:15], v[110:111] op_sel_hi:[1,0]
	v_pk_mul_f32 v[124:125], v[16:17], v[110:111] op_sel_hi:[1,0]
	v_pk_mul_f32 v[100:101], v[18:19], v[110:111] op_sel_hi:[1,0]
	v_pk_mul_f32 v[112:113], v[192:193], v[112:113]
	v_pk_mul_f32 v[114:115], v[194:195], v[114:115]
	v_pk_mul_f32 v[116:117], v[196:197], v[116:117]
	v_pk_mul_f32 v[118:119], v[198:199], v[118:119]
	v_pk_mul_f32 v[120:121], v[200:201], v[120:121]
	v_pk_mul_f32 v[122:123], v[202:203], v[122:123]
	v_pk_mul_f32 v[124:125], v[204:205], v[124:125]
	v_pk_mul_f32 v[100:101], v[206:207], v[100:101]
	v_pk_fma_f32 v[112:113], v[208:209], v[112:113], v[224:225]
	v_pk_fma_f32 v[114:115], v[210:211], v[114:115], v[226:227]
	v_pk_fma_f32 v[116:117], v[212:213], v[116:117], v[228:229]
	v_pk_fma_f32 v[118:119], v[214:215], v[118:119], v[230:231]
	v_pk_fma_f32 v[120:121], v[216:217], v[120:121], v[232:233]
	v_pk_fma_f32 v[122:123], v[218:219], v[122:123], v[234:235]
; __device__ __forceinline__ float lo_bf(unsigned w) { return __uint_as_float(w << 16); }
; template <bool HAS_F, bool HAS_H>
; __device__ __forceinline__ void phase_rows(const Params& p, int sp, int sn, float resw, bool from_input, bool write_x = true) {
;     ...
;     for (int row = gw; row < T; row += NGW) {
;         const int b = row_batch(row);
;         const float* xin = !from_input ? p.out + (size_t)row * D : (row < TP ? p.in[0] + (size_t)row * D : p.in[1] + (size_t)(row - TP) * D);
;         f32x4 v[4];
; #pragma unroll
;         for (int j = 0; j < 4; ++j) v[j] = *(const f32x4*)(xin + 4 * lane + 256 * j);
;         if (HAS_F) {
;             f32x4 f[4]; float ss = 0.f;
; #pragma unroll
;             for (int j = 0; j < 4; ++j) { const u32x2 w = *(const u32x2*)(F + (size_t)row * D + 4 * lane + 256 * j);
;                 f[j] = (f32x4){lo_bf(w.x), hi_bf(w.x), lo_bf(w.y), hi_bf(w.y)}; ss += (f[j].x * f[j].x + f[j].y * f[j].y) + (f[j].z * f[j].z + f[j].w * f[j].w); }
;             const float rs = 1.0f / sqrtf(wave_sum(ss) * (1.0f / D) + EPS) * resw;
;             const float* gate = mod + b * 9216 + sp * 3072 + 2048; const float* gp = p.in[7] + sp * D;
; #pragma unroll
;             for (int j = 0; j < 4; ++j) { const f32x4 g = *(const f32x4*)(gate + 4 * lane + 256 * j), q = *(const f32x4*)(gp + 4 * lane + 256 * j);
;                 v[j] = v[j] + g * (f[j] * rs * q);
;                 if (write_x) *(f32x4*)(p.out + (size_t)row * D + 4 * lane + 256 * j) = v[j]; }
;         }
;         if (HAS_H) {
;             float ss = 0.f;
; #pragma unroll
;             for (int j = 0; j < 4; ++j) ss += (v[j].x * v[j].x + v[j].y * v[j].y) + (v[j].z * v[j].z + v[j].w * v[j].w);
;             const float rs = 1.0f / sqrtf(wave_sum(ss) * (1.0f / D) + EPS);
;             const float* sh = mod + b * 9216 + sn * 3072; const float* scl = sh + 1024; const float* gq = p.in[6] + sn * D;
; #pragma unroll
;             for (int j = 0; j < 4; ++j) { const f32x4 a = *(const f32x4*)(sh + 4 * lane + 256 * j), s = *(const f32x4*)(scl + 4 * lane + 256 * j), q = *(const f32x4*)(gq + 4 * lane + 256 * j);
;                 const f32x4 h = (v[j] * rs * q) * (s + 1.0f) + a;
;                 u32x2 w; w.x = pk_bf16(h.x, h.y); w.y = pk_bf16(h.z, h.w);
;                 *(u32x2*)(H + (size_t)row * D + 4 * lane + 256 * j) = w; }
;         }
	v_pk_fma_f32 v[124:125], v[220:221], v[124:125], v[236:237]
	v_pk_fma_f32 v[100:101], v[222:223], v[100:101], v[238:239]
	v_cvt_pk_bf16_f32 v240, v112, v113
	v_cvt_pk_bf16_f32 v241, v114, v115
	v_cvt_pk_bf16_f32 v242, v116, v117
	v_cvt_pk_bf16_f32 v243, v118, v119
	v_cvt_pk_bf16_f32 v244, v120, v121
	v_cvt_pk_bf16_f32 v245, v122, v123
	v_cvt_pk_bf16_f32 v246, v124, v125
	v_cvt_pk_bf16_f32 v247, v100, v101
	global_store_dwordx2 v1, v[240:241], s[70:71]
	global_store_dwordx2 v1, v[242:243], s[70:71] offset:512
	global_store_dwordx2 v1, v[244:245], s[70:71] offset:1024
	global_store_dwordx2 v1, v[246:247], s[70:71] offset:1536
	s_add_u32 s55, s55, 8
	s_add_u32 s57, s55, 8
	s_min_u32 s57, s57, s54
	s_lshl_b32 s60, s57, 12
	s_add_u32 s64, s84, s60
	s_addc_u32 s65, s85, 0
	s_lshl_b32 s60, s57, 11
	s_add_u32 s66, s82, s60
	s_addc_u32 s67, s83, 0
	global_load_dwordx4 v[4:7], v0, s[64:65] nt
	global_load_dwordx4 v[8:11], v0, s[64:65] offset:1024 nt
	global_load_dwordx4 v[12:15], v0, s[64:65] offset:2048 nt
	global_load_dwordx4 v[16:19], v0, s[64:65] offset:3072 nt
	global_load_dwordx2 v[20:21], v1, s[66:67] nt
	global_load_dwordx2 v[22:23], v1, s[66:67] offset:512 nt
	global_load_dwordx2 v[24:25], v1, s[66:67] offset:1024 nt
	global_load_dwordx2 v[26:27], v1, s[66:67] offset:1536 nt
	s_lshr_b32 s60, s55, 11
	s_sub_u32 s61, s55, 0x8000
	s_lshr_b32 s61, s61, 12
	s_add_u32 s61, s61, 16
	s_cmp_lt_u32 s55, 0x8000
	s_cselect_b32 s63, s60, s61
	s_cmp_eq_u32 s63, s56
	s_cbranch_scc1 .Lrp12_pk5
	s_mov_b32 s56, s63
	s_mul_i32 s60, s56, 0x9000
	s_add_u32 s60, s60, 0x3185000
	s_add_u32 s0, s92, s60
	s_addc_u32 s1, s93, 0
	global_load_dwordx4 v[160:163], v0, s[0:1]
	global_load_dwordx4 v[164:167], v0, s[0:1] offset:1024
	global_load_dwordx4 v[168:171], v0, s[0:1] offset:2048
	global_load_dwordx4 v[172:175], v0, s[0:1] offset:3072
	s_add_u32 s0, s22, 0x1000
	s_addc_u32 s1, s23, 0
	global_load_dwordx4 v[176:179], v0, s[0:1]
	global_load_dwordx4 v[180:183], v0, s[0:1] offset:1024
	global_load_dwordx4 v[184:187], v0, s[0:1] offset:2048
	global_load_dwordx4 v[188:191], v0, s[0:1] offset:3072
	s_add_u32 s0, s20, 0x2000
	s_addc_u32 s1, s21, 0
	global_load_dwordx4 v[192:195], v0, s[0:1]
	global_load_dwordx4 v[196:199], v0, s[0:1] offset:1024
	global_load_dwordx4 v[200:203], v0, s[0:1] offset:2048
	global_load_dwordx4 v[204:207], v0, s[0:1] offset:3072
	s_mul_i32 s60, s56, 0x9000
	s_add_u32 s60, s60, 0x3187000
	s_add_u32 s0, s92, s60
	s_addc_u32 s1, s93, 0
	global_load_dwordx4 v[208:211], v0, s[0:1]
	global_load_dwordx4 v[212:215], v0, s[0:1] offset:1024
	global_load_dwordx4 v[216:219], v0, s[0:1] offset:2048
	global_load_dwordx4 v[220:223], v0, s[0:1] offset:3072
	s_mul_i32 s60, s56, 0x9000
	s_add_u32 s60, s60, 0x3186000
	s_add_u32 s0, s92, s60
	s_addc_u32 s1, s93, 0
	global_load_dwordx4 v[224:227], v0, s[0:1]
	global_load_dwordx4 v[228:231], v0, s[0:1] offset:1024
	global_load_dwordx4 v[232:235], v0, s[0:1] offset:2048
	global_load_dwordx4 v[236:239], v0, s[0:1] offset:3072
	s_waitcnt vmcnt(0)
	v_pk_add_f32 v[208:209], v[208:209], 1.0 op_sel_hi:[1,0]
	v_pk_add_f32 v[210:211], v[210:211], 1.0 op_sel_hi:[1,0]
	v_pk_add_f32 v[212:213], v[212:213], 1.0 op_sel_hi:[1,0]
	v_pk_add_f32 v[214:215], v[214:215], 1.0 op_sel_hi:[1,0]
	v_pk_add_f32 v[216:217], v[216:217], 1.0 op_sel_hi:[1,0]
	v_pk_add_f32 v[218:219], v[218:219], 1.0 op_sel_hi:[1,0]
	v_pk_add_f32 v[220:221], v[220:221], 1.0 op_sel_hi:[1,0]
	v_pk_add_f32 v[222:223], v[222:223], 1.0 op_sel_hi:[1,0]
.Lrp12_pk5:
	s_waitcnt vmcnt(12)
	v_lshlrev_b32_e32 v112, 16, v52
	v_and_b32_e32 v113, 0xffff0000, v52
	v_lshlrev_b32_e32 v114, 16, v53
	v_and_b32_e32 v115, 0xffff0000, v53
	v_lshlrev_b32_e32 v116, 16, v54
	v_and_b32_e32 v117, 0xffff0000, v54
	v_lshlrev_b32_e32 v118, 16, v55
	v_and_b32_e32 v119, 0xffff0000, v55
	v_lshlrev_b32_e32 v120, 16, v56
	v_and_b32_e32 v121, 0xffff0000, v56
	v_lshlrev_b32_e32 v122, 16, v57
	v_and_b32_e32 v123, 0xffff0000, v57
	v_lshlrev_b32_e32 v124, 16, v58
	v_and_b32_e32 v125, 0xffff0000, v58
	v_lshlrev_b32_e32 v100, 16, v59
	v_and_b32_e32 v101, 0xffff0000, v59
	v_pk_mul_f32 v[102:103], v[112:113], v[112:113]
	v_pk_mul_f32 v[106:107], v[114:115], v[114:115]
	v_pk_fma_f32 v[102:103], v[116:117], v[116:117], v[102:103]
	v_pk_fma_f32 v[106:107], v[118:119], v[118:119], v[106:107]
	v_pk_fma_f32 v[102:103], v[120:121], v[120:121], v[102:103]
	v_pk_fma_f32 v[106:107], v[122:123], v[122:123], v[106:107]
	v_pk_fma_f32 v[102:103], v[124:125], v[124:125], v[102:103]
	v_pk_fma_f32 v[106:107], v[100:101], v[100:101], v[106:107]
	s_nop 0
	v_pk_add_f32 v[102:103], v[102:103], v[106:107]
	s_nop 0
	v_add_f32_e32 v102, v102, v103
	s_nop 1
	v_add_f32_dpp v102, v102, v102 quad_perm:[1,0,3,2] row_mask:0xf bank_mask:0xf
	s_nop 1
	v_add_f32_dpp v102, v102, v102 quad_perm:[2,3,0,1] row_mask:0xf bank_mask:0xf
	s_nop 1
	v_add_f32_dpp v102, v102, v102 row_half_mirror row_mask:0xf bank_mask:0xf
	s_nop 1
	v_add_f32_dpp v102, v102, v102 row_mirror row_mask:0xf bank_mask:0xf
	s_nop 1
	v_add_f32_dpp v102, v102, v102 row_bcast:15 row_mask:0xa bank_mask:0xf
	s_nop 1
	v_add_f32_dpp v102, v102, v102 row_bcast:31 row_mask:0xc bank_mask:0xf
	s_nop 1
	v_readlane_b32 s74, v102, 63
	s_nop 2
	v_mov_b32_e32 v102, s74
	v_fmamk_f32 v102, v102, 0x3a800000, v2
	v_mul_f32_e32 v103, 0x4f800000, v102
	v_cmp_gt_f32_e32 vcc, 0xf800000, v102
	s_nop 1
	v_cndmask_b32_e32 v102, v102, v103, vcc
	v_sqrt_f32_e32 v103, v102
	s_nop 0
	v_add_u32_e32 v104, -1, v103
	v_add_u32_e32 v106, 1, v103
	v_fma_f32 v107, -v104, v103, v102
	v_fma_f32 v108, -v106, v103, v102
	v_cmp_ge_f32_e64 s[76:77], 0, v107
	s_nop 1
	v_cndmask_b32_e64 v103, v103, v104, s[76:77]
; __device__ __forceinline__ unsigned pk_bf16(float lo, float hi) { const f32x2 v = {lo, hi}; const bf16x2_t b = __builtin_convertvector(v, bf16x2_t); return __builtin_bit_cast(unsigned, b); }
; __device__ __forceinline__ float lo_bf(unsigned w) { return __uint_as_float(w << 16); }
; __device__ __forceinline__ float hi_bf(unsigned w) { return __uint_as_float(w & 0xffff0000u); }
; template <bool HAS_F, bool HAS_H>
; __device__ __forceinline__ void phase_rows(const Params& p, int sp, int sn, float resw, bool from_input, bool write_x = true) {
;     ...
;             for (int j = 0; j < 4; ++j) { const u32x2 w = *(const u32x2*)(F + (size_t)row * D + 4 * lane + 256 * j);
;                 f[j] = (f32x4){lo_bf(w.x), hi_bf(w.x), lo_bf(w.y), hi_bf(w.y)}; ss += (f[j].x * f[j].x + f[j].y * f[j].y) + (f[j].z * f[j].z + f[j].w * f[j].w); }
;             const float rs = 1.0f / sqrtf(wave_sum(ss) * (1.0f / D) + EPS) * resw;
;             const float* gate = mod + b * 9216 + sp * 3072 + 2048; const float* gp = p.in[7] + sp * D;
; #pragma unroll
;             for (int j = 0; j < 4; ++j) { const f32x4 g = *(const f32x4*)(gate + 4 * lane + 256 * j), q = *(const f32x4*)(gp + 4 * lane + 256 * j);
;                 v[j] = v[j] + g * (f[j] * rs * q);
;                 if (write_x) *(f32x4*)(p.out + (size_t)row * D + 4 * lane + 256 * j) = v[j]; }
;         }
;         if (HAS_H) {
;             float ss = 0.f;
; #pragma unroll
;             for (int j = 0; j < 4; ++j) ss += (v[j].x * v[j].x + v[j].y * v[j].y) + (v[j].z * v[j].z + v[j].w * v[j].w);
;             const float rs = 1.0f / sqrtf(wave_sum(ss) * (1.0f / D) + EPS);
;             const float* sh = mod + b * 9216 + sn * 3072; const float* scl = sh + 1024; const float* gq = p.in[6] + sn * D;
; #pragma unroll
;             for (int j = 0; j < 4; ++j) { const f32x4 a = *(const f32x4*)(sh + 4 * lane + 256 * j), s = *(const f32x4*)(scl + 4 * lane + 256 * j), q = *(const f32x4*)(gq + 4 * lane + 256 * j);
;                 const f32x4 h = (v[j] * rs * q) * (s + 1.0f) + a;
;                 u32x2 w; w.x = pk_bf16(h.x, h.y); w.y = pk_bf16(h.z, h.w);
;                 *(u32x2*)(H + (size_t)row * D + 4 * lane + 256 * j) = w; }
	v_cmp_lt_f32_e64 s[76:77], 0, v108
	s_nop 1
	v_cndmask_b32_e64 v103, v103, v106, s[76:77]
	v_mul_f32_e32 v104, 0x37800000, v103
	v_cndmask_b32_e32 v103, v103, v104, vcc
	v_cmp_class_f32_e32 vcc, v102, v3
	s_nop 1
	v_cndmask_b32_e32 v102, v103, v102, vcc
	v_div_scale_f32 v103, s[76:77], v102, v102, 1.0
	v_rcp_f32_e32 v104, v103
	v_div_scale_f32 v106, vcc, 1.0, v102, 1.0
	v_fma_f32 v107, -v103, v104, 1.0
	v_fmac_f32_e32 v104, v107, v104
	v_mul_f32_e32 v107, v106, v104
	v_fma_f32 v108, -v103, v107, v106
	v_fmac_f32_e32 v107, v108, v104
	v_fma_f32 v103, -v103, v107, v106
	v_div_fmas_f32 v103, v103, v104, v107
	v_div_fixup_f32 v110, v103, v102, 1.0
	v_pk_mul_f32 v[112:113], v[112:113], v[110:111] op_sel_hi:[1,0]
	v_pk_mul_f32 v[114:115], v[114:115], v[110:111] op_sel_hi:[1,0]
	v_pk_mul_f32 v[116:117], v[116:117], v[110:111] op_sel_hi:[1,0]
	v_pk_mul_f32 v[118:119], v[118:119], v[110:111] op_sel_hi:[1,0]
	v_pk_mul_f32 v[120:121], v[120:121], v[110:111] op_sel_hi:[1,0]
	v_pk_mul_f32 v[122:123], v[122:123], v[110:111] op_sel_hi:[1,0]
	v_pk_mul_f32 v[124:125], v[124:125], v[110:111] op_sel_hi:[1,0]
	v_pk_mul_f32 v[100:101], v[100:101], v[110:111] op_sel_hi:[1,0]
	v_pk_mul_f32 v[112:113], v[176:177], v[112:113]
	v_pk_mul_f32 v[114:115], v[178:179], v[114:115]
	v_pk_mul_f32 v[116:117], v[180:181], v[116:117]
	v_pk_mul_f32 v[118:119], v[182:183], v[118:119]
	v_pk_mul_f32 v[120:121], v[184:185], v[120:121]
	v_pk_mul_f32 v[122:123], v[186:187], v[122:123]
	v_pk_mul_f32 v[124:125], v[188:189], v[124:125]
	v_pk_mul_f32 v[100:101], v[190:191], v[100:101]
	v_pk_fma_f32 v[36:37], v[160:161], v[112:113], v[36:37]
	v_pk_fma_f32 v[38:39], v[162:163], v[114:115], v[38:39]
	v_pk_fma_f32 v[40:41], v[164:165], v[116:117], v[40:41]
	v_pk_fma_f32 v[42:43], v[166:167], v[118:119], v[42:43]
	v_pk_fma_f32 v[44:45], v[168:169], v[120:121], v[44:45]
	v_pk_fma_f32 v[46:47], v[170:171], v[122:123], v[46:47]
	v_pk_fma_f32 v[48:49], v[172:173], v[124:125], v[48:49]
	v_pk_fma_f32 v[50:51], v[174:175], v[100:101], v[50:51]
	v_pk_mul_f32 v[102:103], v[36:37], v[36:37]
	v_pk_mul_f32 v[106:107], v[38:39], v[38:39]
	v_pk_fma_f32 v[102:103], v[40:41], v[40:41], v[102:103]
	v_pk_fma_f32 v[106:107], v[42:43], v[42:43], v[106:107]
	v_pk_fma_f32 v[102:103], v[44:45], v[44:45], v[102:103]
	v_pk_fma_f32 v[106:107], v[46:47], v[46:47], v[106:107]
	v_pk_fma_f32 v[102:103], v[48:49], v[48:49], v[102:103]
	v_pk_fma_f32 v[106:107], v[50:51], v[50:51], v[106:107]
	s_nop 0
	v_pk_add_f32 v[102:103], v[102:103], v[106:107]
	s_nop 0
	v_add_f32_e32 v102, v102, v103
	s_nop 1
	v_add_f32_dpp v102, v102, v102 quad_perm:[1,0,3,2] row_mask:0xf bank_mask:0xf
	s_nop 1
	v_add_f32_dpp v102, v102, v102 quad_perm:[2,3,0,1] row_mask:0xf bank_mask:0xf
	s_nop 1
	v_add_f32_dpp v102, v102, v102 row_half_mirror row_mask:0xf bank_mask:0xf
	s_nop 1
	v_add_f32_dpp v102, v102, v102 row_mirror row_mask:0xf bank_mask:0xf
	s_nop 1
	v_add_f32_dpp v102, v102, v102 row_bcast:15 row_mask:0xa bank_mask:0xf
	s_nop 1
	v_add_f32_dpp v102, v102, v102 row_bcast:31 row_mask:0xc bank_mask:0xf
	s_nop 1
	v_readlane_b32 s74, v102, 63
	s_nop 2
	v_mov_b32_e32 v102, s74
	v_fmamk_f32 v102, v102, 0x3a800000, v2
	v_mul_f32_e32 v103, 0x4f800000, v102
	v_cmp_gt_f32_e32 vcc, 0xf800000, v102
	s_nop 1
	v_cndmask_b32_e32 v102, v102, v103, vcc
	v_sqrt_f32_e32 v103, v102
	s_nop 0
	v_add_u32_e32 v104, -1, v103
	v_add_u32_e32 v106, 1, v103
	v_fma_f32 v107, -v104, v103, v102
	v_fma_f32 v108, -v106, v103, v102
	v_cmp_ge_f32_e64 s[76:77], 0, v107
	s_nop 1
	v_cndmask_b32_e64 v103, v103, v104, s[76:77]
	v_cmp_lt_f32_e64 s[76:77], 0, v108
	s_nop 1
	v_cndmask_b32_e64 v103, v103, v106, s[76:77]
	v_mul_f32_e32 v104, 0x37800000, v103
	v_cndmask_b32_e32 v103, v103, v104, vcc
	v_cmp_class_f32_e32 vcc, v102, v3
	s_nop 1
	v_cndmask_b32_e32 v102, v103, v102, vcc
	v_div_scale_f32 v103, s[76:77], v102, v102, 1.0
	v_rcp_f32_e32 v104, v103
	v_div_scale_f32 v106, vcc, 1.0, v102, 1.0
	v_fma_f32 v107, -v103, v104, 1.0
	v_fmac_f32_e32 v104, v107, v104
	v_mul_f32_e32 v107, v106, v104
	v_fma_f32 v108, -v103, v107, v106
	v_fmac_f32_e32 v107, v108, v104
	v_fma_f32 v103, -v103, v107, v106
	v_div_fmas_f32 v103, v103, v104, v107
	v_div_fixup_f32 v110, v103, v102, 1.0
	s_lshl_b32 s60, s55, 11
	s_add_u32 s70, s78, s60
	s_addc_u32 s71, s79, 0
	v_pk_mul_f32 v[112:113], v[36:37], v[110:111] op_sel_hi:[1,0]
	v_pk_mul_f32 v[114:115], v[38:39], v[110:111] op_sel_hi:[1,0]
	v_pk_mul_f32 v[116:117], v[40:41], v[110:111] op_sel_hi:[1,0]
	v_pk_mul_f32 v[118:119], v[42:43], v[110:111] op_sel_hi:[1,0]
	v_pk_mul_f32 v[120:121], v[44:45], v[110:111] op_sel_hi:[1,0]
	v_pk_mul_f32 v[122:123], v[46:47], v[110:111] op_sel_hi:[1,0]
	v_pk_mul_f32 v[124:125], v[48:49], v[110:111] op_sel_hi:[1,0]
	v_pk_mul_f32 v[100:101], v[50:51], v[110:111] op_sel_hi:[1,0]
	v_pk_mul_f32 v[112:113], v[192:193], v[112:113]
	v_pk_mul_f32 v[114:115], v[194:195], v[114:115]
	v_pk_mul_f32 v[116:117], v[196:197], v[116:117]
	v_pk_mul_f32 v[118:119], v[198:199], v[118:119]
	v_pk_mul_f32 v[120:121], v[200:201], v[120:121]
	v_pk_mul_f32 v[122:123], v[202:203], v[122:123]
	v_pk_mul_f32 v[124:125], v[204:205], v[124:125]
	v_pk_mul_f32 v[100:101], v[206:207], v[100:101]
	v_pk_fma_f32 v[112:113], v[208:209], v[112:113], v[224:225]
	v_pk_fma_f32 v[114:115], v[210:211], v[114:115], v[226:227]
	v_pk_fma_f32 v[116:117], v[212:213], v[116:117], v[228:229]
	v_pk_fma_f32 v[118:119], v[214:215], v[118:119], v[230:231]
	v_pk_fma_f32 v[120:121], v[216:217], v[120:121], v[232:233]
	v_pk_fma_f32 v[122:123], v[218:219], v[122:123], v[234:235]
	v_pk_fma_f32 v[124:125], v[220:221], v[124:125], v[236:237]
	v_pk_fma_f32 v[100:101], v[222:223], v[100:101], v[238:239]
	v_cvt_pk_bf16_f32 v240, v112, v113
	v_cvt_pk_bf16_f32 v241, v114, v115
	v_cvt_pk_bf16_f32 v242, v116, v117
	v_cvt_pk_bf16_f32 v243, v118, v119
	v_cvt_pk_bf16_f32 v244, v120, v121
	v_cvt_pk_bf16_f32 v245, v122, v123
	v_cvt_pk_bf16_f32 v246, v124, v125
	v_cvt_pk_bf16_f32 v247, v100, v101
	global_store_dwordx2 v1, v[240:241], s[70:71]
	global_store_dwordx2 v1, v[242:243], s[70:71] offset:512
	global_store_dwordx2 v1, v[244:245], s[70:71] offset:1024
	global_store_dwordx2 v1, v[246:247], s[70:71] offset:1536
	s_add_u32 s55, s55, 8
; __device__ __forceinline__ float lo_bf(unsigned w) { return __uint_as_float(w << 16); }
; __device__ __forceinline__ float hi_bf(unsigned w) { return __uint_as_float(w & 0xffff0000u); }
; template <bool HAS_F, bool HAS_H>
; __device__ __forceinline__ void phase_rows(const Params& p, int sp, int sn, float resw, bool from_input, bool write_x = true) {
;     ...
;     for (int row = gw; row < T; row += NGW) {
;         const int b = row_batch(row);
;         const float* xin = !from_input ? p.out + (size_t)row * D : (row < TP ? p.in[0] + (size_t)row * D : p.in[1] + (size_t)(row - TP) * D);
;         f32x4 v[4];
; #pragma unroll
;         for (int j = 0; j < 4; ++j) v[j] = *(const f32x4*)(xin + 4 * lane + 256 * j);
;         if (HAS_F) {
;             f32x4 f[4]; float ss = 0.f;
; #pragma unroll
;             for (int j = 0; j < 4; ++j) { const u32x2 w = *(const u32x2*)(F + (size_t)row * D + 4 * lane + 256 * j);
;                 f[j] = (f32x4){lo_bf(w.x), hi_bf(w.x), lo_bf(w.y), hi_bf(w.y)}; ss += (f[j].x * f[j].x + f[j].y * f[j].y) + (f[j].z * f[j].z + f[j].w * f[j].w); }
;             const float rs = 1.0f / sqrtf(wave_sum(ss) * (1.0f / D) + EPS) * resw;
;             const float* gate = mod + b * 9216 + sp * 3072 + 2048; const float* gp = p.in[7] + sp * D;
; #pragma unroll
;             for (int j = 0; j < 4; ++j) { const f32x4 g = *(const f32x4*)(gate + 4 * lane + 256 * j), q = *(const f32x4*)(gp + 4 * lane + 256 * j);
;                 v[j] = v[j] + g * (f[j] * rs * q);
;                 if (write_x) *(f32x4*)(p.out + (size_t)row * D + 4 * lane + 256 * j) = v[j]; }
;         }
;         if (HAS_H) {
;             float ss = 0.f;
; #pragma unroll
;             for (int j = 0; j < 4; ++j) ss += (v[j].x * v[j].x + v[j].y * v[j].y) + (v[j].z * v[j].z + v[j].w * v[j].w);
;             const float rs = 1.0f / sqrtf(wave_sum(ss) * (1.0f / D) + EPS);
.Lrp12_loop3:
	s_add_u32 s57, s55, 8
	s_min_u32 s57, s57, s54
	s_lshl_b32 s60, s57, 12
	s_add_u32 s64, s84, s60
	s_addc_u32 s65, s85, 0
	s_lshl_b32 s60, s57, 11
	s_add_u32 s66, s82, s60
	s_addc_u32 s67, s83, 0
	global_load_dwordx4 v[36:39], v0, s[64:65] nt
	global_load_dwordx4 v[40:43], v0, s[64:65] offset:1024 nt
	global_load_dwordx4 v[44:47], v0, s[64:65] offset:2048 nt
	global_load_dwordx4 v[48:51], v0, s[64:65] offset:3072 nt
	global_load_dwordx2 v[52:53], v1, s[66:67] nt
	global_load_dwordx2 v[54:55], v1, s[66:67] offset:512 nt
	global_load_dwordx2 v[56:57], v1, s[66:67] offset:1024 nt
	global_load_dwordx2 v[58:59], v1, s[66:67] offset:1536 nt
	s_lshr_b32 s60, s55, 11
	s_sub_u32 s61, s55, 0x8000
	s_lshr_b32 s61, s61, 12
	s_add_u32 s61, s61, 16
	s_cmp_lt_u32 s55, 0x8000
	s_cselect_b32 s63, s60, s61
	s_cmp_eq_u32 s63, s56
	s_cbranch_scc1 .Lrp12_pk6
	s_mov_b32 s56, s63
	s_mul_i32 s60, s56, 0x9000
	s_add_u32 s60, s60, 0x3185000
	s_add_u32 s0, s92, s60
	s_addc_u32 s1, s93, 0
	global_load_dwordx4 v[160:163], v0, s[0:1]
	global_load_dwordx4 v[164:167], v0, s[0:1] offset:1024
	global_load_dwordx4 v[168:171], v0, s[0:1] offset:2048
	global_load_dwordx4 v[172:175], v0, s[0:1] offset:3072
	s_add_u32 s0, s22, 0x1000
	s_addc_u32 s1, s23, 0
	global_load_dwordx4 v[176:179], v0, s[0:1]
	global_load_dwordx4 v[180:183], v0, s[0:1] offset:1024
	global_load_dwordx4 v[184:187], v0, s[0:1] offset:2048
	global_load_dwordx4 v[188:191], v0, s[0:1] offset:3072
	s_add_u32 s0, s20, 0x2000
	s_addc_u32 s1, s21, 0
	global_load_dwordx4 v[192:195], v0, s[0:1]
	global_load_dwordx4 v[196:199], v0, s[0:1] offset:1024
	global_load_dwordx4 v[200:203], v0, s[0:1] offset:2048
	global_load_dwordx4 v[204:207], v0, s[0:1] offset:3072
	s_mul_i32 s60, s56, 0x9000
	s_add_u32 s60, s60, 0x3187000
	s_add_u32 s0, s92, s60
	s_addc_u32 s1, s93, 0
	global_load_dwordx4 v[208:211], v0, s[0:1]
	global_load_dwordx4 v[212:215], v0, s[0:1] offset:1024
	global_load_dwordx4 v[216:219], v0, s[0:1] offset:2048
	global_load_dwordx4 v[220:223], v0, s[0:1] offset:3072
	s_mul_i32 s60, s56, 0x9000
	s_add_u32 s60, s60, 0x3186000
	s_add_u32 s0, s92, s60
	s_addc_u32 s1, s93, 0
	global_load_dwordx4 v[224:227], v0, s[0:1]
	global_load_dwordx4 v[228:231], v0, s[0:1] offset:1024
	global_load_dwordx4 v[232:235], v0, s[0:1] offset:2048
	global_load_dwordx4 v[236:239], v0, s[0:1] offset:3072
	s_waitcnt vmcnt(0)
	v_pk_add_f32 v[208:209], v[208:209], 1.0 op_sel_hi:[1,0]
	v_pk_add_f32 v[210:211], v[210:211], 1.0 op_sel_hi:[1,0]
	v_pk_add_f32 v[212:213], v[212:213], 1.0 op_sel_hi:[1,0]
	v_pk_add_f32 v[214:215], v[214:215], 1.0 op_sel_hi:[1,0]
	v_pk_add_f32 v[216:217], v[216:217], 1.0 op_sel_hi:[1,0]
	v_pk_add_f32 v[218:219], v[218:219], 1.0 op_sel_hi:[1,0]
	v_pk_add_f32 v[220:221], v[220:221], 1.0 op_sel_hi:[1,0]
	v_pk_add_f32 v[222:223], v[222:223], 1.0 op_sel_hi:[1,0]
.Lrp12_pk6:
	s_waitcnt vmcnt(12)
	v_lshlrev_b32_e32 v112, 16, v20
	v_and_b32_e32 v113, 0xffff0000, v20
	v_lshlrev_b32_e32 v114, 16, v21
	v_and_b32_e32 v115, 0xffff0000, v21
	v_lshlrev_b32_e32 v116, 16, v22
	v_and_b32_e32 v117, 0xffff0000, v22
	v_lshlrev_b32_e32 v118, 16, v23
	v_and_b32_e32 v119, 0xffff0000, v23
	v_lshlrev_b32_e32 v120, 16, v24
	v_and_b32_e32 v121, 0xffff0000, v24
	v_lshlrev_b32_e32 v122, 16, v25
	v_and_b32_e32 v123, 0xffff0000, v25
	v_lshlrev_b32_e32 v124, 16, v26
	v_and_b32_e32 v125, 0xffff0000, v26
	v_lshlrev_b32_e32 v100, 16, v27
	v_and_b32_e32 v101, 0xffff0000, v27
	v_pk_mul_f32 v[102:103], v[112:113], v[112:113]
	v_pk_mul_f32 v[106:107], v[114:115], v[114:115]
	v_pk_fma_f32 v[102:103], v[116:117], v[116:117], v[102:103]
	v_pk_fma_f32 v[106:107], v[118:119], v[118:119], v[106:107]
	v_pk_fma_f32 v[102:103], v[120:121], v[120:121], v[102:103]
	v_pk_fma_f32 v[106:107], v[122:123], v[122:123], v[106:107]
	v_pk_fma_f32 v[102:103], v[124:125], v[124:125], v[102:103]
	v_pk_fma_f32 v[106:107], v[100:101], v[100:101], v[106:107]
	s_nop 0
	v_pk_add_f32 v[102:103], v[102:103], v[106:107]
	s_nop 0
	v_add_f32_e32 v102, v102, v103
	s_nop 1
	v_add_f32_dpp v102, v102, v102 quad_perm:[1,0,3,2] row_mask:0xf bank_mask:0xf
	s_nop 1
	v_add_f32_dpp v102, v102, v102 quad_perm:[2,3,0,1] row_mask:0xf bank_mask:0xf
	s_nop 1
	v_add_f32_dpp v102, v102, v102 row_half_mirror row_mask:0xf bank_mask:0xf
	s_nop 1
	v_add_f32_dpp v102, v102, v102 row_mirror row_mask:0xf bank_mask:0xf
	s_nop 1
	v_add_f32_dpp v102, v102, v102 row_bcast:15 row_mask:0xa bank_mask:0xf
	s_nop 1
	v_add_f32_dpp v102, v102, v102 row_bcast:31 row_mask:0xc bank_mask:0xf
	s_nop 1
	v_readlane_b32 s74, v102, 63
	s_nop 2
	v_mov_b32_e32 v102, s74
	v_fmamk_f32 v102, v102, 0x3a800000, v2
	v_mul_f32_e32 v103, 0x4f800000, v102
	v_cmp_gt_f32_e32 vcc, 0xf800000, v102
	s_nop 1
	v_cndmask_b32_e32 v102, v102, v103, vcc
	v_sqrt_f32_e32 v103, v102
	s_nop 0
	v_add_u32_e32 v104, -1, v103
	v_add_u32_e32 v106, 1, v103
	v_fma_f32 v107, -v104, v103, v102
	v_fma_f32 v108, -v106, v103, v102
	v_cmp_ge_f32_e64 s[76:77], 0, v107
	s_nop 1
	v_cndmask_b32_e64 v103, v103, v104, s[76:77]
	v_cmp_lt_f32_e64 s[76:77], 0, v108
	s_nop 1
	v_cndmask_b32_e64 v103, v103, v106, s[76:77]
	v_mul_f32_e32 v104, 0x37800000, v103
	v_cndmask_b32_e32 v103, v103, v104, vcc
	v_cmp_class_f32_e32 vcc, v102, v3
	s_nop 1
	v_cndmask_b32_e32 v102, v103, v102, vcc
	v_div_scale_f32 v103, s[76:77], v102, v102, 1.0
	v_rcp_f32_e32 v104, v103
	v_div_scale_f32 v106, vcc, 1.0, v102, 1.0
	v_fma_f32 v107, -v103, v104, 1.0
	v_fmac_f32_e32 v104, v107, v104
	v_mul_f32_e32 v107, v106, v104
	v_fma_f32 v108, -v103, v107, v106
	v_fmac_f32_e32 v107, v108, v104
	v_fma_f32 v103, -v103, v107, v106
	v_div_fmas_f32 v103, v103, v104, v107
	v_div_fixup_f32 v110, v103, v102, 1.0
; __device__ __forceinline__ unsigned pk_bf16(float lo, float hi) { const f32x2 v = {lo, hi}; const bf16x2_t b = __builtin_convertvector(v, bf16x2_t); return __builtin_bit_cast(unsigned, b); }
; __device__ __forceinline__ float lo_bf(unsigned w) { return __uint_as_float(w << 16); }
; __device__ __forceinline__ float hi_bf(unsigned w) { return __uint_as_float(w & 0xffff0000u); }
; template <bool HAS_F, bool HAS_H>
; __device__ __forceinline__ void phase_rows(const Params& p, int sp, int sn, float resw, bool from_input, bool write_x = true) {
;     ...
;                 f[j] = (f32x4){lo_bf(w.x), hi_bf(w.x), lo_bf(w.y), hi_bf(w.y)}; ss += (f[j].x * f[j].x + f[j].y * f[j].y) + (f[j].z * f[j].z + f[j].w * f[j].w); }
;             const float rs = 1.0f / sqrtf(wave_sum(ss) * (1.0f / D) + EPS) * resw;
;             const float* gate = mod + b * 9216 + sp * 3072 + 2048; const float* gp = p.in[7] + sp * D;
; #pragma unroll
;             for (int j = 0; j < 4; ++j) { const f32x4 g = *(const f32x4*)(gate + 4 * lane + 256 * j), q = *(const f32x4*)(gp + 4 * lane + 256 * j);
;                 v[j] = v[j] + g * (f[j] * rs * q);
;                 if (write_x) *(f32x4*)(p.out + (size_t)row * D + 4 * lane + 256 * j) = v[j]; }
;         }
;         if (HAS_H) {
;             float ss = 0.f;
; #pragma unroll
;             for (int j = 0; j < 4; ++j) ss += (v[j].x * v[j].x + v[j].y * v[j].y) + (v[j].z * v[j].z + v[j].w * v[j].w);
;             const float rs = 1.0f / sqrtf(wave_sum(ss) * (1.0f / D) + EPS);
;             const float* sh = mod + b * 9216 + sn * 3072; const float* scl = sh + 1024; const float* gq = p.in[6] + sn * D;
; #pragma unroll
;             for (int j = 0; j < 4; ++j) { const f32x4 a = *(const f32x4*)(sh + 4 * lane + 256 * j), s = *(const f32x4*)(scl + 4 * lane + 256 * j), q = *(const f32x4*)(gq + 4 * lane + 256 * j);
;                 const f32x4 h = (v[j] * rs * q) * (s + 1.0f) + a;
;                 u32x2 w; w.x = pk_bf16(h.x, h.y); w.y = pk_bf16(h.z, h.w);
;                 *(u32x2*)(H + (size_t)row * D + 4 * lane + 256 * j) = w; }
	v_pk_mul_f32 v[112:113], v[112:113], v[110:111] op_sel_hi:[1,0]
	v_pk_mul_f32 v[114:115], v[114:115], v[110:111] op_sel_hi:[1,0]
	v_pk_mul_f32 v[116:117], v[116:117], v[110:111] op_sel_hi:[1,0]
	v_pk_mul_f32 v[118:119], v[118:119], v[110:111] op_sel_hi:[1,0]
	v_pk_mul_f32 v[120:121], v[120:121], v[110:111] op_sel_hi:[1,0]
	v_pk_mul_f32 v[122:123], v[122:123], v[110:111] op_sel_hi:[1,0]
	v_pk_mul_f32 v[124:125], v[124:125], v[110:111] op_sel_hi:[1,0]
	v_pk_mul_f32 v[100:101], v[100:101], v[110:111] op_sel_hi:[1,0]
	v_pk_mul_f32 v[112:113], v[176:177], v[112:113]
	v_pk_mul_f32 v[114:115], v[178:179], v[114:115]
	v_pk_mul_f32 v[116:117], v[180:181], v[116:117]
	v_pk_mul_f32 v[118:119], v[182:183], v[118:119]
	v_pk_mul_f32 v[120:121], v[184:185], v[120:121]
	v_pk_mul_f32 v[122:123], v[186:187], v[122:123]
	v_pk_mul_f32 v[124:125], v[188:189], v[124:125]
	v_pk_mul_f32 v[100:101], v[190:191], v[100:101]
	v_pk_fma_f32 v[4:5], v[160:161], v[112:113], v[4:5]
	v_pk_fma_f32 v[6:7], v[162:163], v[114:115], v[6:7]
	v_pk_fma_f32 v[8:9], v[164:165], v[116:117], v[8:9]
	v_pk_fma_f32 v[10:11], v[166:167], v[118:119], v[10:11]
	v_pk_fma_f32 v[12:13], v[168:169], v[120:121], v[12:13]
	v_pk_fma_f32 v[14:15], v[170:171], v[122:123], v[14:15]
	v_pk_fma_f32 v[16:17], v[172:173], v[124:125], v[16:17]
	v_pk_fma_f32 v[18:19], v[174:175], v[100:101], v[18:19]
	v_pk_mul_f32 v[102:103], v[4:5], v[4:5]
	v_pk_mul_f32 v[106:107], v[6:7], v[6:7]
	v_pk_fma_f32 v[102:103], v[8:9], v[8:9], v[102:103]
	v_pk_fma_f32 v[106:107], v[10:11], v[10:11], v[106:107]
	v_pk_fma_f32 v[102:103], v[12:13], v[12:13], v[102:103]
	v_pk_fma_f32 v[106:107], v[14:15], v[14:15], v[106:107]
	v_pk_fma_f32 v[102:103], v[16:17], v[16:17], v[102:103]
	v_pk_fma_f32 v[106:107], v[18:19], v[18:19], v[106:107]
	s_nop 0
	v_pk_add_f32 v[102:103], v[102:103], v[106:107]
	s_nop 0
	v_add_f32_e32 v102, v102, v103
	s_nop 1
	v_add_f32_dpp v102, v102, v102 quad_perm:[1,0,3,2] row_mask:0xf bank_mask:0xf
	s_nop 1
	v_add_f32_dpp v102, v102, v102 quad_perm:[2,3,0,1] row_mask:0xf bank_mask:0xf
	s_nop 1
	v_add_f32_dpp v102, v102, v102 row_half_mirror row_mask:0xf bank_mask:0xf
	s_nop 1
	v_add_f32_dpp v102, v102, v102 row_mirror row_mask:0xf bank_mask:0xf
	s_nop 1
	v_add_f32_dpp v102, v102, v102 row_bcast:15 row_mask:0xa bank_mask:0xf
	s_nop 1
	v_add_f32_dpp v102, v102, v102 row_bcast:31 row_mask:0xc bank_mask:0xf
	s_nop 1
	v_readlane_b32 s74, v102, 63
	s_nop 2
	v_mov_b32_e32 v102, s74
	v_fmamk_f32 v102, v102, 0x3a800000, v2
	v_mul_f32_e32 v103, 0x4f800000, v102
	v_cmp_gt_f32_e32 vcc, 0xf800000, v102
	s_nop 1
	v_cndmask_b32_e32 v102, v102, v103, vcc
	v_sqrt_f32_e32 v103, v102
	s_nop 0
	v_add_u32_e32 v104, -1, v103
	v_add_u32_e32 v106, 1, v103
	v_fma_f32 v107, -v104, v103, v102
	v_fma_f32 v108, -v106, v103, v102
	v_cmp_ge_f32_e64 s[76:77], 0, v107
	s_nop 1
	v_cndmask_b32_e64 v103, v103, v104, s[76:77]
	v_cmp_lt_f32_e64 s[76:77], 0, v108
	s_nop 1
	v_cndmask_b32_e64 v103, v103, v106, s[76:77]
	v_mul_f32_e32 v104, 0x37800000, v103
	v_cndmask_b32_e32 v103, v103, v104, vcc
	v_cmp_class_f32_e32 vcc, v102, v3
	s_nop 1
	v_cndmask_b32_e32 v102, v103, v102, vcc
	v_div_scale_f32 v103, s[76:77], v102, v102, 1.0
	v_rcp_f32_e32 v104, v103
	v_div_scale_f32 v106, vcc, 1.0, v102, 1.0
	v_fma_f32 v107, -v103, v104, 1.0
	v_fmac_f32_e32 v104, v107, v104
	v_mul_f32_e32 v107, v106, v104
	v_fma_f32 v108, -v103, v107, v106
	v_fmac_f32_e32 v107, v108, v104
	v_fma_f32 v103, -v103, v107, v106
	v_div_fmas_f32 v103, v103, v104, v107
	v_div_fixup_f32 v110, v103, v102, 1.0
	s_lshl_b32 s60, s55, 11
	s_add_u32 s70, s78, s60
	s_addc_u32 s71, s79, 0
	v_pk_mul_f32 v[112:113], v[4:5], v[110:111] op_sel_hi:[1,0]
	v_pk_mul_f32 v[114:115], v[6:7], v[110:111] op_sel_hi:[1,0]
	v_pk_mul_f32 v[116:117], v[8:9], v[110:111] op_sel_hi:[1,0]
	v_pk_mul_f32 v[118:119], v[10:11], v[110:111] op_sel_hi:[1,0]
	v_pk_mul_f32 v[120:121], v[12:13], v[110:111] op_sel_hi:[1,0]
	v_pk_mul_f32 v[122:123], v[14:15], v[110:111] op_sel_hi:[1,0]
	v_pk_mul_f32 v[124:125], v[16:17], v[110:111] op_sel_hi:[1,0]
	v_pk_mul_f32 v[100:101], v[18:19], v[110:111] op_sel_hi:[1,0]
	v_pk_mul_f32 v[112:113], v[192:193], v[112:113]
	v_pk_mul_f32 v[114:115], v[194:195], v[114:115]
	v_pk_mul_f32 v[116:117], v[196:197], v[116:117]
	v_pk_mul_f32 v[118:119], v[198:199], v[118:119]
	v_pk_mul_f32 v[120:121], v[200:201], v[120:121]
	v_pk_mul_f32 v[122:123], v[202:203], v[122:123]
	v_pk_mul_f32 v[124:125], v[204:205], v[124:125]
	v_pk_mul_f32 v[100:101], v[206:207], v[100:101]
	v_pk_fma_f32 v[112:113], v[208:209], v[112:113], v[224:225]
	v_pk_fma_f32 v[114:115], v[210:211], v[114:115], v[226:227]
	v_pk_fma_f32 v[116:117], v[212:213], v[116:117], v[228:229]
	v_pk_fma_f32 v[118:119], v[214:215], v[118:119], v[230:231]
	v_pk_fma_f32 v[120:121], v[216:217], v[120:121], v[232:233]
	v_pk_fma_f32 v[122:123], v[218:219], v[122:123], v[234:235]
	v_pk_fma_f32 v[124:125], v[220:221], v[124:125], v[236:237]
	v_pk_fma_f32 v[100:101], v[222:223], v[100:101], v[238:239]
	v_cvt_pk_bf16_f32 v240, v112, v113
	v_cvt_pk_bf16_f32 v241, v114, v115
	v_cvt_pk_bf16_f32 v242, v116, v117
	v_cvt_pk_bf16_f32 v243, v118, v119
	v_cvt_pk_bf16_f32 v244, v120, v121
	v_cvt_pk_bf16_f32 v245, v122, v123
	v_cvt_pk_bf16_f32 v246, v124, v125
	v_cvt_pk_bf16_f32 v247, v100, v101
	global_store_dwordx2 v1, v[240:241], s[70:71]
	global_store_dwordx2 v1, v[242:243], s[70:71] offset:512
	global_store_dwordx2 v1, v[244:245], s[70:71] offset:1024
	global_store_dwordx2 v1, v[246:247], s[70:71] offset:1536
	s_add_u32 s55, s55, 8
	s_add_u32 s57, s55, 8
	s_min_u32 s57, s57, s54
	s_lshl_b32 s60, s57, 12
	s_add_u32 s64, s84, s60
	s_addc_u32 s65, s85, 0
	s_lshl_b32 s60, s57, 11
	s_add_u32 s66, s82, s60
	s_addc_u32 s67, s83, 0
	global_load_dwordx4 v[4:7], v0, s[64:65] nt
	global_load_dwordx4 v[8:11], v0, s[64:65] offset:1024 nt
	global_load_dwordx4 v[12:15], v0, s[64:65] offset:2048 nt
	global_load_dwordx4 v[16:19], v0, s[64:65] offset:3072 nt
	global_load_dwordx2 v[20:21], v1, s[66:67] nt
	global_load_dwordx2 v[22:23], v1, s[66:67] offset:512 nt
	global_load_dwordx2 v[24:25], v1, s[66:67] offset:1024 nt
	global_load_dwordx2 v[26:27], v1, s[66:67] offset:1536 nt
	s_lshr_b32 s60, s55, 11
	s_sub_u32 s61, s55, 0x8000
	s_lshr_b32 s61, s61, 12
	s_add_u32 s61, s61, 16
	s_cmp_lt_u32 s55, 0x8000
	s_cselect_b32 s63, s60, s61
	s_cmp_eq_u32 s63, s56
	s_cbranch_scc1 .Lrp12_pk7
; __device__ __forceinline__ float lo_bf(unsigned w) { return __uint_as_float(w << 16); }
; __device__ __forceinline__ float hi_bf(unsigned w) { return __uint_as_float(w & 0xffff0000u); }
; template <bool HAS_F, bool HAS_H>
; __device__ __forceinline__ void phase_rows(const Params& p, int sp, int sn, float resw, bool from_input, bool write_x = true) {
;     ...
;             for (int j = 0; j < 4; ++j) { const u32x2 w = *(const u32x2*)(F + (size_t)row * D + 4 * lane + 256 * j);
;                 f[j] = (f32x4){lo_bf(w.x), hi_bf(w.x), lo_bf(w.y), hi_bf(w.y)}; ss += (f[j].x * f[j].x + f[j].y * f[j].y) + (f[j].z * f[j].z + f[j].w * f[j].w); }
;             const float rs = 1.0f / sqrtf(wave_sum(ss) * (1.0f / D) + EPS) * resw;
;     ...
;             const float* sh = mod + b * 9216 + sn * 3072; const float* scl = sh + 1024; const float* gq = p.in[6] + sn * D;
; #pragma unroll
;             for (int j = 0; j < 4; ++j) { const f32x4 a = *(const f32x4*)(sh + 4 * lane + 256 * j), s = *(const f32x4*)(scl + 4 * lane + 256 * j), q = *(const f32x4*)(gq + 4 * lane + 256 * j);
	s_mov_b32 s56, s63
	s_mul_i32 s60, s56, 0x9000
	s_add_u32 s60, s60, 0x3185000
	s_add_u32 s0, s92, s60
	s_addc_u32 s1, s93, 0
	global_load_dwordx4 v[160:163], v0, s[0:1]
	global_load_dwordx4 v[164:167], v0, s[0:1] offset:1024
	global_load_dwordx4 v[168:171], v0, s[0:1] offset:2048
	global_load_dwordx4 v[172:175], v0, s[0:1] offset:3072
	s_add_u32 s0, s22, 0x1000
	s_addc_u32 s1, s23, 0
	global_load_dwordx4 v[176:179], v0, s[0:1]
	global_load_dwordx4 v[180:183], v0, s[0:1] offset:1024
	global_load_dwordx4 v[184:187], v0, s[0:1] offset:2048
	global_load_dwordx4 v[188:191], v0, s[0:1] offset:3072
	s_add_u32 s0, s20, 0x2000
	s_addc_u32 s1, s21, 0
	global_load_dwordx4 v[192:195], v0, s[0:1]
	global_load_dwordx4 v[196:199], v0, s[0:1] offset:1024
	global_load_dwordx4 v[200:203], v0, s[0:1] offset:2048
	global_load_dwordx4 v[204:207], v0, s[0:1] offset:3072
	s_mul_i32 s60, s56, 0x9000
	s_add_u32 s60, s60, 0x3187000
	s_add_u32 s0, s92, s60
	s_addc_u32 s1, s93, 0
	global_load_dwordx4 v[208:211], v0, s[0:1]
	global_load_dwordx4 v[212:215], v0, s[0:1] offset:1024
	global_load_dwordx4 v[216:219], v0, s[0:1] offset:2048
	global_load_dwordx4 v[220:223], v0, s[0:1] offset:3072
	s_mul_i32 s60, s56, 0x9000
	s_add_u32 s60, s60, 0x3186000
	s_add_u32 s0, s92, s60
	s_addc_u32 s1, s93, 0
	global_load_dwordx4 v[224:227], v0, s[0:1]
	global_load_dwordx4 v[228:231], v0, s[0:1] offset:1024
	global_load_dwordx4 v[232:235], v0, s[0:1] offset:2048
	global_load_dwordx4 v[236:239], v0, s[0:1] offset:3072
	s_waitcnt vmcnt(0)
	v_pk_add_f32 v[208:209], v[208:209], 1.0 op_sel_hi:[1,0]
	v_pk_add_f32 v[210:211], v[210:211], 1.0 op_sel_hi:[1,0]
	v_pk_add_f32 v[212:213], v[212:213], 1.0 op_sel_hi:[1,0]
	v_pk_add_f32 v[214:215], v[214:215], 1.0 op_sel_hi:[1,0]
	v_pk_add_f32 v[216:217], v[216:217], 1.0 op_sel_hi:[1,0]
	v_pk_add_f32 v[218:219], v[218:219], 1.0 op_sel_hi:[1,0]
	v_pk_add_f32 v[220:221], v[220:221], 1.0 op_sel_hi:[1,0]
	v_pk_add_f32 v[222:223], v[222:223], 1.0 op_sel_hi:[1,0]
.Lrp12_pk7:
	s_waitcnt vmcnt(12)
	v_lshlrev_b32_e32 v112, 16, v52
	v_and_b32_e32 v113, 0xffff0000, v52
	v_lshlrev_b32_e32 v114, 16, v53
	v_and_b32_e32 v115, 0xffff0000, v53
	v_lshlrev_b32_e32 v116, 16, v54
	v_and_b32_e32 v117, 0xffff0000, v54
	v_lshlrev_b32_e32 v118, 16, v55
	v_and_b32_e32 v119, 0xffff0000, v55
	v_lshlrev_b32_e32 v120, 16, v56
	v_and_b32_e32 v121, 0xffff0000, v56
	v_lshlrev_b32_e32 v122, 16, v57
	v_and_b32_e32 v123, 0xffff0000, v57
	v_lshlrev_b32_e32 v124, 16, v58
	v_and_b32_e32 v125, 0xffff0000, v58
	v_lshlrev_b32_e32 v100, 16, v59
	v_and_b32_e32 v101, 0xffff0000, v59
	v_pk_mul_f32 v[102:103], v[112:113], v[112:113]
	v_pk_mul_f32 v[106:107], v[114:115], v[114:115]
	v_pk_fma_f32 v[102:103], v[116:117], v[116:117], v[102:103]
	v_pk_fma_f32 v[106:107], v[118:119], v[118:119], v[106:107]
	v_pk_fma_f32 v[102:103], v[120:121], v[120:121], v[102:103]
	v_pk_fma_f32 v[106:107], v[122:123], v[122:123], v[106:107]
	v_pk_fma_f32 v[102:103], v[124:125], v[124:125], v[102:103]
	v_pk_fma_f32 v[106:107], v[100:101], v[100:101], v[106:107]
	s_nop 0
	v_pk_add_f32 v[102:103], v[102:103], v[106:107]
	s_nop 0
	v_add_f32_e32 v102, v102, v103
	s_nop 1
	v_add_f32_dpp v102, v102, v102 quad_perm:[1,0,3,2] row_mask:0xf bank_mask:0xf
	s_nop 1
	v_add_f32_dpp v102, v102, v102 quad_perm:[2,3,0,1] row_mask:0xf bank_mask:0xf
	s_nop 1
	v_add_f32_dpp v102, v102, v102 row_half_mirror row_mask:0xf bank_mask:0xf
	s_nop 1
	v_add_f32_dpp v102, v102, v102 row_mirror row_mask:0xf bank_mask:0xf
	s_nop 1
	v_add_f32_dpp v102, v102, v102 row_bcast:15 row_mask:0xa bank_mask:0xf
	s_nop 1
	v_add_f32_dpp v102, v102, v102 row_bcast:31 row_mask:0xc bank_mask:0xf
	s_nop 1
	v_readlane_b32 s74, v102, 63
	s_nop 2
	v_mov_b32_e32 v102, s74
	v_fmamk_f32 v102, v102, 0x3a800000, v2
	v_mul_f32_e32 v103, 0x4f800000, v102
	v_cmp_gt_f32_e32 vcc, 0xf800000, v102
	s_nop 1
	v_cndmask_b32_e32 v102, v102, v103, vcc
	v_sqrt_f32_e32 v103, v102
	s_nop 0
	v_add_u32_e32 v104, -1, v103
	v_add_u32_e32 v106, 1, v103
	v_fma_f32 v107, -v104, v103, v102
	v_fma_f32 v108, -v106, v103, v102
	v_cmp_ge_f32_e64 s[76:77], 0, v107
	s_nop 1
	v_cndmask_b32_e64 v103, v103, v104, s[76:77]
	v_cmp_lt_f32_e64 s[76:77], 0, v108
	s_nop 1
	v_cndmask_b32_e64 v103, v103, v106, s[76:77]
	v_mul_f32_e32 v104, 0x37800000, v103
	v_cndmask_b32_e32 v103, v103, v104, vcc
	v_cmp_class_f32_e32 vcc, v102, v3
	s_nop 1
	v_cndmask_b32_e32 v102, v103, v102, vcc
	v_div_scale_f32 v103, s[76:77], v102, v102, 1.0
	v_rcp_f32_e32 v104, v103
	v_div_scale_f32 v106, vcc, 1.0, v102, 1.0
	v_fma_f32 v107, -v103, v104, 1.0
	v_fmac_f32_e32 v104, v107, v104
	v_mul_f32_e32 v107, v106, v104
	v_fma_f32 v108, -v103, v107, v106
	v_fmac_f32_e32 v107, v108, v104
	v_fma_f32 v103, -v103, v107, v106
	v_div_fmas_f32 v103, v103, v104, v107
	v_div_fixup_f32 v110, v103, v102, 1.0
	v_pk_mul_f32 v[112:113], v[112:113], v[110:111] op_sel_hi:[1,0]
	v_pk_mul_f32 v[114:115], v[114:115], v[110:111] op_sel_hi:[1,0]
	v_pk_mul_f32 v[116:117], v[116:117], v[110:111] op_sel_hi:[1,0]
	v_pk_mul_f32 v[118:119], v[118:119], v[110:111] op_sel_hi:[1,0]
	v_pk_mul_f32 v[120:121], v[120:121], v[110:111] op_sel_hi:[1,0]
	v_pk_mul_f32 v[122:123], v[122:123], v[110:111] op_sel_hi:[1,0]
	v_pk_mul_f32 v[124:125], v[124:125], v[110:111] op_sel_hi:[1,0]
; __device__ __forceinline__ unsigned pk_bf16(float lo, float hi) { const f32x2 v = {lo, hi}; const bf16x2_t b = __builtin_convertvector(v, bf16x2_t); return __builtin_bit_cast(unsigned, b); }
; template <bool HAS_F, bool HAS_H>
; __device__ __forceinline__ void phase_rows(const Params& p, int sp, int sn, float resw, bool from_input, bool write_x = true) {
;     ...
;             const float rs = 1.0f / sqrtf(wave_sum(ss) * (1.0f / D) + EPS) * resw;
;             const float* gate = mod + b * 9216 + sp * 3072 + 2048; const float* gp = p.in[7] + sp * D;
; #pragma unroll
;             for (int j = 0; j < 4; ++j) { const f32x4 g = *(const f32x4*)(gate + 4 * lane + 256 * j), q = *(const f32x4*)(gp + 4 * lane + 256 * j);
;                 v[j] = v[j] + g * (f[j] * rs * q);
;                 if (write_x) *(f32x4*)(p.out + (size_t)row * D + 4 * lane + 256 * j) = v[j]; }
;         }
;         if (HAS_H) {
;             float ss = 0.f;
; #pragma unroll
;             for (int j = 0; j < 4; ++j) ss += (v[j].x * v[j].x + v[j].y * v[j].y) + (v[j].z * v[j].z + v[j].w * v[j].w);
;             const float rs = 1.0f / sqrtf(wave_sum(ss) * (1.0f / D) + EPS);
;             const float* sh = mod + b * 9216 + sn * 3072; const float* scl = sh + 1024; const float* gq = p.in[6] + sn * D;
; #pragma unroll
;             for (int j = 0; j < 4; ++j) { const f32x4 a = *(const f32x4*)(sh + 4 * lane + 256 * j), s = *(const f32x4*)(scl + 4 * lane + 256 * j), q = *(const f32x4*)(gq + 4 * lane + 256 * j);
;                 const f32x4 h = (v[j] * rs * q) * (s + 1.0f) + a;
;                 u32x2 w; w.x = pk_bf16(h.x, h.y); w.y = pk_bf16(h.z, h.w);
;                 *(u32x2*)(H + (size_t)row * D + 4 * lane + 256 * j) = w; }
	v_pk_mul_f32 v[100:101], v[100:101], v[110:111] op_sel_hi:[1,0]
	v_pk_mul_f32 v[112:113], v[176:177], v[112:113]
	v_pk_mul_f32 v[114:115], v[178:179], v[114:115]
	v_pk_mul_f32 v[116:117], v[180:181], v[116:117]
	v_pk_mul_f32 v[118:119], v[182:183], v[118:119]
	v_pk_mul_f32 v[120:121], v[184:185], v[120:121]
	v_pk_mul_f32 v[122:123], v[186:187], v[122:123]
	v_pk_mul_f32 v[124:125], v[188:189], v[124:125]
	v_pk_mul_f32 v[100:101], v[190:191], v[100:101]
	v_pk_fma_f32 v[36:37], v[160:161], v[112:113], v[36:37]
	v_pk_fma_f32 v[38:39], v[162:163], v[114:115], v[38:39]
	v_pk_fma_f32 v[40:41], v[164:165], v[116:117], v[40:41]
	v_pk_fma_f32 v[42:43], v[166:167], v[118:119], v[42:43]
	v_pk_fma_f32 v[44:45], v[168:169], v[120:121], v[44:45]
	v_pk_fma_f32 v[46:47], v[170:171], v[122:123], v[46:47]
	v_pk_fma_f32 v[48:49], v[172:173], v[124:125], v[48:49]
	v_pk_fma_f32 v[50:51], v[174:175], v[100:101], v[50:51]
	v_pk_mul_f32 v[102:103], v[36:37], v[36:37]
	v_pk_mul_f32 v[106:107], v[38:39], v[38:39]
	v_pk_fma_f32 v[102:103], v[40:41], v[40:41], v[102:103]
	v_pk_fma_f32 v[106:107], v[42:43], v[42:43], v[106:107]
	v_pk_fma_f32 v[102:103], v[44:45], v[44:45], v[102:103]
	v_pk_fma_f32 v[106:107], v[46:47], v[46:47], v[106:107]
	v_pk_fma_f32 v[102:103], v[48:49], v[48:49], v[102:103]
	v_pk_fma_f32 v[106:107], v[50:51], v[50:51], v[106:107]
	s_nop 0
	v_pk_add_f32 v[102:103], v[102:103], v[106:107]
	s_nop 0
	v_add_f32_e32 v102, v102, v103
	s_nop 1
	v_add_f32_dpp v102, v102, v102 quad_perm:[1,0,3,2] row_mask:0xf bank_mask:0xf
	s_nop 1
	v_add_f32_dpp v102, v102, v102 quad_perm:[2,3,0,1] row_mask:0xf bank_mask:0xf
	s_nop 1
	v_add_f32_dpp v102, v102, v102 row_half_mirror row_mask:0xf bank_mask:0xf
	s_nop 1
	v_add_f32_dpp v102, v102, v102 row_mirror row_mask:0xf bank_mask:0xf
	s_nop 1
	v_add_f32_dpp v102, v102, v102 row_bcast:15 row_mask:0xa bank_mask:0xf
	s_nop 1
	v_add_f32_dpp v102, v102, v102 row_bcast:31 row_mask:0xc bank_mask:0xf
	s_nop 1
	v_readlane_b32 s74, v102, 63
	s_nop 2
	v_mov_b32_e32 v102, s74
	v_fmamk_f32 v102, v102, 0x3a800000, v2
	v_mul_f32_e32 v103, 0x4f800000, v102
	v_cmp_gt_f32_e32 vcc, 0xf800000, v102
	s_nop 1
	v_cndmask_b32_e32 v102, v102, v103, vcc
	v_sqrt_f32_e32 v103, v102
	s_nop 0
	v_add_u32_e32 v104, -1, v103
	v_add_u32_e32 v106, 1, v103
	v_fma_f32 v107, -v104, v103, v102
	v_fma_f32 v108, -v106, v103, v102
	v_cmp_ge_f32_e64 s[76:77], 0, v107
	s_nop 1
	v_cndmask_b32_e64 v103, v103, v104, s[76:77]
	v_cmp_lt_f32_e64 s[76:77], 0, v108
	s_nop 1
	v_cndmask_b32_e64 v103, v103, v106, s[76:77]
	v_mul_f32_e32 v104, 0x37800000, v103
	v_cndmask_b32_e32 v103, v103, v104, vcc
	v_cmp_class_f32_e32 vcc, v102, v3
	s_nop 1
	v_cndmask_b32_e32 v102, v103, v102, vcc
	v_div_scale_f32 v103, s[76:77], v102, v102, 1.0
	v_rcp_f32_e32 v104, v103
	v_div_scale_f32 v106, vcc, 1.0, v102, 1.0
	v_fma_f32 v107, -v103, v104, 1.0
	v_fmac_f32_e32 v104, v107, v104
	v_mul_f32_e32 v107, v106, v104
	v_fma_f32 v108, -v103, v107, v106
	v_fmac_f32_e32 v107, v108, v104
	v_fma_f32 v103, -v103, v107, v106
	v_div_fmas_f32 v103, v103, v104, v107
	v_div_fixup_f32 v110, v103, v102, 1.0
	s_lshl_b32 s60, s55, 11
	s_add_u32 s70, s78, s60
	s_addc_u32 s71, s79, 0
	v_pk_mul_f32 v[112:113], v[36:37], v[110:111] op_sel_hi:[1,0]
	v_pk_mul_f32 v[114:115], v[38:39], v[110:111] op_sel_hi:[1,0]
	v_pk_mul_f32 v[116:117], v[40:41], v[110:111] op_sel_hi:[1,0]
	v_pk_mul_f32 v[118:119], v[42:43], v[110:111] op_sel_hi:[1,0]
	v_pk_mul_f32 v[120:121], v[44:45], v[110:111] op_sel_hi:[1,0]
	v_pk_mul_f32 v[122:123], v[46:47], v[110:111] op_sel_hi:[1,0]
	v_pk_mul_f32 v[124:125], v[48:49], v[110:111] op_sel_hi:[1,0]
	v_pk_mul_f32 v[100:101], v[50:51], v[110:111] op_sel_hi:[1,0]
	v_pk_mul_f32 v[112:113], v[192:193], v[112:113]
	v_pk_mul_f32 v[114:115], v[194:195], v[114:115]
	v_pk_mul_f32 v[116:117], v[196:197], v[116:117]
	v_pk_mul_f32 v[118:119], v[198:199], v[118:119]
	v_pk_mul_f32 v[120:121], v[200:201], v[120:121]
	v_pk_mul_f32 v[122:123], v[202:203], v[122:123]
	v_pk_mul_f32 v[124:125], v[204:205], v[124:125]
	v_pk_mul_f32 v[100:101], v[206:207], v[100:101]
	v_pk_fma_f32 v[112:113], v[208:209], v[112:113], v[224:225]
	v_pk_fma_f32 v[114:115], v[210:211], v[114:115], v[226:227]
	v_pk_fma_f32 v[116:117], v[212:213], v[116:117], v[228:229]
	v_pk_fma_f32 v[118:119], v[214:215], v[118:119], v[230:231]
	v_pk_fma_f32 v[120:121], v[216:217], v[120:121], v[232:233]
	v_pk_fma_f32 v[122:123], v[218:219], v[122:123], v[234:235]
	v_pk_fma_f32 v[124:125], v[220:221], v[124:125], v[236:237]
	v_pk_fma_f32 v[100:101], v[222:223], v[100:101], v[238:239]
	v_cvt_pk_bf16_f32 v240, v112, v113
	v_cvt_pk_bf16_f32 v241, v114, v115
	v_cvt_pk_bf16_f32 v242, v116, v117
	v_cvt_pk_bf16_f32 v243, v118, v119
	v_cvt_pk_bf16_f32 v244, v120, v121
	v_cvt_pk_bf16_f32 v245, v122, v123
	v_cvt_pk_bf16_f32 v246, v124, v125
	v_cvt_pk_bf16_f32 v247, v100, v101
	global_store_dwordx2 v1, v[240:241], s[70:71]
	global_store_dwordx2 v1, v[242:243], s[70:71] offset:512
	global_store_dwordx2 v1, v[244:245], s[70:71] offset:1024
	global_store_dwordx2 v1, v[246:247], s[70:71] offset:1536
	s_add_u32 s55, s55, 8
	s_cmp_le_u32 s55, s54
	s_cbranch_scc1 .Lrp12_loop3
	s_add_u32 s51, s51, s52
	s_branch .Lrp12_chunk1

; __device__ __forceinline__ float lo_bf(unsigned w) { return __uint_as_float(w << 16); }
; __device__ __forceinline__ float hi_bf(unsigned w) { return __uint_as_float(w & 0xffff0000u); }
; __device__ __forceinline__ void phase_final(const Params& p) {
;     ...
;     for (int row = gw; row < T; row += NGW) {
;         const int b = row_batch(row);
;         f32x4 v[4], m[4], f[4]; float sm = 0.f, sf = 0.f;
; #pragma unroll
;         for (int j = 0; j < 4; ++j) { v[j] = *(const f32x4*)(p.out + (size_t)row * D + 4 * lane + 256 * j);
;             const u32x2 wm = *(const u32x2*)(Fm + (size_t)row * D + 4 * lane + 256 * j), wf = *(const u32x2*)(F2 + (size_t)row * D + 4 * lane + 256 * j);
;             m[j] = (f32x4){lo_bf(wm.x), hi_bf(wm.x), lo_bf(wm.y), hi_bf(wm.y)}; f[j] = (f32x4){lo_bf(wf.x), hi_bf(wf.x), lo_bf(wf.y), hi_bf(wf.y)};
;             sm += (m[j].x * m[j].x + m[j].y * m[j].y) + (m[j].z * m[j].z + m[j].w * m[j].w); sf += (f[j].x * f[j].x + f[j].y * f[j].y) + (f[j].z * f[j].z + f[j].w * f[j].w); }
.Lrp15_chunk1:
	s_mul_i32 s53, s51, 384
	s_cmp_ge_u32 s53, 0x18000
	s_cbranch_scc1 .Lrp15_done2
	s_add_u32 s53, s53, s50
	s_add_u32 s54, s53, 376
	s_mov_b32 s56, -1
	s_mov_b32 s55, s53
	s_add_u32 s57, s53, 0
	s_lshl_b32 s60, s57, 12
	s_add_u32 s64, s84, s60
	s_addc_u32 s65, s85, 0
	s_lshl_b32 s60, s57, 11
	s_add_u32 s66, s82, s60
	s_addc_u32 s67, s83, 0
	s_lshl_b32 s60, s57, 11
	s_add_u32 s68, s78, s60
	s_addc_u32 s69, s79, 0
	global_load_dwordx4 v[4:7], v0, s[64:65] nt
	global_load_dwordx4 v[8:11], v0, s[64:65] offset:1024 nt
	global_load_dwordx4 v[12:15], v0, s[64:65] offset:2048 nt
	global_load_dwordx4 v[16:19], v0, s[64:65] offset:3072 nt
	global_load_dwordx2 v[20:21], v1, s[66:67] nt
	global_load_dwordx2 v[22:23], v1, s[66:67] offset:512 nt
	global_load_dwordx2 v[24:25], v1, s[66:67] offset:1024 nt
	global_load_dwordx2 v[26:27], v1, s[66:67] offset:1536 nt
	global_load_dwordx2 v[28:29], v1, s[68:69] nt
	global_load_dwordx2 v[30:31], v1, s[68:69] offset:512 nt
	global_load_dwordx2 v[32:33], v1, s[68:69] offset:1024 nt
	global_load_dwordx2 v[34:35], v1, s[68:69] offset:1536 nt
	s_add_u32 s57, s55, 8
	s_min_u32 s57, s57, s54
	s_lshl_b32 s60, s57, 12
	s_add_u32 s64, s84, s60
	s_addc_u32 s65, s85, 0
	s_lshl_b32 s60, s57, 11
	s_add_u32 s66, s82, s60
	s_addc_u32 s67, s83, 0
	s_lshl_b32 s60, s57, 11
	s_add_u32 s68, s78, s60
	s_addc_u32 s69, s79, 0
	global_load_dwordx4 v[36:39], v0, s[64:65] nt
	global_load_dwordx4 v[40:43], v0, s[64:65] offset:1024 nt
	global_load_dwordx4 v[44:47], v0, s[64:65] offset:2048 nt
	global_load_dwordx4 v[48:51], v0, s[64:65] offset:3072 nt
	global_load_dwordx2 v[52:53], v1, s[66:67] nt
	global_load_dwordx2 v[54:55], v1, s[66:67] offset:512 nt
	global_load_dwordx2 v[56:57], v1, s[66:67] offset:1024 nt
	global_load_dwordx2 v[58:59], v1, s[66:67] offset:1536 nt
	global_load_dwordx2 v[60:61], v1, s[68:69] nt
	global_load_dwordx2 v[62:63], v1, s[68:69] offset:512 nt
	global_load_dwordx2 v[64:65], v1, s[68:69] offset:1024 nt
	global_load_dwordx2 v[66:67], v1, s[68:69] offset:1536 nt
	s_lshr_b32 s60, s55, 11
	s_sub_u32 s61, s55, 0x8000
	s_lshr_b32 s61, s61, 12
	s_add_u32 s61, s61, 16
	s_cmp_lt_u32 s55, 0x8000
	s_cselect_b32 s63, s60, s61
	s_cmp_eq_u32 s63, s56
	s_cbranch_scc1 .Lrp15_pk4
	s_mov_b32 s56, s63
	s_mul_i32 s60, s56, 0x9000
	s_add_u32 s60, s60, 0x3185000
	s_add_u32 s0, s92, s60
	s_addc_u32 s1, s93, 0
	global_load_dwordx4 v[160:163], v0, s[0:1]
	global_load_dwordx4 v[164:167], v0, s[0:1] offset:1024
	global_load_dwordx4 v[168:171], v0, s[0:1] offset:2048
	global_load_dwordx4 v[172:175], v0, s[0:1] offset:3072
	s_add_u32 s0, s22, 0x1000
	s_addc_u32 s1, s23, 0
	global_load_dwordx4 v[176:179], v0, s[0:1]
	global_load_dwordx4 v[180:183], v0, s[0:1] offset:1024
	global_load_dwordx4 v[184:187], v0, s[0:1] offset:2048
	global_load_dwordx4 v[188:191], v0, s[0:1] offset:3072
	s_mul_i32 s60, s56, 0x9000
	s_add_u32 s60, s60, 0x3188000
	s_add_u32 s0, s92, s60
	s_addc_u32 s1, s93, 0
	global_load_dwordx4 v[192:195], v0, s[0:1]
	global_load_dwordx4 v[196:199], v0, s[0:1] offset:1024
	global_load_dwordx4 v[200:203], v0, s[0:1] offset:2048
	global_load_dwordx4 v[204:207], v0, s[0:1] offset:3072
	s_add_u32 s0, s22, 0x2000
	s_addc_u32 s1, s23, 0
	global_load_dwordx4 v[208:211], v0, s[0:1]
	global_load_dwordx4 v[212:215], v0, s[0:1] offset:1024
	global_load_dwordx4 v[216:219], v0, s[0:1] offset:2048
	global_load_dwordx4 v[220:223], v0, s[0:1] offset:3072
	s_waitcnt vmcnt(0)
.Lrp15_pk4:
	s_waitcnt vmcnt(12)
	v_lshlrev_b32_e32 v112, 16, v20
	v_and_b32_e32 v113, 0xffff0000, v20
	v_lshlrev_b32_e32 v114, 16, v21
	v_and_b32_e32 v115, 0xffff0000, v21
	v_lshlrev_b32_e32 v116, 16, v22
	v_and_b32_e32 v117, 0xffff0000, v22
	v_lshlrev_b32_e32 v118, 16, v23
	v_and_b32_e32 v119, 0xffff0000, v23
	v_lshlrev_b32_e32 v120, 16, v24
	v_and_b32_e32 v121, 0xffff0000, v24
	v_lshlrev_b32_e32 v122, 16, v25
	v_and_b32_e32 v123, 0xffff0000, v25
	v_lshlrev_b32_e32 v124, 16, v26
	v_and_b32_e32 v125, 0xffff0000, v26
	v_lshlrev_b32_e32 v100, 16, v27
	v_and_b32_e32 v101, 0xffff0000, v27
	v_pk_mul_f32 v[102:103], v[112:113], v[112:113]
	v_pk_mul_f32 v[106:107], v[114:115], v[114:115]
	v_pk_fma_f32 v[102:103], v[116:117], v[116:117], v[102:103]
	v_pk_fma_f32 v[106:107], v[118:119], v[118:119], v[106:107]
	v_pk_fma_f32 v[102:103], v[120:121], v[120:121], v[102:103]
	v_pk_fma_f32 v[106:107], v[122:123], v[122:123], v[106:107]
	v_pk_fma_f32 v[102:103], v[124:125], v[124:125], v[102:103]
	v_pk_fma_f32 v[106:107], v[100:101], v[100:101], v[106:107]
	s_nop 0
	v_pk_add_f32 v[102:103], v[102:103], v[106:107]
	s_nop 0
	v_add_f32_e32 v102, v102, v103
	v_mov_b32_e32 v104, v102
	v_lshlrev_b32_e32 v112, 16, v28
	v_and_b32_e32 v113, 0xffff0000, v28
	v_lshlrev_b32_e32 v114, 16, v29
	v_and_b32_e32 v115, 0xffff0000, v29
	v_lshlrev_b32_e32 v116, 16, v30
	v_and_b32_e32 v117, 0xffff0000, v30
	v_lshlrev_b32_e32 v118, 16, v31
	v_and_b32_e32 v119, 0xffff0000, v31
	v_lshlrev_b32_e32 v120, 16, v32
	v_and_b32_e32 v121, 0xffff0000, v32
	v_lshlrev_b32_e32 v122, 16, v33
	v_and_b32_e32 v123, 0xffff0000, v33
	v_lshlrev_b32_e32 v124, 16, v34
	v_and_b32_e32 v125, 0xffff0000, v34
	v_lshlrev_b32_e32 v100, 16, v35
	v_and_b32_e32 v101, 0xffff0000, v35
	v_pk_mul_f32 v[102:103], v[112:113], v[112:113]
	v_pk_mul_f32 v[106:107], v[114:115], v[114:115]
	v_pk_fma_f32 v[102:103], v[116:117], v[116:117], v[102:103]
	v_pk_fma_f32 v[106:107], v[118:119], v[118:119], v[106:107]
	v_pk_fma_f32 v[102:103], v[120:121], v[120:121], v[102:103]
	v_pk_fma_f32 v[106:107], v[122:123], v[122:123], v[106:107]
	v_pk_fma_f32 v[102:103], v[124:125], v[124:125], v[102:103]
	v_pk_fma_f32 v[106:107], v[100:101], v[100:101], v[106:107]
; __device__ __forceinline__ void phase_final(const Params& p) {
;     ...
;         const float rm = 1.0f / sqrtf(wave_sum(sm) * (1.0f / D) + EPS), rf = 1.0f / sqrtf(wave_sum(sf) * (1.0f / D) + EPS) * 0.5f;
;         const float* g1 = mod + b * 9216 + 1 * 3072 + 2048; const float* g2 = mod + b * 9216 + 2 * 3072 + 2048;
;         const float* q1 = p.in[7] + 1 * D; const float* q2 = p.in[7] + 2 * D;
; #pragma unroll
;         for (int j = 0; j < 4; ++j) { const int c = 4 * lane + 256 * j;
;             const f32x4 x2 = v[j] + *(const f32x4*)(g1 + c) * (m[j] * rm * *(const f32x4*)(q1 + c));
;             *(f32x4*)(p.out + (size_t)row * D + c) = x2 + *(const f32x4*)(g2 + c) * (f[j] * rf * *(const f32x4*)(q2 + c)); }
	s_nop 0
	v_pk_add_f32 v[102:103], v[102:103], v[106:107]
	s_nop 0
	v_add_f32_e32 v102, v102, v103
	s_nop 1
	v_add_f32_dpp v104, v104, v104 quad_perm:[1,0,3,2] row_mask:0xf bank_mask:0xf
	v_add_f32_dpp v102, v102, v102 quad_perm:[1,0,3,2] row_mask:0xf bank_mask:0xf
	s_nop 1
	v_add_f32_dpp v104, v104, v104 quad_perm:[2,3,0,1] row_mask:0xf bank_mask:0xf
	v_add_f32_dpp v102, v102, v102 quad_perm:[2,3,0,1] row_mask:0xf bank_mask:0xf
	s_nop 1
	v_add_f32_dpp v104, v104, v104 row_half_mirror row_mask:0xf bank_mask:0xf
	v_add_f32_dpp v102, v102, v102 row_half_mirror row_mask:0xf bank_mask:0xf
	s_nop 1
	v_add_f32_dpp v104, v104, v104 row_mirror row_mask:0xf bank_mask:0xf
	v_add_f32_dpp v102, v102, v102 row_mirror row_mask:0xf bank_mask:0xf
	s_nop 1
	v_add_f32_dpp v104, v104, v104 row_bcast:15 row_mask:0xa bank_mask:0xf
	v_add_f32_dpp v102, v102, v102 row_bcast:15 row_mask:0xa bank_mask:0xf
	s_nop 1
	v_add_f32_dpp v104, v104, v104 row_bcast:31 row_mask:0xc bank_mask:0xf
	v_add_f32_dpp v102, v102, v102 row_bcast:31 row_mask:0xc bank_mask:0xf
	s_nop 1
	v_readlane_b32 s74, v104, 63
	v_readlane_b32 s75, v102, 63
	s_nop 2
	v_mov_b32_e32 v102, s74
	v_fmamk_f32 v102, v102, 0x3a800000, v2
	v_mul_f32_e32 v103, 0x4f800000, v102
	v_cmp_gt_f32_e32 vcc, 0xf800000, v102
	s_nop 1
	v_cndmask_b32_e32 v102, v102, v103, vcc
	v_sqrt_f32_e32 v103, v102
	s_nop 0
	v_add_u32_e32 v104, -1, v103
	v_add_u32_e32 v106, 1, v103
	v_fma_f32 v107, -v104, v103, v102
	v_fma_f32 v108, -v106, v103, v102
	v_cmp_ge_f32_e64 s[76:77], 0, v107
	s_nop 1
	v_cndmask_b32_e64 v103, v103, v104, s[76:77]
	v_cmp_lt_f32_e64 s[76:77], 0, v108
	s_nop 1
	v_cndmask_b32_e64 v103, v103, v106, s[76:77]
	v_mul_f32_e32 v104, 0x37800000, v103
	v_cndmask_b32_e32 v103, v103, v104, vcc
	v_cmp_class_f32_e32 vcc, v102, v3
	s_nop 1
	v_cndmask_b32_e32 v102, v103, v102, vcc
	v_div_scale_f32 v103, s[76:77], v102, v102, 1.0
	v_rcp_f32_e32 v104, v103
	v_div_scale_f32 v106, vcc, 1.0, v102, 1.0
	v_fma_f32 v107, -v103, v104, 1.0
	v_fmac_f32_e32 v104, v107, v104
	v_mul_f32_e32 v107, v106, v104
	v_fma_f32 v108, -v103, v107, v106
	v_fmac_f32_e32 v107, v108, v104
	v_fma_f32 v103, -v103, v107, v106
	v_div_fmas_f32 v103, v103, v104, v107
	v_div_fixup_f32 v110, v103, v102, 1.0
	v_mov_b32_e32 v102, s75
	v_fmamk_f32 v102, v102, 0x3a800000, v2
	v_mul_f32_e32 v103, 0x4f800000, v102
	v_cmp_gt_f32_e32 vcc, 0xf800000, v102
	s_nop 1
	v_cndmask_b32_e32 v102, v102, v103, vcc
	v_sqrt_f32_e32 v103, v102
	s_nop 0
	v_add_u32_e32 v104, -1, v103
	v_add_u32_e32 v106, 1, v103
	v_fma_f32 v107, -v104, v103, v102
	v_fma_f32 v108, -v106, v103, v102
	v_cmp_ge_f32_e64 s[76:77], 0, v107
	s_nop 1
	v_cndmask_b32_e64 v103, v103, v104, s[76:77]
	v_cmp_lt_f32_e64 s[76:77], 0, v108
	s_nop 1
	v_cndmask_b32_e64 v103, v103, v106, s[76:77]
	v_mul_f32_e32 v104, 0x37800000, v103
	v_cndmask_b32_e32 v103, v103, v104, vcc
	v_cmp_class_f32_e32 vcc, v102, v3
	s_nop 1
	v_cndmask_b32_e32 v102, v103, v102, vcc
	v_div_scale_f32 v103, s[76:77], v102, v102, 1.0
	v_rcp_f32_e32 v104, v103
	v_div_scale_f32 v106, vcc, 1.0, v102, 1.0
	v_fma_f32 v107, -v103, v104, 1.0
	v_fmac_f32_e32 v104, v107, v104
	v_mul_f32_e32 v107, v106, v104
	v_fma_f32 v108, -v103, v107, v106
	v_fmac_f32_e32 v107, v108, v104
	v_fma_f32 v103, -v103, v107, v106
	v_div_fmas_f32 v103, v103, v104, v107
	v_div_fixup_f32 v108, v103, v102, 1.0
	v_mul_f32_e32 v108, 0.5, v108
	v_pk_mul_f32 v[112:113], v[112:113], v[108:109] op_sel_hi:[1,0]
	v_pk_mul_f32 v[114:115], v[114:115], v[108:109] op_sel_hi:[1,0]
	v_pk_mul_f32 v[116:117], v[116:117], v[108:109] op_sel_hi:[1,0]
	v_pk_mul_f32 v[118:119], v[118:119], v[108:109] op_sel_hi:[1,0]
	v_pk_mul_f32 v[120:121], v[120:121], v[108:109] op_sel_hi:[1,0]
	v_pk_mul_f32 v[122:123], v[122:123], v[108:109] op_sel_hi:[1,0]
	v_pk_mul_f32 v[124:125], v[124:125], v[108:109] op_sel_hi:[1,0]
	v_pk_mul_f32 v[100:101], v[100:101], v[108:109] op_sel_hi:[1,0]
	v_pk_mul_f32 v[112:113], v[112:113], v[208:209]
	v_pk_mul_f32 v[114:115], v[114:115], v[210:211]
	v_pk_mul_f32 v[116:117], v[116:117], v[212:213]
	v_pk_mul_f32 v[118:119], v[118:119], v[214:215]
	v_pk_mul_f32 v[120:121], v[120:121], v[216:217]
	v_pk_mul_f32 v[122:123], v[122:123], v[218:219]
	v_pk_mul_f32 v[124:125], v[124:125], v[220:221]
	v_pk_mul_f32 v[100:101], v[100:101], v[222:223]
	v_lshlrev_b32_e32 v28, 16, v20
	v_and_b32_e32 v29, 0xffff0000, v20
	v_lshlrev_b32_e32 v30, 16, v21
	v_and_b32_e32 v31, 0xffff0000, v21
	v_lshlrev_b32_e32 v32, 16, v22
	v_and_b32_e32 v33, 0xffff0000, v22
	v_lshlrev_b32_e32 v34, 16, v23
	v_and_b32_e32 v35, 0xffff0000, v23
	v_lshlrev_b32_e32 v240, 16, v24
	v_and_b32_e32 v241, 0xffff0000, v24
	v_lshlrev_b32_e32 v242, 16, v25
	v_and_b32_e32 v243, 0xffff0000, v25
	v_lshlrev_b32_e32 v244, 16, v26
	v_and_b32_e32 v245, 0xffff0000, v26
	v_lshlrev_b32_e32 v246, 16, v27
	v_and_b32_e32 v247, 0xffff0000, v27
	v_pk_mul_f32 v[28:29], v[28:29], v[110:111] op_sel_hi:[1,0]
	v_pk_mul_f32 v[30:31], v[30:31], v[110:111] op_sel_hi:[1,0]
	v_pk_mul_f32 v[32:33], v[32:33], v[110:111] op_sel_hi:[1,0]
	v_pk_mul_f32 v[34:35], v[34:35], v[110:111] op_sel_hi:[1,0]
	v_pk_mul_f32 v[240:241], v[240:241], v[110:111] op_sel_hi:[1,0]
	v_pk_mul_f32 v[242:243], v[242:243], v[110:111] op_sel_hi:[1,0]
	v_pk_mul_f32 v[244:245], v[244:245], v[110:111] op_sel_hi:[1,0]
	v_pk_mul_f32 v[246:247], v[246:247], v[110:111] op_sel_hi:[1,0]
	v_pk_mul_f32 v[28:29], v[28:29], v[176:177]
	v_pk_mul_f32 v[30:31], v[30:31], v[178:179]
	v_pk_mul_f32 v[32:33], v[32:33], v[180:181]
	v_pk_mul_f32 v[34:35], v[34:35], v[182:183]
	v_pk_mul_f32 v[240:241], v[240:241], v[184:185]
	v_pk_mul_f32 v[242:243], v[242:243], v[186:187]
	v_pk_mul_f32 v[244:245], v[244:245], v[188:189]
; __device__ __forceinline__ float lo_bf(unsigned w) { return __uint_as_float(w << 16); }
; __device__ __forceinline__ float hi_bf(unsigned w) { return __uint_as_float(w & 0xffff0000u); }
; __device__ __forceinline__ void phase_final(const Params& p) {
;     ...
;     for (int row = gw; row < T; row += NGW) {
;         const int b = row_batch(row);
;         f32x4 v[4], m[4], f[4]; float sm = 0.f, sf = 0.f;
; #pragma unroll
;         for (int j = 0; j < 4; ++j) { v[j] = *(const f32x4*)(p.out + (size_t)row * D + 4 * lane + 256 * j);
;             const u32x2 wm = *(const u32x2*)(Fm + (size_t)row * D + 4 * lane + 256 * j), wf = *(const u32x2*)(F2 + (size_t)row * D + 4 * lane + 256 * j);
;             m[j] = (f32x4){lo_bf(wm.x), hi_bf(wm.x), lo_bf(wm.y), hi_bf(wm.y)}; f[j] = (f32x4){lo_bf(wf.x), hi_bf(wf.x), lo_bf(wf.y), hi_bf(wf.y)};
;             sm += (m[j].x * m[j].x + m[j].y * m[j].y) + (m[j].z * m[j].z + m[j].w * m[j].w); sf += (f[j].x * f[j].x + f[j].y * f[j].y) + (f[j].z * f[j].z + f[j].w * f[j].w); }
;     ...
;         for (int j = 0; j < 4; ++j) { const int c = 4 * lane + 256 * j;
;             const f32x4 x2 = v[j] + *(const f32x4*)(g1 + c) * (m[j] * rm * *(const f32x4*)(q1 + c));
;             *(f32x4*)(p.out + (size_t)row * D + c) = x2 + *(const f32x4*)(g2 + c) * (f[j] * rf * *(const f32x4*)(q2 + c)); }
	v_pk_mul_f32 v[246:247], v[246:247], v[190:191]
	v_pk_fma_f32 v[4:5], v[160:161], v[28:29], v[4:5]
	v_pk_fma_f32 v[6:7], v[162:163], v[30:31], v[6:7]
	v_pk_fma_f32 v[8:9], v[164:165], v[32:33], v[8:9]
	v_pk_fma_f32 v[10:11], v[166:167], v[34:35], v[10:11]
	v_pk_fma_f32 v[12:13], v[168:169], v[240:241], v[12:13]
	v_pk_fma_f32 v[14:15], v[170:171], v[242:243], v[14:15]
	v_pk_fma_f32 v[16:17], v[172:173], v[244:245], v[16:17]
	v_pk_fma_f32 v[18:19], v[174:175], v[246:247], v[18:19]
	v_pk_fma_f32 v[4:5], v[192:193], v[112:113], v[4:5]
	v_pk_fma_f32 v[6:7], v[194:195], v[114:115], v[6:7]
	v_pk_fma_f32 v[8:9], v[196:197], v[116:117], v[8:9]
	v_pk_fma_f32 v[10:11], v[198:199], v[118:119], v[10:11]
	v_pk_fma_f32 v[12:13], v[200:201], v[120:121], v[12:13]
	v_pk_fma_f32 v[14:15], v[202:203], v[122:123], v[14:15]
	v_pk_fma_f32 v[16:17], v[204:205], v[124:125], v[16:17]
	v_pk_fma_f32 v[18:19], v[206:207], v[100:101], v[18:19]
	s_lshl_b32 s60, s55, 12
	s_add_u32 s72, s84, s60
	s_addc_u32 s73, s85, 0
	global_store_dwordx4 v0, v[4:7], s[72:73] sc1
	global_store_dwordx4 v0, v[8:11], s[72:73] offset:1024 sc1
	global_store_dwordx4 v0, v[12:15], s[72:73] offset:2048 sc1
	global_store_dwordx4 v0, v[16:19], s[72:73] offset:3072 sc1
	s_add_u32 s55, s55, 8
	s_add_u32 s57, s55, 8
	s_min_u32 s57, s57, s54
	s_lshl_b32 s60, s57, 12
	s_add_u32 s64, s84, s60
	s_addc_u32 s65, s85, 0
	s_lshl_b32 s60, s57, 11
	s_add_u32 s66, s82, s60
	s_addc_u32 s67, s83, 0
	s_lshl_b32 s60, s57, 11
	s_add_u32 s68, s78, s60
	s_addc_u32 s69, s79, 0
	global_load_dwordx4 v[4:7], v0, s[64:65] nt
	global_load_dwordx4 v[8:11], v0, s[64:65] offset:1024 nt
	global_load_dwordx4 v[12:15], v0, s[64:65] offset:2048 nt
	global_load_dwordx4 v[16:19], v0, s[64:65] offset:3072 nt
	global_load_dwordx2 v[20:21], v1, s[66:67] nt
	global_load_dwordx2 v[22:23], v1, s[66:67] offset:512 nt
	global_load_dwordx2 v[24:25], v1, s[66:67] offset:1024 nt
	global_load_dwordx2 v[26:27], v1, s[66:67] offset:1536 nt
	global_load_dwordx2 v[28:29], v1, s[68:69] nt
	global_load_dwordx2 v[30:31], v1, s[68:69] offset:512 nt
	global_load_dwordx2 v[32:33], v1, s[68:69] offset:1024 nt
	global_load_dwordx2 v[34:35], v1, s[68:69] offset:1536 nt
	s_lshr_b32 s60, s55, 11
	s_sub_u32 s61, s55, 0x8000
	s_lshr_b32 s61, s61, 12
	s_add_u32 s61, s61, 16
	s_cmp_lt_u32 s55, 0x8000
	s_cselect_b32 s63, s60, s61
	s_cmp_eq_u32 s63, s56
	s_cbranch_scc1 .Lrp15_pk5
	s_mov_b32 s56, s63
	s_mul_i32 s60, s56, 0x9000
	s_add_u32 s60, s60, 0x3185000
	s_add_u32 s0, s92, s60
	s_addc_u32 s1, s93, 0
	global_load_dwordx4 v[160:163], v0, s[0:1]
	global_load_dwordx4 v[164:167], v0, s[0:1] offset:1024
	global_load_dwordx4 v[168:171], v0, s[0:1] offset:2048
	global_load_dwordx4 v[172:175], v0, s[0:1] offset:3072
	s_add_u32 s0, s22, 0x1000
	s_addc_u32 s1, s23, 0
	global_load_dwordx4 v[176:179], v0, s[0:1]
	global_load_dwordx4 v[180:183], v0, s[0:1] offset:1024
	global_load_dwordx4 v[184:187], v0, s[0:1] offset:2048
	global_load_dwordx4 v[188:191], v0, s[0:1] offset:3072
	s_mul_i32 s60, s56, 0x9000
	s_add_u32 s60, s60, 0x3188000
	s_add_u32 s0, s92, s60
	s_addc_u32 s1, s93, 0
	global_load_dwordx4 v[192:195], v0, s[0:1]
	global_load_dwordx4 v[196:199], v0, s[0:1] offset:1024
	global_load_dwordx4 v[200:203], v0, s[0:1] offset:2048
	global_load_dwordx4 v[204:207], v0, s[0:1] offset:3072
	s_add_u32 s0, s22, 0x2000
	s_addc_u32 s1, s23, 0
	global_load_dwordx4 v[208:211], v0, s[0:1]
	global_load_dwordx4 v[212:215], v0, s[0:1] offset:1024
	global_load_dwordx4 v[216:219], v0, s[0:1] offset:2048
	global_load_dwordx4 v[220:223], v0, s[0:1] offset:3072
	s_waitcnt vmcnt(0)
.Lrp15_pk5:
	s_waitcnt vmcnt(16)
	v_lshlrev_b32_e32 v112, 16, v52
	v_and_b32_e32 v113, 0xffff0000, v52
	v_lshlrev_b32_e32 v114, 16, v53
	v_and_b32_e32 v115, 0xffff0000, v53
	v_lshlrev_b32_e32 v116, 16, v54
	v_and_b32_e32 v117, 0xffff0000, v54
	v_lshlrev_b32_e32 v118, 16, v55
	v_and_b32_e32 v119, 0xffff0000, v55
	v_lshlrev_b32_e32 v120, 16, v56
	v_and_b32_e32 v121, 0xffff0000, v56
	v_lshlrev_b32_e32 v122, 16, v57
	v_and_b32_e32 v123, 0xffff0000, v57
	v_lshlrev_b32_e32 v124, 16, v58
	v_and_b32_e32 v125, 0xffff0000, v58
	v_lshlrev_b32_e32 v100, 16, v59
	v_and_b32_e32 v101, 0xffff0000, v59
	v_pk_mul_f32 v[102:103], v[112:113], v[112:113]
	v_pk_mul_f32 v[106:107], v[114:115], v[114:115]
	v_pk_fma_f32 v[102:103], v[116:117], v[116:117], v[102:103]
	v_pk_fma_f32 v[106:107], v[118:119], v[118:119], v[106:107]
	v_pk_fma_f32 v[102:103], v[120:121], v[120:121], v[102:103]
	v_pk_fma_f32 v[106:107], v[122:123], v[122:123], v[106:107]
	v_pk_fma_f32 v[102:103], v[124:125], v[124:125], v[102:103]
	v_pk_fma_f32 v[106:107], v[100:101], v[100:101], v[106:107]
	s_nop 0
	v_pk_add_f32 v[102:103], v[102:103], v[106:107]
	s_nop 0
	v_add_f32_e32 v102, v102, v103
	v_mov_b32_e32 v104, v102
	v_lshlrev_b32_e32 v112, 16, v60
	v_and_b32_e32 v113, 0xffff0000, v60
	v_lshlrev_b32_e32 v114, 16, v61
	v_and_b32_e32 v115, 0xffff0000, v61
	v_lshlrev_b32_e32 v116, 16, v62
	v_and_b32_e32 v117, 0xffff0000, v62
	v_lshlrev_b32_e32 v118, 16, v63
	v_and_b32_e32 v119, 0xffff0000, v63
	v_lshlrev_b32_e32 v120, 16, v64
	v_and_b32_e32 v121, 0xffff0000, v64
	v_lshlrev_b32_e32 v122, 16, v65
	v_and_b32_e32 v123, 0xffff0000, v65
	v_lshlrev_b32_e32 v124, 16, v66
	v_and_b32_e32 v125, 0xffff0000, v66
	v_lshlrev_b32_e32 v100, 16, v67
	v_and_b32_e32 v101, 0xffff0000, v67
	v_pk_mul_f32 v[102:103], v[112:113], v[112:113]
	v_pk_mul_f32 v[106:107], v[114:115], v[114:115]
	v_pk_fma_f32 v[102:103], v[116:117], v[116:117], v[102:103]
	v_pk_fma_f32 v[106:107], v[118:119], v[118:119], v[106:107]
	v_pk_fma_f32 v[102:103], v[120:121], v[120:121], v[102:103]
; __device__ __forceinline__ void phase_final(const Params& p) {
;     ...
;             sm += (m[j].x * m[j].x + m[j].y * m[j].y) + (m[j].z * m[j].z + m[j].w * m[j].w); sf += (f[j].x * f[j].x + f[j].y * f[j].y) + (f[j].z * f[j].z + f[j].w * f[j].w); }
;         const float rm = 1.0f / sqrtf(wave_sum(sm) * (1.0f / D) + EPS), rf = 1.0f / sqrtf(wave_sum(sf) * (1.0f / D) + EPS) * 0.5f;
;         const float* g1 = mod + b * 9216 + 1 * 3072 + 2048; const float* g2 = mod + b * 9216 + 2 * 3072 + 2048;
;         const float* q1 = p.in[7] + 1 * D; const float* q2 = p.in[7] + 2 * D;
; #pragma unroll
;         for (int j = 0; j < 4; ++j) { const int c = 4 * lane + 256 * j;
;             const f32x4 x2 = v[j] + *(const f32x4*)(g1 + c) * (m[j] * rm * *(const f32x4*)(q1 + c));
	v_pk_fma_f32 v[106:107], v[122:123], v[122:123], v[106:107]
	v_pk_fma_f32 v[102:103], v[124:125], v[124:125], v[102:103]
	v_pk_fma_f32 v[106:107], v[100:101], v[100:101], v[106:107]
	s_nop 0
	v_pk_add_f32 v[102:103], v[102:103], v[106:107]
	s_nop 0
	v_add_f32_e32 v102, v102, v103
	s_nop 1
	v_add_f32_dpp v104, v104, v104 quad_perm:[1,0,3,2] row_mask:0xf bank_mask:0xf
	v_add_f32_dpp v102, v102, v102 quad_perm:[1,0,3,2] row_mask:0xf bank_mask:0xf
	s_nop 1
	v_add_f32_dpp v104, v104, v104 quad_perm:[2,3,0,1] row_mask:0xf bank_mask:0xf
	v_add_f32_dpp v102, v102, v102 quad_perm:[2,3,0,1] row_mask:0xf bank_mask:0xf
	s_nop 1
	v_add_f32_dpp v104, v104, v104 row_half_mirror row_mask:0xf bank_mask:0xf
	v_add_f32_dpp v102, v102, v102 row_half_mirror row_mask:0xf bank_mask:0xf
	s_nop 1
	v_add_f32_dpp v104, v104, v104 row_mirror row_mask:0xf bank_mask:0xf
	v_add_f32_dpp v102, v102, v102 row_mirror row_mask:0xf bank_mask:0xf
	s_nop 1
	v_add_f32_dpp v104, v104, v104 row_bcast:15 row_mask:0xa bank_mask:0xf
	v_add_f32_dpp v102, v102, v102 row_bcast:15 row_mask:0xa bank_mask:0xf
	s_nop 1
	v_add_f32_dpp v104, v104, v104 row_bcast:31 row_mask:0xc bank_mask:0xf
	v_add_f32_dpp v102, v102, v102 row_bcast:31 row_mask:0xc bank_mask:0xf
	s_nop 1
	v_readlane_b32 s74, v104, 63
	v_readlane_b32 s75, v102, 63
	s_nop 2
	v_mov_b32_e32 v102, s74
	v_fmamk_f32 v102, v102, 0x3a800000, v2
	v_mul_f32_e32 v103, 0x4f800000, v102
	v_cmp_gt_f32_e32 vcc, 0xf800000, v102
	s_nop 1
	v_cndmask_b32_e32 v102, v102, v103, vcc
	v_sqrt_f32_e32 v103, v102
	s_nop 0
	v_add_u32_e32 v104, -1, v103
	v_add_u32_e32 v106, 1, v103
	v_fma_f32 v107, -v104, v103, v102
	v_fma_f32 v108, -v106, v103, v102
	v_cmp_ge_f32_e64 s[76:77], 0, v107
	s_nop 1
	v_cndmask_b32_e64 v103, v103, v104, s[76:77]
	v_cmp_lt_f32_e64 s[76:77], 0, v108
	s_nop 1
	v_cndmask_b32_e64 v103, v103, v106, s[76:77]
	v_mul_f32_e32 v104, 0x37800000, v103
	v_cndmask_b32_e32 v103, v103, v104, vcc
	v_cmp_class_f32_e32 vcc, v102, v3
	s_nop 1
	v_cndmask_b32_e32 v102, v103, v102, vcc
	v_div_scale_f32 v103, s[76:77], v102, v102, 1.0
	v_rcp_f32_e32 v104, v103
	v_div_scale_f32 v106, vcc, 1.0, v102, 1.0
	v_fma_f32 v107, -v103, v104, 1.0
	v_fmac_f32_e32 v104, v107, v104
	v_mul_f32_e32 v107, v106, v104
	v_fma_f32 v108, -v103, v107, v106
	v_fmac_f32_e32 v107, v108, v104
	v_fma_f32 v103, -v103, v107, v106
	v_div_fmas_f32 v103, v103, v104, v107
	v_div_fixup_f32 v110, v103, v102, 1.0
	v_mov_b32_e32 v102, s75
	v_fmamk_f32 v102, v102, 0x3a800000, v2
	v_mul_f32_e32 v103, 0x4f800000, v102
	v_cmp_gt_f32_e32 vcc, 0xf800000, v102
	s_nop 1
	v_cndmask_b32_e32 v102, v102, v103, vcc
	v_sqrt_f32_e32 v103, v102
	s_nop 0
	v_add_u32_e32 v104, -1, v103
	v_add_u32_e32 v106, 1, v103
	v_fma_f32 v107, -v104, v103, v102
	v_fma_f32 v108, -v106, v103, v102
	v_cmp_ge_f32_e64 s[76:77], 0, v107
	s_nop 1
	v_cndmask_b32_e64 v103, v103, v104, s[76:77]
	v_cmp_lt_f32_e64 s[76:77], 0, v108
	s_nop 1
	v_cndmask_b32_e64 v103, v103, v106, s[76:77]
	v_mul_f32_e32 v104, 0x37800000, v103
	v_cndmask_b32_e32 v103, v103, v104, vcc
	v_cmp_class_f32_e32 vcc, v102, v3
	s_nop 1
	v_cndmask_b32_e32 v102, v103, v102, vcc
	v_div_scale_f32 v103, s[76:77], v102, v102, 1.0
	v_rcp_f32_e32 v104, v103
	v_div_scale_f32 v106, vcc, 1.0, v102, 1.0
	v_fma_f32 v107, -v103, v104, 1.0
	v_fmac_f32_e32 v104, v107, v104
	v_mul_f32_e32 v107, v106, v104
	v_fma_f32 v108, -v103, v107, v106
	v_fmac_f32_e32 v107, v108, v104
	v_fma_f32 v103, -v103, v107, v106
	v_div_fmas_f32 v103, v103, v104, v107
	v_div_fixup_f32 v108, v103, v102, 1.0
	v_mul_f32_e32 v108, 0.5, v108
	v_pk_mul_f32 v[112:113], v[112:113], v[108:109] op_sel_hi:[1,0]
	v_pk_mul_f32 v[114:115], v[114:115], v[108:109] op_sel_hi:[1,0]
	v_pk_mul_f32 v[116:117], v[116:117], v[108:109] op_sel_hi:[1,0]
	v_pk_mul_f32 v[118:119], v[118:119], v[108:109] op_sel_hi:[1,0]
	v_pk_mul_f32 v[120:121], v[120:121], v[108:109] op_sel_hi:[1,0]
	v_pk_mul_f32 v[122:123], v[122:123], v[108:109] op_sel_hi:[1,0]
	v_pk_mul_f32 v[124:125], v[124:125], v[108:109] op_sel_hi:[1,0]
	v_pk_mul_f32 v[100:101], v[100:101], v[108:109] op_sel_hi:[1,0]
	v_pk_mul_f32 v[112:113], v[112:113], v[208:209]
	v_pk_mul_f32 v[114:115], v[114:115], v[210:211]
	v_pk_mul_f32 v[116:117], v[116:117], v[212:213]
	v_pk_mul_f32 v[118:119], v[118:119], v[214:215]
	v_pk_mul_f32 v[120:121], v[120:121], v[216:217]
	v_pk_mul_f32 v[122:123], v[122:123], v[218:219]
	v_pk_mul_f32 v[124:125], v[124:125], v[220:221]
	v_pk_mul_f32 v[100:101], v[100:101], v[222:223]
	v_lshlrev_b32_e32 v60, 16, v52
	v_and_b32_e32 v61, 0xffff0000, v52
	v_lshlrev_b32_e32 v62, 16, v53
	v_and_b32_e32 v63, 0xffff0000, v53
	v_lshlrev_b32_e32 v64, 16, v54
	v_and_b32_e32 v65, 0xffff0000, v54
	v_lshlrev_b32_e32 v66, 16, v55
	v_and_b32_e32 v67, 0xffff0000, v55
	v_lshlrev_b32_e32 v240, 16, v56
	v_and_b32_e32 v241, 0xffff0000, v56
	v_lshlrev_b32_e32 v242, 16, v57
	v_and_b32_e32 v243, 0xffff0000, v57
	v_lshlrev_b32_e32 v244, 16, v58
	v_and_b32_e32 v245, 0xffff0000, v58
	v_lshlrev_b32_e32 v246, 16, v59
	v_and_b32_e32 v247, 0xffff0000, v59
	v_pk_mul_f32 v[60:61], v[60:61], v[110:111] op_sel_hi:[1,0]
	v_pk_mul_f32 v[62:63], v[62:63], v[110:111] op_sel_hi:[1,0]
	v_pk_mul_f32 v[64:65], v[64:65], v[110:111] op_sel_hi:[1,0]
	v_pk_mul_f32 v[66:67], v[66:67], v[110:111] op_sel_hi:[1,0]
	v_pk_mul_f32 v[240:241], v[240:241], v[110:111] op_sel_hi:[1,0]
	v_pk_mul_f32 v[242:243], v[242:243], v[110:111] op_sel_hi:[1,0]
	v_pk_mul_f32 v[244:245], v[244:245], v[110:111] op_sel_hi:[1,0]
	v_pk_mul_f32 v[246:247], v[246:247], v[110:111] op_sel_hi:[1,0]
	v_pk_mul_f32 v[60:61], v[60:61], v[176:177]
	v_pk_mul_f32 v[62:63], v[62:63], v[178:179]
	v_pk_mul_f32 v[64:65], v[64:65], v[180:181]
; __device__ __forceinline__ float lo_bf(unsigned w) { return __uint_as_float(w << 16); }
; __device__ __forceinline__ float hi_bf(unsigned w) { return __uint_as_float(w & 0xffff0000u); }
; __device__ __forceinline__ void phase_final(const Params& p) {
;     ...
;     for (int row = gw; row < T; row += NGW) {
;         const int b = row_batch(row);
;         f32x4 v[4], m[4], f[4]; float sm = 0.f, sf = 0.f;
; #pragma unroll
;         for (int j = 0; j < 4; ++j) { v[j] = *(const f32x4*)(p.out + (size_t)row * D + 4 * lane + 256 * j);
;             const u32x2 wm = *(const u32x2*)(Fm + (size_t)row * D + 4 * lane + 256 * j), wf = *(const u32x2*)(F2 + (size_t)row * D + 4 * lane + 256 * j);
;             m[j] = (f32x4){lo_bf(wm.x), hi_bf(wm.x), lo_bf(wm.y), hi_bf(wm.y)}; f[j] = (f32x4){lo_bf(wf.x), hi_bf(wf.x), lo_bf(wf.y), hi_bf(wf.y)};
;             sm += (m[j].x * m[j].x + m[j].y * m[j].y) + (m[j].z * m[j].z + m[j].w * m[j].w); sf += (f[j].x * f[j].x + f[j].y * f[j].y) + (f[j].z * f[j].z + f[j].w * f[j].w); }
;     ...
;         for (int j = 0; j < 4; ++j) { const int c = 4 * lane + 256 * j;
;             const f32x4 x2 = v[j] + *(const f32x4*)(g1 + c) * (m[j] * rm * *(const f32x4*)(q1 + c));
;             *(f32x4*)(p.out + (size_t)row * D + c) = x2 + *(const f32x4*)(g2 + c) * (f[j] * rf * *(const f32x4*)(q2 + c)); }
	v_pk_mul_f32 v[66:67], v[66:67], v[182:183]
	v_pk_mul_f32 v[240:241], v[240:241], v[184:185]
	v_pk_mul_f32 v[242:243], v[242:243], v[186:187]
	v_pk_mul_f32 v[244:245], v[244:245], v[188:189]
	v_pk_mul_f32 v[246:247], v[246:247], v[190:191]
	v_pk_fma_f32 v[36:37], v[160:161], v[60:61], v[36:37]
	v_pk_fma_f32 v[38:39], v[162:163], v[62:63], v[38:39]
	v_pk_fma_f32 v[40:41], v[164:165], v[64:65], v[40:41]
	v_pk_fma_f32 v[42:43], v[166:167], v[66:67], v[42:43]
	v_pk_fma_f32 v[44:45], v[168:169], v[240:241], v[44:45]
	v_pk_fma_f32 v[46:47], v[170:171], v[242:243], v[46:47]
	v_pk_fma_f32 v[48:49], v[172:173], v[244:245], v[48:49]
	v_pk_fma_f32 v[50:51], v[174:175], v[246:247], v[50:51]
	v_pk_fma_f32 v[36:37], v[192:193], v[112:113], v[36:37]
	v_pk_fma_f32 v[38:39], v[194:195], v[114:115], v[38:39]
	v_pk_fma_f32 v[40:41], v[196:197], v[116:117], v[40:41]
	v_pk_fma_f32 v[42:43], v[198:199], v[118:119], v[42:43]
	v_pk_fma_f32 v[44:45], v[200:201], v[120:121], v[44:45]
	v_pk_fma_f32 v[46:47], v[202:203], v[122:123], v[46:47]
	v_pk_fma_f32 v[48:49], v[204:205], v[124:125], v[48:49]
	v_pk_fma_f32 v[50:51], v[206:207], v[100:101], v[50:51]
	s_lshl_b32 s60, s55, 12
	s_add_u32 s72, s84, s60
	s_addc_u32 s73, s85, 0
	global_store_dwordx4 v0, v[36:39], s[72:73] sc1
	global_store_dwordx4 v0, v[40:43], s[72:73] offset:1024 sc1
	global_store_dwordx4 v0, v[44:47], s[72:73] offset:2048 sc1
	global_store_dwordx4 v0, v[48:51], s[72:73] offset:3072 sc1
	s_add_u32 s55, s55, 8
.Lrp15_loop3:
	s_add_u32 s57, s55, 8
	s_min_u32 s57, s57, s54
	s_lshl_b32 s60, s57, 12
	s_add_u32 s64, s84, s60
	s_addc_u32 s65, s85, 0
	s_lshl_b32 s60, s57, 11
	s_add_u32 s66, s82, s60
	s_addc_u32 s67, s83, 0
	s_lshl_b32 s60, s57, 11
	s_add_u32 s68, s78, s60
	s_addc_u32 s69, s79, 0
	global_load_dwordx4 v[36:39], v0, s[64:65] nt
	global_load_dwordx4 v[40:43], v0, s[64:65] offset:1024 nt
	global_load_dwordx4 v[44:47], v0, s[64:65] offset:2048 nt
	global_load_dwordx4 v[48:51], v0, s[64:65] offset:3072 nt
	global_load_dwordx2 v[52:53], v1, s[66:67] nt
	global_load_dwordx2 v[54:55], v1, s[66:67] offset:512 nt
	global_load_dwordx2 v[56:57], v1, s[66:67] offset:1024 nt
	global_load_dwordx2 v[58:59], v1, s[66:67] offset:1536 nt
	global_load_dwordx2 v[60:61], v1, s[68:69] nt
	global_load_dwordx2 v[62:63], v1, s[68:69] offset:512 nt
	global_load_dwordx2 v[64:65], v1, s[68:69] offset:1024 nt
	global_load_dwordx2 v[66:67], v1, s[68:69] offset:1536 nt
	s_lshr_b32 s60, s55, 11
	s_sub_u32 s61, s55, 0x8000
	s_lshr_b32 s61, s61, 12
	s_add_u32 s61, s61, 16
	s_cmp_lt_u32 s55, 0x8000
	s_cselect_b32 s63, s60, s61
	s_cmp_eq_u32 s63, s56
	s_cbranch_scc1 .Lrp15_pk6
	s_mov_b32 s56, s63
	s_mul_i32 s60, s56, 0x9000
	s_add_u32 s60, s60, 0x3185000
	s_add_u32 s0, s92, s60
	s_addc_u32 s1, s93, 0
	global_load_dwordx4 v[160:163], v0, s[0:1]
	global_load_dwordx4 v[164:167], v0, s[0:1] offset:1024
	global_load_dwordx4 v[168:171], v0, s[0:1] offset:2048
	global_load_dwordx4 v[172:175], v0, s[0:1] offset:3072
	s_add_u32 s0, s22, 0x1000
	s_addc_u32 s1, s23, 0
	global_load_dwordx4 v[176:179], v0, s[0:1]
	global_load_dwordx4 v[180:183], v0, s[0:1] offset:1024
	global_load_dwordx4 v[184:187], v0, s[0:1] offset:2048
	global_load_dwordx4 v[188:191], v0, s[0:1] offset:3072
	s_mul_i32 s60, s56, 0x9000
	s_add_u32 s60, s60, 0x3188000
	s_add_u32 s0, s92, s60
	s_addc_u32 s1, s93, 0
	global_load_dwordx4 v[192:195], v0, s[0:1]
	global_load_dwordx4 v[196:199], v0, s[0:1] offset:1024
	global_load_dwordx4 v[200:203], v0, s[0:1] offset:2048
	global_load_dwordx4 v[204:207], v0, s[0:1] offset:3072
	s_add_u32 s0, s22, 0x2000
	s_addc_u32 s1, s23, 0
	global_load_dwordx4 v[208:211], v0, s[0:1]
	global_load_dwordx4 v[212:215], v0, s[0:1] offset:1024
	global_load_dwordx4 v[216:219], v0, s[0:1] offset:2048
	global_load_dwordx4 v[220:223], v0, s[0:1] offset:3072
	s_waitcnt vmcnt(0)
.Lrp15_pk6:
	s_waitcnt vmcnt(16)
	v_lshlrev_b32_e32 v112, 16, v20
	v_and_b32_e32 v113, 0xffff0000, v20
	v_lshlrev_b32_e32 v114, 16, v21
	v_and_b32_e32 v115, 0xffff0000, v21
	v_lshlrev_b32_e32 v116, 16, v22
	v_and_b32_e32 v117, 0xffff0000, v22
	v_lshlrev_b32_e32 v118, 16, v23
	v_and_b32_e32 v119, 0xffff0000, v23
	v_lshlrev_b32_e32 v120, 16, v24
	v_and_b32_e32 v121, 0xffff0000, v24
	v_lshlrev_b32_e32 v122, 16, v25
	v_and_b32_e32 v123, 0xffff0000, v25
	v_lshlrev_b32_e32 v124, 16, v26
	v_and_b32_e32 v125, 0xffff0000, v26
	v_lshlrev_b32_e32 v100, 16, v27
	v_and_b32_e32 v101, 0xffff0000, v27
	v_pk_mul_f32 v[102:103], v[112:113], v[112:113]
	v_pk_mul_f32 v[106:107], v[114:115], v[114:115]
	v_pk_fma_f32 v[102:103], v[116:117], v[116:117], v[102:103]
	v_pk_fma_f32 v[106:107], v[118:119], v[118:119], v[106:107]
	v_pk_fma_f32 v[102:103], v[120:121], v[120:121], v[102:103]
	v_pk_fma_f32 v[106:107], v[122:123], v[122:123], v[106:107]
	v_pk_fma_f32 v[102:103], v[124:125], v[124:125], v[102:103]
	v_pk_fma_f32 v[106:107], v[100:101], v[100:101], v[106:107]
	s_nop 0
	v_pk_add_f32 v[102:103], v[102:103], v[106:107]
	s_nop 0
	v_add_f32_e32 v102, v102, v103
	v_mov_b32_e32 v104, v102
	v_lshlrev_b32_e32 v112, 16, v28
	v_and_b32_e32 v113, 0xffff0000, v28
	v_lshlrev_b32_e32 v114, 16, v29
	v_and_b32_e32 v115, 0xffff0000, v29
	v_lshlrev_b32_e32 v116, 16, v30
	v_and_b32_e32 v117, 0xffff0000, v30
	v_lshlrev_b32_e32 v118, 16, v31
	v_and_b32_e32 v119, 0xffff0000, v31
	v_lshlrev_b32_e32 v120, 16, v32
	v_and_b32_e32 v121, 0xffff0000, v32
	v_lshlrev_b32_e32 v122, 16, v33
	v_and_b32_e32 v123, 0xffff0000, v33
	v_lshlrev_b32_e32 v124, 16, v34
	v_and_b32_e32 v125, 0xffff0000, v34
	v_lshlrev_b32_e32 v100, 16, v35
	v_and_b32_e32 v101, 0xffff0000, v35
	v_pk_mul_f32 v[102:103], v[112:113], v[112:113]
; __device__ __forceinline__ void phase_final(const Params& p) {
;     ...
;             sm += (m[j].x * m[j].x + m[j].y * m[j].y) + (m[j].z * m[j].z + m[j].w * m[j].w); sf += (f[j].x * f[j].x + f[j].y * f[j].y) + (f[j].z * f[j].z + f[j].w * f[j].w); }
;         const float rm = 1.0f / sqrtf(wave_sum(sm) * (1.0f / D) + EPS), rf = 1.0f / sqrtf(wave_sum(sf) * (1.0f / D) + EPS) * 0.5f;
;         const float* g1 = mod + b * 9216 + 1 * 3072 + 2048; const float* g2 = mod + b * 9216 + 2 * 3072 + 2048;
;         const float* q1 = p.in[7] + 1 * D; const float* q2 = p.in[7] + 2 * D;
; #pragma unroll
;         for (int j = 0; j < 4; ++j) { const int c = 4 * lane + 256 * j;
;             const f32x4 x2 = v[j] + *(const f32x4*)(g1 + c) * (m[j] * rm * *(const f32x4*)(q1 + c));
	v_pk_mul_f32 v[106:107], v[114:115], v[114:115]
	v_pk_fma_f32 v[102:103], v[116:117], v[116:117], v[102:103]
	v_pk_fma_f32 v[106:107], v[118:119], v[118:119], v[106:107]
	v_pk_fma_f32 v[102:103], v[120:121], v[120:121], v[102:103]
	v_pk_fma_f32 v[106:107], v[122:123], v[122:123], v[106:107]
	v_pk_fma_f32 v[102:103], v[124:125], v[124:125], v[102:103]
	v_pk_fma_f32 v[106:107], v[100:101], v[100:101], v[106:107]
	s_nop 0
	v_pk_add_f32 v[102:103], v[102:103], v[106:107]
	s_nop 0
	v_add_f32_e32 v102, v102, v103
	s_nop 1
	v_add_f32_dpp v104, v104, v104 quad_perm:[1,0,3,2] row_mask:0xf bank_mask:0xf
	v_add_f32_dpp v102, v102, v102 quad_perm:[1,0,3,2] row_mask:0xf bank_mask:0xf
	s_nop 1
	v_add_f32_dpp v104, v104, v104 quad_perm:[2,3,0,1] row_mask:0xf bank_mask:0xf
	v_add_f32_dpp v102, v102, v102 quad_perm:[2,3,0,1] row_mask:0xf bank_mask:0xf
	s_nop 1
	v_add_f32_dpp v104, v104, v104 row_half_mirror row_mask:0xf bank_mask:0xf
	v_add_f32_dpp v102, v102, v102 row_half_mirror row_mask:0xf bank_mask:0xf
	s_nop 1
	v_add_f32_dpp v104, v104, v104 row_mirror row_mask:0xf bank_mask:0xf
	v_add_f32_dpp v102, v102, v102 row_mirror row_mask:0xf bank_mask:0xf
	s_nop 1
	v_add_f32_dpp v104, v104, v104 row_bcast:15 row_mask:0xa bank_mask:0xf
	v_add_f32_dpp v102, v102, v102 row_bcast:15 row_mask:0xa bank_mask:0xf
	s_nop 1
	v_add_f32_dpp v104, v104, v104 row_bcast:31 row_mask:0xc bank_mask:0xf
	v_add_f32_dpp v102, v102, v102 row_bcast:31 row_mask:0xc bank_mask:0xf
	s_nop 1
	v_readlane_b32 s74, v104, 63
	v_readlane_b32 s75, v102, 63
	s_nop 2
	v_mov_b32_e32 v102, s74
	v_fmamk_f32 v102, v102, 0x3a800000, v2
	v_mul_f32_e32 v103, 0x4f800000, v102
	v_cmp_gt_f32_e32 vcc, 0xf800000, v102
	s_nop 1
	v_cndmask_b32_e32 v102, v102, v103, vcc
	v_sqrt_f32_e32 v103, v102
	s_nop 0
	v_add_u32_e32 v104, -1, v103
	v_add_u32_e32 v106, 1, v103
	v_fma_f32 v107, -v104, v103, v102
	v_fma_f32 v108, -v106, v103, v102
	v_cmp_ge_f32_e64 s[76:77], 0, v107
	s_nop 1
	v_cndmask_b32_e64 v103, v103, v104, s[76:77]
	v_cmp_lt_f32_e64 s[76:77], 0, v108
	s_nop 1
	v_cndmask_b32_e64 v103, v103, v106, s[76:77]
	v_mul_f32_e32 v104, 0x37800000, v103
	v_cndmask_b32_e32 v103, v103, v104, vcc
	v_cmp_class_f32_e32 vcc, v102, v3
	s_nop 1
	v_cndmask_b32_e32 v102, v103, v102, vcc
	v_div_scale_f32 v103, s[76:77], v102, v102, 1.0
	v_rcp_f32_e32 v104, v103
	v_div_scale_f32 v106, vcc, 1.0, v102, 1.0
	v_fma_f32 v107, -v103, v104, 1.0
	v_fmac_f32_e32 v104, v107, v104
	v_mul_f32_e32 v107, v106, v104
	v_fma_f32 v108, -v103, v107, v106
	v_fmac_f32_e32 v107, v108, v104
	v_fma_f32 v103, -v103, v107, v106
	v_div_fmas_f32 v103, v103, v104, v107
	v_div_fixup_f32 v110, v103, v102, 1.0
	v_mov_b32_e32 v102, s75
	v_fmamk_f32 v102, v102, 0x3a800000, v2
	v_mul_f32_e32 v103, 0x4f800000, v102
	v_cmp_gt_f32_e32 vcc, 0xf800000, v102
	s_nop 1
	v_cndmask_b32_e32 v102, v102, v103, vcc
	v_sqrt_f32_e32 v103, v102
	s_nop 0
	v_add_u32_e32 v104, -1, v103
	v_add_u32_e32 v106, 1, v103
	v_fma_f32 v107, -v104, v103, v102
	v_fma_f32 v108, -v106, v103, v102
	v_cmp_ge_f32_e64 s[76:77], 0, v107
	s_nop 1
	v_cndmask_b32_e64 v103, v103, v104, s[76:77]
	v_cmp_lt_f32_e64 s[76:77], 0, v108
	s_nop 1
	v_cndmask_b32_e64 v103, v103, v106, s[76:77]
	v_mul_f32_e32 v104, 0x37800000, v103
	v_cndmask_b32_e32 v103, v103, v104, vcc
	v_cmp_class_f32_e32 vcc, v102, v3
	s_nop 1
	v_cndmask_b32_e32 v102, v103, v102, vcc
	v_div_scale_f32 v103, s[76:77], v102, v102, 1.0
	v_rcp_f32_e32 v104, v103
	v_div_scale_f32 v106, vcc, 1.0, v102, 1.0
	v_fma_f32 v107, -v103, v104, 1.0
	v_fmac_f32_e32 v104, v107, v104
	v_mul_f32_e32 v107, v106, v104
	v_fma_f32 v108, -v103, v107, v106
	v_fmac_f32_e32 v107, v108, v104
	v_fma_f32 v103, -v103, v107, v106
	v_div_fmas_f32 v103, v103, v104, v107
	v_div_fixup_f32 v108, v103, v102, 1.0
	v_mul_f32_e32 v108, 0.5, v108
	v_pk_mul_f32 v[112:113], v[112:113], v[108:109] op_sel_hi:[1,0]
	v_pk_mul_f32 v[114:115], v[114:115], v[108:109] op_sel_hi:[1,0]
	v_pk_mul_f32 v[116:117], v[116:117], v[108:109] op_sel_hi:[1,0]
	v_pk_mul_f32 v[118:119], v[118:119], v[108:109] op_sel_hi:[1,0]
	v_pk_mul_f32 v[120:121], v[120:121], v[108:109] op_sel_hi:[1,0]
	v_pk_mul_f32 v[122:123], v[122:123], v[108:109] op_sel_hi:[1,0]
	v_pk_mul_f32 v[124:125], v[124:125], v[108:109] op_sel_hi:[1,0]
	v_pk_mul_f32 v[100:101], v[100:101], v[108:109] op_sel_hi:[1,0]
	v_pk_mul_f32 v[112:113], v[112:113], v[208:209]
	v_pk_mul_f32 v[114:115], v[114:115], v[210:211]
	v_pk_mul_f32 v[116:117], v[116:117], v[212:213]
	v_pk_mul_f32 v[118:119], v[118:119], v[214:215]
	v_pk_mul_f32 v[120:121], v[120:121], v[216:217]
	v_pk_mul_f32 v[122:123], v[122:123], v[218:219]
	v_pk_mul_f32 v[124:125], v[124:125], v[220:221]
	v_pk_mul_f32 v[100:101], v[100:101], v[222:223]
	v_lshlrev_b32_e32 v28, 16, v20
	v_and_b32_e32 v29, 0xffff0000, v20
	v_lshlrev_b32_e32 v30, 16, v21
	v_and_b32_e32 v31, 0xffff0000, v21
	v_lshlrev_b32_e32 v32, 16, v22
	v_and_b32_e32 v33, 0xffff0000, v22
	v_lshlrev_b32_e32 v34, 16, v23
	v_and_b32_e32 v35, 0xffff0000, v23
	v_lshlrev_b32_e32 v240, 16, v24
	v_and_b32_e32 v241, 0xffff0000, v24
	v_lshlrev_b32_e32 v242, 16, v25
	v_and_b32_e32 v243, 0xffff0000, v25
	v_lshlrev_b32_e32 v244, 16, v26
	v_and_b32_e32 v245, 0xffff0000, v26
	v_lshlrev_b32_e32 v246, 16, v27
	v_and_b32_e32 v247, 0xffff0000, v27
	v_pk_mul_f32 v[28:29], v[28:29], v[110:111] op_sel_hi:[1,0]
	v_pk_mul_f32 v[30:31], v[30:31], v[110:111] op_sel_hi:[1,0]
	v_pk_mul_f32 v[32:33], v[32:33], v[110:111] op_sel_hi:[1,0]
	v_pk_mul_f32 v[34:35], v[34:35], v[110:111] op_sel_hi:[1,0]
	v_pk_mul_f32 v[240:241], v[240:241], v[110:111] op_sel_hi:[1,0]
	v_pk_mul_f32 v[242:243], v[242:243], v[110:111] op_sel_hi:[1,0]
; __device__ __forceinline__ float lo_bf(unsigned w) { return __uint_as_float(w << 16); }
; __device__ __forceinline__ float hi_bf(unsigned w) { return __uint_as_float(w & 0xffff0000u); }
; __device__ __forceinline__ void phase_final(const Params& p) {
;     ...
;     for (int row = gw; row < T; row += NGW) {
;         const int b = row_batch(row);
;         f32x4 v[4], m[4], f[4]; float sm = 0.f, sf = 0.f;
; #pragma unroll
;         for (int j = 0; j < 4; ++j) { v[j] = *(const f32x4*)(p.out + (size_t)row * D + 4 * lane + 256 * j);
;             const u32x2 wm = *(const u32x2*)(Fm + (size_t)row * D + 4 * lane + 256 * j), wf = *(const u32x2*)(F2 + (size_t)row * D + 4 * lane + 256 * j);
;             m[j] = (f32x4){lo_bf(wm.x), hi_bf(wm.x), lo_bf(wm.y), hi_bf(wm.y)}; f[j] = (f32x4){lo_bf(wf.x), hi_bf(wf.x), lo_bf(wf.y), hi_bf(wf.y)};
;             sm += (m[j].x * m[j].x + m[j].y * m[j].y) + (m[j].z * m[j].z + m[j].w * m[j].w); sf += (f[j].x * f[j].x + f[j].y * f[j].y) + (f[j].z * f[j].z + f[j].w * f[j].w); }
;     ...
;         for (int j = 0; j < 4; ++j) { const int c = 4 * lane + 256 * j;
;             const f32x4 x2 = v[j] + *(const f32x4*)(g1 + c) * (m[j] * rm * *(const f32x4*)(q1 + c));
;             *(f32x4*)(p.out + (size_t)row * D + c) = x2 + *(const f32x4*)(g2 + c) * (f[j] * rf * *(const f32x4*)(q2 + c)); }
	v_pk_mul_f32 v[244:245], v[244:245], v[110:111] op_sel_hi:[1,0]
	v_pk_mul_f32 v[246:247], v[246:247], v[110:111] op_sel_hi:[1,0]
	v_pk_mul_f32 v[28:29], v[28:29], v[176:177]
	v_pk_mul_f32 v[30:31], v[30:31], v[178:179]
	v_pk_mul_f32 v[32:33], v[32:33], v[180:181]
	v_pk_mul_f32 v[34:35], v[34:35], v[182:183]
	v_pk_mul_f32 v[240:241], v[240:241], v[184:185]
	v_pk_mul_f32 v[242:243], v[242:243], v[186:187]
	v_pk_mul_f32 v[244:245], v[244:245], v[188:189]
	v_pk_mul_f32 v[246:247], v[246:247], v[190:191]
	v_pk_fma_f32 v[4:5], v[160:161], v[28:29], v[4:5]
	v_pk_fma_f32 v[6:7], v[162:163], v[30:31], v[6:7]
	v_pk_fma_f32 v[8:9], v[164:165], v[32:33], v[8:9]
	v_pk_fma_f32 v[10:11], v[166:167], v[34:35], v[10:11]
	v_pk_fma_f32 v[12:13], v[168:169], v[240:241], v[12:13]
	v_pk_fma_f32 v[14:15], v[170:171], v[242:243], v[14:15]
	v_pk_fma_f32 v[16:17], v[172:173], v[244:245], v[16:17]
	v_pk_fma_f32 v[18:19], v[174:175], v[246:247], v[18:19]
	v_pk_fma_f32 v[4:5], v[192:193], v[112:113], v[4:5]
	v_pk_fma_f32 v[6:7], v[194:195], v[114:115], v[6:7]
	v_pk_fma_f32 v[8:9], v[196:197], v[116:117], v[8:9]
	v_pk_fma_f32 v[10:11], v[198:199], v[118:119], v[10:11]
	v_pk_fma_f32 v[12:13], v[200:201], v[120:121], v[12:13]
	v_pk_fma_f32 v[14:15], v[202:203], v[122:123], v[14:15]
	v_pk_fma_f32 v[16:17], v[204:205], v[124:125], v[16:17]
	v_pk_fma_f32 v[18:19], v[206:207], v[100:101], v[18:19]
	s_lshl_b32 s60, s55, 12
	s_add_u32 s72, s84, s60
	s_addc_u32 s73, s85, 0
	global_store_dwordx4 v0, v[4:7], s[72:73] sc1
	global_store_dwordx4 v0, v[8:11], s[72:73] offset:1024 sc1
	global_store_dwordx4 v0, v[12:15], s[72:73] offset:2048 sc1
	global_store_dwordx4 v0, v[16:19], s[72:73] offset:3072 sc1
	s_add_u32 s55, s55, 8
	s_add_u32 s57, s55, 8
	s_min_u32 s57, s57, s54
	s_lshl_b32 s60, s57, 12
	s_add_u32 s64, s84, s60
	s_addc_u32 s65, s85, 0
	s_lshl_b32 s60, s57, 11
	s_add_u32 s66, s82, s60
	s_addc_u32 s67, s83, 0
	s_lshl_b32 s60, s57, 11
	s_add_u32 s68, s78, s60
	s_addc_u32 s69, s79, 0
	global_load_dwordx4 v[4:7], v0, s[64:65] nt
	global_load_dwordx4 v[8:11], v0, s[64:65] offset:1024 nt
	global_load_dwordx4 v[12:15], v0, s[64:65] offset:2048 nt
	global_load_dwordx4 v[16:19], v0, s[64:65] offset:3072 nt
	global_load_dwordx2 v[20:21], v1, s[66:67] nt
	global_load_dwordx2 v[22:23], v1, s[66:67] offset:512 nt
	global_load_dwordx2 v[24:25], v1, s[66:67] offset:1024 nt
	global_load_dwordx2 v[26:27], v1, s[66:67] offset:1536 nt
	global_load_dwordx2 v[28:29], v1, s[68:69] nt
	global_load_dwordx2 v[30:31], v1, s[68:69] offset:512 nt
	global_load_dwordx2 v[32:33], v1, s[68:69] offset:1024 nt
	global_load_dwordx2 v[34:35], v1, s[68:69] offset:1536 nt
	s_lshr_b32 s60, s55, 11
	s_sub_u32 s61, s55, 0x8000
	s_lshr_b32 s61, s61, 12
	s_add_u32 s61, s61, 16
	s_cmp_lt_u32 s55, 0x8000
	s_cselect_b32 s63, s60, s61
	s_cmp_eq_u32 s63, s56
	s_cbranch_scc1 .Lrp15_pk7
	s_mov_b32 s56, s63
	s_mul_i32 s60, s56, 0x9000
	s_add_u32 s60, s60, 0x3185000
	s_add_u32 s0, s92, s60
	s_addc_u32 s1, s93, 0
	global_load_dwordx4 v[160:163], v0, s[0:1]
	global_load_dwordx4 v[164:167], v0, s[0:1] offset:1024
	global_load_dwordx4 v[168:171], v0, s[0:1] offset:2048
	global_load_dwordx4 v[172:175], v0, s[0:1] offset:3072
	s_add_u32 s0, s22, 0x1000
	s_addc_u32 s1, s23, 0
	global_load_dwordx4 v[176:179], v0, s[0:1]
	global_load_dwordx4 v[180:183], v0, s[0:1] offset:1024
	global_load_dwordx4 v[184:187], v0, s[0:1] offset:2048
	global_load_dwordx4 v[188:191], v0, s[0:1] offset:3072
	s_mul_i32 s60, s56, 0x9000
	s_add_u32 s60, s60, 0x3188000
	s_add_u32 s0, s92, s60
	s_addc_u32 s1, s93, 0
	global_load_dwordx4 v[192:195], v0, s[0:1]
	global_load_dwordx4 v[196:199], v0, s[0:1] offset:1024
	global_load_dwordx4 v[200:203], v0, s[0:1] offset:2048
	global_load_dwordx4 v[204:207], v0, s[0:1] offset:3072
	s_add_u32 s0, s22, 0x2000
	s_addc_u32 s1, s23, 0
	global_load_dwordx4 v[208:211], v0, s[0:1]
	global_load_dwordx4 v[212:215], v0, s[0:1] offset:1024
	global_load_dwordx4 v[216:219], v0, s[0:1] offset:2048
	global_load_dwordx4 v[220:223], v0, s[0:1] offset:3072
	s_waitcnt vmcnt(0)
.Lrp15_pk7:
	s_waitcnt vmcnt(16)
	v_lshlrev_b32_e32 v112, 16, v52
	v_and_b32_e32 v113, 0xffff0000, v52
	v_lshlrev_b32_e32 v114, 16, v53
	v_and_b32_e32 v115, 0xffff0000, v53
	v_lshlrev_b32_e32 v116, 16, v54
	v_and_b32_e32 v117, 0xffff0000, v54
	v_lshlrev_b32_e32 v118, 16, v55
	v_and_b32_e32 v119, 0xffff0000, v55
	v_lshlrev_b32_e32 v120, 16, v56
	v_and_b32_e32 v121, 0xffff0000, v56
	v_lshlrev_b32_e32 v122, 16, v57
	v_and_b32_e32 v123, 0xffff0000, v57
	v_lshlrev_b32_e32 v124, 16, v58
	v_and_b32_e32 v125, 0xffff0000, v58
	v_lshlrev_b32_e32 v100, 16, v59
	v_and_b32_e32 v101, 0xffff0000, v59
	v_pk_mul_f32 v[102:103], v[112:113], v[112:113]
	v_pk_mul_f32 v[106:107], v[114:115], v[114:115]
	v_pk_fma_f32 v[102:103], v[116:117], v[116:117], v[102:103]
	v_pk_fma_f32 v[106:107], v[118:119], v[118:119], v[106:107]
	v_pk_fma_f32 v[102:103], v[120:121], v[120:121], v[102:103]
	v_pk_fma_f32 v[106:107], v[122:123], v[122:123], v[106:107]
	v_pk_fma_f32 v[102:103], v[124:125], v[124:125], v[102:103]
	v_pk_fma_f32 v[106:107], v[100:101], v[100:101], v[106:107]
	s_nop 0
	v_pk_add_f32 v[102:103], v[102:103], v[106:107]
	s_nop 0
	v_add_f32_e32 v102, v102, v103
	v_mov_b32_e32 v104, v102
	v_lshlrev_b32_e32 v112, 16, v60
	v_and_b32_e32 v113, 0xffff0000, v60
	v_lshlrev_b32_e32 v114, 16, v61
	v_and_b32_e32 v115, 0xffff0000, v61
	v_lshlrev_b32_e32 v116, 16, v62
	v_and_b32_e32 v117, 0xffff0000, v62
	v_lshlrev_b32_e32 v118, 16, v63
	v_and_b32_e32 v119, 0xffff0000, v63
	v_lshlrev_b32_e32 v120, 16, v64
	v_and_b32_e32 v121, 0xffff0000, v64
	v_lshlrev_b32_e32 v122, 16, v65
	v_and_b32_e32 v123, 0xffff0000, v65
; __device__ __forceinline__ void phase_final(const Params& p) {
;     ...
;             sm += (m[j].x * m[j].x + m[j].y * m[j].y) + (m[j].z * m[j].z + m[j].w * m[j].w); sf += (f[j].x * f[j].x + f[j].y * f[j].y) + (f[j].z * f[j].z + f[j].w * f[j].w); }
;         const float rm = 1.0f / sqrtf(wave_sum(sm) * (1.0f / D) + EPS), rf = 1.0f / sqrtf(wave_sum(sf) * (1.0f / D) + EPS) * 0.5f;
	v_lshlrev_b32_e32 v124, 16, v66
	v_and_b32_e32 v125, 0xffff0000, v66
	v_lshlrev_b32_e32 v100, 16, v67
	v_and_b32_e32 v101, 0xffff0000, v67
	v_pk_mul_f32 v[102:103], v[112:113], v[112:113]
	v_pk_mul_f32 v[106:107], v[114:115], v[114:115]
	v_pk_fma_f32 v[102:103], v[116:117], v[116:117], v[102:103]
	v_pk_fma_f32 v[106:107], v[118:119], v[118:119], v[106:107]
	v_pk_fma_f32 v[102:103], v[120:121], v[120:121], v[102:103]
	v_pk_fma_f32 v[106:107], v[122:123], v[122:123], v[106:107]
	v_pk_fma_f32 v[102:103], v[124:125], v[124:125], v[102:103]
	v_pk_fma_f32 v[106:107], v[100:101], v[100:101], v[106:107]
	s_nop 0
	v_pk_add_f32 v[102:103], v[102:103], v[106:107]
	s_nop 0
	v_add_f32_e32 v102, v102, v103
	s_nop 1
	v_add_f32_dpp v104, v104, v104 quad_perm:[1,0,3,2] row_mask:0xf bank_mask:0xf
	v_add_f32_dpp v102, v102, v102 quad_perm:[1,0,3,2] row_mask:0xf bank_mask:0xf
	s_nop 1
	v_add_f32_dpp v104, v104, v104 quad_perm:[2,3,0,1] row_mask:0xf bank_mask:0xf
	v_add_f32_dpp v102, v102, v102 quad_perm:[2,3,0,1] row_mask:0xf bank_mask:0xf
	s_nop 1
	v_add_f32_dpp v104, v104, v104 row_half_mirror row_mask:0xf bank_mask:0xf
	v_add_f32_dpp v102, v102, v102 row_half_mirror row_mask:0xf bank_mask:0xf
	s_nop 1
	v_add_f32_dpp v104, v104, v104 row_mirror row_mask:0xf bank_mask:0xf
	v_add_f32_dpp v102, v102, v102 row_mirror row_mask:0xf bank_mask:0xf
	s_nop 1
	v_add_f32_dpp v104, v104, v104 row_bcast:15 row_mask:0xa bank_mask:0xf
	v_add_f32_dpp v102, v102, v102 row_bcast:15 row_mask:0xa bank_mask:0xf
	s_nop 1
	v_add_f32_dpp v104, v104, v104 row_bcast:31 row_mask:0xc bank_mask:0xf
	v_add_f32_dpp v102, v102, v102 row_bcast:31 row_mask:0xc bank_mask:0xf
	s_nop 1
	v_readlane_b32 s74, v104, 63
	v_readlane_b32 s75, v102, 63
	s_nop 2
	v_mov_b32_e32 v102, s74
	v_fmamk_f32 v102, v102, 0x3a800000, v2
	v_mul_f32_e32 v103, 0x4f800000, v102
	v_cmp_gt_f32_e32 vcc, 0xf800000, v102
	s_nop 1
	v_cndmask_b32_e32 v102, v102, v103, vcc
	v_sqrt_f32_e32 v103, v102
	s_nop 0
	v_add_u32_e32 v104, -1, v103
	v_add_u32_e32 v106, 1, v103
	v_fma_f32 v107, -v104, v103, v102
	v_fma_f32 v108, -v106, v103, v102
	v_cmp_ge_f32_e64 s[76:77], 0, v107
	s_nop 1
	v_cndmask_b32_e64 v103, v103, v104, s[76:77]
	v_cmp_lt_f32_e64 s[76:77], 0, v108
	s_nop 1
	v_cndmask_b32_e64 v103, v103, v106, s[76:77]
	v_mul_f32_e32 v104, 0x37800000, v103
	v_cndmask_b32_e32 v103, v103, v104, vcc
	v_cmp_class_f32_e32 vcc, v102, v3
	s_nop 1
	v_cndmask_b32_e32 v102, v103, v102, vcc
	v_div_scale_f32 v103, s[76:77], v102, v102, 1.0
	v_rcp_f32_e32 v104, v103
	v_div_scale_f32 v106, vcc, 1.0, v102, 1.0
	v_fma_f32 v107, -v103, v104, 1.0
	v_fmac_f32_e32 v104, v107, v104
	v_mul_f32_e32 v107, v106, v104
	v_fma_f32 v108, -v103, v107, v106
	v_fmac_f32_e32 v107, v108, v104
	v_fma_f32 v103, -v103, v107, v106
	v_div_fmas_f32 v103, v103, v104, v107
	v_div_fixup_f32 v110, v103, v102, 1.0
	v_mov_b32_e32 v102, s75
	v_fmamk_f32 v102, v102, 0x3a800000, v2
	v_mul_f32_e32 v103, 0x4f800000, v102
	v_cmp_gt_f32_e32 vcc, 0xf800000, v102
	s_nop 1
	v_cndmask_b32_e32 v102, v102, v103, vcc
	v_sqrt_f32_e32 v103, v102
	s_nop 0
	v_add_u32_e32 v104, -1, v103
	v_add_u32_e32 v106, 1, v103
	v_fma_f32 v107, -v104, v103, v102
	v_fma_f32 v108, -v106, v103, v102
	v_cmp_ge_f32_e64 s[76:77], 0, v107
	s_nop 1
	v_cndmask_b32_e64 v103, v103, v104, s[76:77]
	v_cmp_lt_f32_e64 s[76:77], 0, v108
	s_nop 1
	v_cndmask_b32_e64 v103, v103, v106, s[76:77]
	v_mul_f32_e32 v104, 0x37800000, v103
	v_cndmask_b32_e32 v103, v103, v104, vcc
	v_cmp_class_f32_e32 vcc, v102, v3
	s_nop 1
	v_cndmask_b32_e32 v102, v103, v102, vcc
	v_div_scale_f32 v103, s[76:77], v102, v102, 1.0
	v_rcp_f32_e32 v104, v103
	v_div_scale_f32 v106, vcc, 1.0, v102, 1.0
	v_fma_f32 v107, -v103, v104, 1.0
	v_fmac_f32_e32 v104, v107, v104
	v_mul_f32_e32 v107, v106, v104
	v_fma_f32 v108, -v103, v107, v106
	v_fmac_f32_e32 v107, v108, v104
; __device__ __forceinline__ void phase_final(const Params& p) {
;     ...
;         const float rm = 1.0f / sqrtf(wave_sum(sm) * (1.0f / D) + EPS), rf = 1.0f / sqrtf(wave_sum(sf) * (1.0f / D) + EPS) * 0.5f;
;         const float* g1 = mod + b * 9216 + 1 * 3072 + 2048; const float* g2 = mod + b * 9216 + 2 * 3072 + 2048;
;         const float* q1 = p.in[7] + 1 * D; const float* q2 = p.in[7] + 2 * D;
; #pragma unroll
;         for (int j = 0; j < 4; ++j) { const int c = 4 * lane + 256 * j;
;             const f32x4 x2 = v[j] + *(const f32x4*)(g1 + c) * (m[j] * rm * *(const f32x4*)(q1 + c));
;             *(f32x4*)(p.out + (size_t)row * D + c) = x2 + *(const f32x4*)(g2 + c) * (f[j] * rf * *(const f32x4*)(q2 + c)); }
	v_fma_f32 v103, -v103, v107, v106
	v_div_fmas_f32 v103, v103, v104, v107
	v_div_fixup_f32 v108, v103, v102, 1.0
	v_mul_f32_e32 v108, 0.5, v108
	v_pk_mul_f32 v[112:113], v[112:113], v[108:109] op_sel_hi:[1,0]
	v_pk_mul_f32 v[114:115], v[114:115], v[108:109] op_sel_hi:[1,0]
	v_pk_mul_f32 v[116:117], v[116:117], v[108:109] op_sel_hi:[1,0]
	v_pk_mul_f32 v[118:119], v[118:119], v[108:109] op_sel_hi:[1,0]
	v_pk_mul_f32 v[120:121], v[120:121], v[108:109] op_sel_hi:[1,0]
	v_pk_mul_f32 v[122:123], v[122:123], v[108:109] op_sel_hi:[1,0]
	v_pk_mul_f32 v[124:125], v[124:125], v[108:109] op_sel_hi:[1,0]
	v_pk_mul_f32 v[100:101], v[100:101], v[108:109] op_sel_hi:[1,0]
	v_pk_mul_f32 v[112:113], v[112:113], v[208:209]
	v_pk_mul_f32 v[114:115], v[114:115], v[210:211]
	v_pk_mul_f32 v[116:117], v[116:117], v[212:213]
	v_pk_mul_f32 v[118:119], v[118:119], v[214:215]
	v_pk_mul_f32 v[120:121], v[120:121], v[216:217]
	v_pk_mul_f32 v[122:123], v[122:123], v[218:219]
	v_pk_mul_f32 v[124:125], v[124:125], v[220:221]
	v_pk_mul_f32 v[100:101], v[100:101], v[222:223]
	v_lshlrev_b32_e32 v60, 16, v52
	v_and_b32_e32 v61, 0xffff0000, v52
	v_lshlrev_b32_e32 v62, 16, v53
	v_and_b32_e32 v63, 0xffff0000, v53
	v_lshlrev_b32_e32 v64, 16, v54
	v_and_b32_e32 v65, 0xffff0000, v54
	v_lshlrev_b32_e32 v66, 16, v55
	v_and_b32_e32 v67, 0xffff0000, v55
	v_lshlrev_b32_e32 v240, 16, v56
	v_and_b32_e32 v241, 0xffff0000, v56
	v_lshlrev_b32_e32 v242, 16, v57
	v_and_b32_e32 v243, 0xffff0000, v57
	v_lshlrev_b32_e32 v244, 16, v58
	v_and_b32_e32 v245, 0xffff0000, v58
	v_lshlrev_b32_e32 v246, 16, v59
	v_and_b32_e32 v247, 0xffff0000, v59
	v_pk_mul_f32 v[60:61], v[60:61], v[110:111] op_sel_hi:[1,0]
	v_pk_mul_f32 v[62:63], v[62:63], v[110:111] op_sel_hi:[1,0]
	v_pk_mul_f32 v[64:65], v[64:65], v[110:111] op_sel_hi:[1,0]
	v_pk_mul_f32 v[66:67], v[66:67], v[110:111] op_sel_hi:[1,0]
	v_pk_mul_f32 v[240:241], v[240:241], v[110:111] op_sel_hi:[1,0]
	v_pk_mul_f32 v[242:243], v[242:243], v[110:111] op_sel_hi:[1,0]
	v_pk_mul_f32 v[244:245], v[244:245], v[110:111] op_sel_hi:[1,0]
	v_pk_mul_f32 v[246:247], v[246:247], v[110:111] op_sel_hi:[1,0]
	v_pk_mul_f32 v[60:61], v[60:61], v[176:177]
	v_pk_mul_f32 v[62:63], v[62:63], v[178:179]
	v_pk_mul_f32 v[64:65], v[64:65], v[180:181]
	v_pk_mul_f32 v[66:67], v[66:67], v[182:183]
	v_pk_mul_f32 v[240:241], v[240:241], v[184:185]
	v_pk_mul_f32 v[242:243], v[242:243], v[186:187]
	v_pk_mul_f32 v[244:245], v[244:245], v[188:189]
	v_pk_mul_f32 v[246:247], v[246:247], v[190:191]
	v_pk_fma_f32 v[36:37], v[160:161], v[60:61], v[36:37]
	v_pk_fma_f32 v[38:39], v[162:163], v[62:63], v[38:39]
	v_pk_fma_f32 v[40:41], v[164:165], v[64:65], v[40:41]
	v_pk_fma_f32 v[42:43], v[166:167], v[66:67], v[42:43]
	v_pk_fma_f32 v[44:45], v[168:169], v[240:241], v[44:45]
	v_pk_fma_f32 v[46:47], v[170:171], v[242:243], v[46:47]
	v_pk_fma_f32 v[48:49], v[172:173], v[244:245], v[48:49]
	v_pk_fma_f32 v[50:51], v[174:175], v[246:247], v[50:51]
	v_pk_fma_f32 v[36:37], v[192:193], v[112:113], v[36:37]
	v_pk_fma_f32 v[38:39], v[194:195], v[114:115], v[38:39]
	v_pk_fma_f32 v[40:41], v[196:197], v[116:117], v[40:41]
	v_pk_fma_f32 v[42:43], v[198:199], v[118:119], v[42:43]
	v_pk_fma_f32 v[44:45], v[200:201], v[120:121], v[44:45]
	v_pk_fma_f32 v[46:47], v[202:203], v[122:123], v[46:47]
	v_pk_fma_f32 v[48:49], v[204:205], v[124:125], v[48:49]
	v_pk_fma_f32 v[50:51], v[206:207], v[100:101], v[50:51]
	s_lshl_b32 s60, s55, 12
	s_add_u32 s72, s84, s60
	s_addc_u32 s73, s85, 0
	global_store_dwordx4 v0, v[36:39], s[72:73] sc1
	global_store_dwordx4 v0, v[40:43], s[72:73] offset:1024 sc1
	global_store_dwordx4 v0, v[44:47], s[72:73] offset:2048 sc1
	global_store_dwordx4 v0, v[48:51], s[72:73] offset:3072 sc1
	s_add_u32 s55, s55, 8
	s_cmp_le_u32 s55, s54
	s_cbranch_scc1 .Lrp15_loop3
	s_add_u32 s51, s51, s52
	s_branch .Lrp15_chunk1
